# v040 with the per-phase s_setprio flips removed from the GEMM main loops
# speedup vs baseline: 1.0018x; 1.0015x over previous
.LBB0_139:
	v_add_u32_e32 v253, 0x10000, v146
	ds_read_b128 v[140:143], v253
	ds_read_b128 v[150:153], v253 offset:1024
	ds_read_b128 v[154:157], v253 offset:2048
	ds_read_b128 v[158:161], v253 offset:3072
	s_add_u32 s10, s6, 0xfff80080
	s_addc_u32 s11, s7, -1
	s_cmp_eq_u32 s41, 28
	s_cselect_b32 s11, s63, s11
	s_cselect_b32 s10, s62, s10
	s_cselect_b32 s53, s61, s29
	s_cselect_b32 s52, s60, s28
	s_mov_b32 m0, s12
	ds_read_b128 v[162:165], v145
	ds_read_b128 v[166:169], v145 offset:1024
	ds_read_b128 v[170:173], v145 offset:2048
	ds_read_b128 v[174:177], v145 offset:3072
	ds_read_b128 v[178:181], v145 offset:4096
	ds_read_b128 v[182:185], v145 offset:5120
	ds_read_b128 v[186:189], v145 offset:6144
	ds_read_b128 v[190:193], v145 offset:7168
	global_load_lds_dwordx4 v136, s[6:7]
	s_mov_b32 m0, s78
	s_nop 0
	global_load_lds_dwordx4 v138, s[6:7]
	s_waitcnt lgkmcnt(8)
	s_barrier
	s_waitcnt lgkmcnt(0)
	v_mfma_f32_16x16x32_bf16 v[126:129], v[140:143], v[162:165], v[126:129]
	v_mfma_f32_16x16x32_bf16 v[122:125], v[154:157], v[162:165], v[122:125]
	v_mfma_f32_16x16x32_bf16 v[118:121], v[140:143], v[170:173], v[118:121]
	v_mfma_f32_16x16x32_bf16 v[110:113], v[154:157], v[170:173], v[110:113]
	v_mfma_f32_16x16x32_bf16 v[102:105], v[140:143], v[178:181], v[102:105]
	v_mfma_f32_16x16x32_bf16 v[94:97], v[154:157], v[178:181], v[94:97]
	v_mfma_f32_16x16x32_bf16 v[86:89], v[140:143], v[186:189], v[86:89]
	v_mfma_f32_16x16x32_bf16 v[78:81], v[154:157], v[186:189], v[78:81]
	v_mfma_f32_16x16x32_bf16 v[126:129], v[150:153], v[166:169], v[126:129]
	v_mfma_f32_16x16x32_bf16 v[122:125], v[158:161], v[166:169], v[122:125]
	v_mfma_f32_16x16x32_bf16 v[118:121], v[150:153], v[174:177], v[118:121]
	v_mfma_f32_16x16x32_bf16 v[110:113], v[158:161], v[174:177], v[110:113]
	v_mfma_f32_16x16x32_bf16 v[102:105], v[150:153], v[182:185], v[102:105]
	v_mfma_f32_16x16x32_bf16 v[94:97], v[158:161], v[182:185], v[94:97]
	v_mfma_f32_16x16x32_bf16 v[86:89], v[150:153], v[190:193], v[86:89]
	v_mfma_f32_16x16x32_bf16 v[78:81], v[158:161], v[190:193], v[78:81]
	s_barrier
	s_mov_b32 m0, s83
	ds_read_b128 v[206:209], v253 offset:16384
	ds_read_b128 v[210:213], v253 offset:17408
	ds_read_b128 v[214:217], v253 offset:18432
	ds_read_b128 v[218:221], v253 offset:19456
	global_load_lds_dwordx4 v194, s[52:53]
	s_mov_b32 m0, s54
	s_nop 0
	global_load_lds_dwordx4 v134, s[52:53]
	s_barrier
	s_waitcnt lgkmcnt(0)
	v_mfma_f32_16x16x32_bf16 v[114:117], v[206:209], v[162:165], v[114:117]
	v_mfma_f32_16x16x32_bf16 v[106:109], v[214:217], v[162:165], v[106:109]
	v_mfma_f32_16x16x32_bf16 v[98:101], v[206:209], v[170:173], v[98:101]
	v_mfma_f32_16x16x32_bf16 v[90:93], v[214:217], v[170:173], v[90:93]
	v_mfma_f32_16x16x32_bf16 v[82:85], v[206:209], v[178:181], v[82:85]
	v_mfma_f32_16x16x32_bf16 v[74:77], v[214:217], v[178:181], v[74:77]
	v_mfma_f32_16x16x32_bf16 v[70:73], v[206:209], v[186:189], v[70:73]
	v_mfma_f32_16x16x32_bf16 v[66:69], v[214:217], v[186:189], v[66:69]
	v_mfma_f32_16x16x32_bf16 v[114:117], v[210:213], v[166:169], v[114:117]
	v_mfma_f32_16x16x32_bf16 v[106:109], v[218:221], v[166:169], v[106:109]
	v_mfma_f32_16x16x32_bf16 v[98:101], v[210:213], v[174:177], v[98:101]
	v_mfma_f32_16x16x32_bf16 v[90:93], v[218:221], v[174:177], v[90:93]
	v_mfma_f32_16x16x32_bf16 v[82:85], v[210:213], v[182:185], v[82:85]
	v_mfma_f32_16x16x32_bf16 v[74:77], v[218:221], v[182:185], v[74:77]
	v_mfma_f32_16x16x32_bf16 v[70:73], v[210:213], v[190:193], v[70:73]
	s_mov_b32 m0, s55
	v_mfma_f32_16x16x32_bf16 v[66:69], v[218:221], v[190:193], v[66:69]
	s_barrier
	ds_read_b128 v[162:165], v145 offset:16384
	ds_read_b128 v[166:169], v145 offset:17408
	ds_read_b128 v[170:173], v145 offset:18432
	ds_read_b128 v[174:177], v145 offset:19456
	ds_read_b128 v[178:181], v145 offset:20480
	ds_read_b128 v[182:185], v145 offset:21504
	ds_read_b128 v[186:189], v145 offset:22528
	ds_read_b128 v[190:193], v145 offset:23552
	global_load_lds_dwordx4 v130, s[10:11]
	s_mov_b32 m0, s34
	s_nop 0
	global_load_lds_dwordx4 v132, s[10:11]
	s_barrier
	s_waitcnt lgkmcnt(0)
	v_mfma_f32_16x16x32_bf16 v[62:65], v[140:143], v[162:165], v[62:65]
	v_mfma_f32_16x16x32_bf16 v[58:61], v[154:157], v[162:165], v[58:61]
	v_mfma_f32_16x16x32_bf16 v[54:57], v[140:143], v[170:173], v[54:57]
	v_mfma_f32_16x16x32_bf16 v[46:49], v[154:157], v[170:173], v[46:49]
	v_mfma_f32_16x16x32_bf16 v[38:41], v[140:143], v[178:181], v[38:41]
	v_mfma_f32_16x16x32_bf16 v[30:33], v[154:157], v[178:181], v[30:33]
	v_mfma_f32_16x16x32_bf16 v[22:25], v[140:143], v[186:189], v[22:25]
	v_mfma_f32_16x16x32_bf16 v[14:17], v[154:157], v[186:189], v[14:17]
	v_mfma_f32_16x16x32_bf16 v[62:65], v[150:153], v[166:169], v[62:65]
	v_mfma_f32_16x16x32_bf16 v[58:61], v[158:161], v[166:169], v[58:61]
	v_mfma_f32_16x16x32_bf16 v[54:57], v[150:153], v[174:177], v[54:57]
	v_mfma_f32_16x16x32_bf16 v[46:49], v[158:161], v[174:177], v[46:49]
	v_mfma_f32_16x16x32_bf16 v[38:41], v[150:153], v[182:185], v[38:41]
	v_mfma_f32_16x16x32_bf16 v[30:33], v[158:161], v[182:185], v[30:33]
	v_mfma_f32_16x16x32_bf16 v[22:25], v[150:153], v[190:193], v[22:25]
	v_mfma_f32_16x16x32_bf16 v[14:17], v[158:161], v[190:193], v[14:17]
	s_barrier
	s_add_u32 s58, s52, 0x80000
	s_addc_u32 s59, s53, 0
	s_mov_b32 m0, s4
	s_nop 0
	global_load_lds_dwordx4 v194, s[58:59]
	s_mov_b32 m0, s5
	s_nop 0
	global_load_lds_dwordx4 v134, s[58:59]
	s_waitcnt vmcnt(6)
	s_barrier
	v_mfma_f32_16x16x32_bf16 v[50:53], v[206:209], v[162:165], v[50:53]
	v_mfma_f32_16x16x32_bf16 v[42:45], v[214:217], v[162:165], v[42:45]
	v_mfma_f32_16x16x32_bf16 v[34:37], v[206:209], v[170:173], v[34:37]
	v_mfma_f32_16x16x32_bf16 v[26:29], v[214:217], v[170:173], v[26:29]
	v_mfma_f32_16x16x32_bf16 v[18:21], v[206:209], v[178:181], v[18:21]
	v_mfma_f32_16x16x32_bf16 v[10:13], v[214:217], v[178:181], v[10:13]
	v_mfma_f32_16x16x32_bf16 v[6:9], v[206:209], v[186:189], v[6:9]
	v_mfma_f32_16x16x32_bf16 v[2:5], v[214:217], v[186:189], v[2:5]
	v_mfma_f32_16x16x32_bf16 v[50:53], v[210:213], v[166:169], v[50:53]
	v_mfma_f32_16x16x32_bf16 v[42:45], v[218:221], v[166:169], v[42:45]
	v_mfma_f32_16x16x32_bf16 v[34:37], v[210:213], v[174:177], v[34:37]
	v_mfma_f32_16x16x32_bf16 v[26:29], v[218:221], v[174:177], v[26:29]
	v_mfma_f32_16x16x32_bf16 v[18:21], v[210:213], v[182:185], v[18:21]
	v_mfma_f32_16x16x32_bf16 v[10:13], v[218:221], v[182:185], v[10:13]
	v_mfma_f32_16x16x32_bf16 v[6:9], v[210:213], v[190:193], v[6:9]
	v_mfma_f32_16x16x32_bf16 v[2:5], v[218:221], v[190:193], v[2:5]
	s_barrier
	ds_read_b128 v[140:143], v253 offset:32768
	ds_read_b128 v[150:153], v253 offset:33792
	ds_read_b128 v[154:157], v253 offset:34816
	ds_read_b128 v[158:161], v253 offset:35840
	s_add_u32 s10, s10, 0x80000
	s_addc_u32 s11, s11, 0
	s_mov_b32 m0, s56
	ds_read_b128 v[162:165], v145 offset:32768
	ds_read_b128 v[166:169], v145 offset:33792
	ds_read_b128 v[170:173], v145 offset:34816
	ds_read_b128 v[174:177], v145 offset:35840
	ds_read_b128 v[178:181], v145 offset:36864
	ds_read_b128 v[182:185], v145 offset:37888
	ds_read_b128 v[186:189], v145 offset:38912
	ds_read_b128 v[190:193], v145 offset:39936
	global_load_lds_dwordx4 v130, s[10:11]
	s_mov_b32 m0, s57
	s_nop 0
	global_load_lds_dwordx4 v132, s[10:11]
	s_waitcnt lgkmcnt(8)
	s_barrier
	s_waitcnt lgkmcnt(0)
	v_mfma_f32_16x16x32_bf16 v[126:129], v[140:143], v[162:165], v[126:129]
	v_mfma_f32_16x16x32_bf16 v[122:125], v[154:157], v[162:165], v[122:125]
	v_mfma_f32_16x16x32_bf16 v[118:121], v[140:143], v[170:173], v[118:121]
	v_mfma_f32_16x16x32_bf16 v[110:113], v[154:157], v[170:173], v[110:113]
	v_mfma_f32_16x16x32_bf16 v[102:105], v[140:143], v[178:181], v[102:105]
	v_mfma_f32_16x16x32_bf16 v[94:97], v[154:157], v[178:181], v[94:97]
	v_mfma_f32_16x16x32_bf16 v[86:89], v[140:143], v[186:189], v[86:89]
	v_mfma_f32_16x16x32_bf16 v[78:81], v[154:157], v[186:189], v[78:81]
	v_mfma_f32_16x16x32_bf16 v[126:129], v[150:153], v[166:169], v[126:129]
	v_mfma_f32_16x16x32_bf16 v[122:125], v[158:161], v[166:169], v[122:125]
	v_mfma_f32_16x16x32_bf16 v[118:121], v[150:153], v[174:177], v[118:121]
	v_mfma_f32_16x16x32_bf16 v[110:113], v[158:161], v[174:177], v[110:113]
	v_mfma_f32_16x16x32_bf16 v[102:105], v[150:153], v[182:185], v[102:105]
	v_mfma_f32_16x16x32_bf16 v[94:97], v[158:161], v[182:185], v[94:97]
	v_mfma_f32_16x16x32_bf16 v[86:89], v[150:153], v[190:193], v[86:89]
	v_mfma_f32_16x16x32_bf16 v[78:81], v[158:161], v[190:193], v[78:81]
	s_barrier
	s_mov_b32 m0, s70
	ds_read_b128 v[206:209], v253 offset:49152
	ds_read_b128 v[210:213], v253 offset:50176
	ds_read_b128 v[214:217], v253 offset:51200
	ds_read_b128 v[218:221], v253 offset:52224
	s_add_u32 s98, s52, 0x80
	s_addc_u32 s99, s53, 0
	global_load_lds_dwordx4 v194, s[98:99]
	s_mov_b32 m0, s71
	s_nop 0
	global_load_lds_dwordx4 v134, s[98:99]
	s_barrier
	s_waitcnt lgkmcnt(0)
	v_mfma_f32_16x16x32_bf16 v[114:117], v[206:209], v[162:165], v[114:117]
	v_mfma_f32_16x16x32_bf16 v[106:109], v[214:217], v[162:165], v[106:109]
	v_mfma_f32_16x16x32_bf16 v[98:101], v[206:209], v[170:173], v[98:101]
	v_mfma_f32_16x16x32_bf16 v[90:93], v[214:217], v[170:173], v[90:93]
	v_mfma_f32_16x16x32_bf16 v[82:85], v[206:209], v[178:181], v[82:85]
	v_mfma_f32_16x16x32_bf16 v[74:77], v[214:217], v[178:181], v[74:77]
	v_mfma_f32_16x16x32_bf16 v[70:73], v[206:209], v[186:189], v[70:73]
	v_mfma_f32_16x16x32_bf16 v[66:69], v[214:217], v[186:189], v[66:69]
	v_mfma_f32_16x16x32_bf16 v[114:117], v[210:213], v[166:169], v[114:117]
	v_mfma_f32_16x16x32_bf16 v[106:109], v[218:221], v[166:169], v[106:109]
	v_mfma_f32_16x16x32_bf16 v[98:101], v[210:213], v[174:177], v[98:101]
	v_mfma_f32_16x16x32_bf16 v[90:93], v[218:221], v[174:177], v[90:93]
	v_mfma_f32_16x16x32_bf16 v[82:85], v[210:213], v[182:185], v[82:85]
	v_mfma_f32_16x16x32_bf16 v[74:77], v[218:221], v[182:185], v[74:77]
	v_mfma_f32_16x16x32_bf16 v[70:73], v[210:213], v[190:193], v[70:73]
	s_mov_b32 m0, s33
	v_mfma_f32_16x16x32_bf16 v[66:69], v[218:221], v[190:193], v[66:69]
	s_barrier
	ds_read_b128 v[162:165], v145 offset:49152
	ds_read_b128 v[166:169], v145 offset:50176
	ds_read_b128 v[170:173], v145 offset:51200
	ds_read_b128 v[174:177], v145 offset:52224
	ds_read_b128 v[178:181], v145 offset:53248
	ds_read_b128 v[182:185], v145 offset:54272
	ds_read_b128 v[186:189], v145 offset:55296
	ds_read_b128 v[190:193], v145 offset:56320
	s_add_u32 s100, s10, 0xfff80080
	s_addc_u32 s101, s11, -1
	global_load_lds_dwordx4 v130, s[100:101]
	s_mov_b32 m0, s35
	s_nop 0
	global_load_lds_dwordx4 v132, s[100:101]
	s_barrier
	s_waitcnt lgkmcnt(0)
	v_mfma_f32_16x16x32_bf16 v[62:65], v[140:143], v[162:165], v[62:65]
	v_mfma_f32_16x16x32_bf16 v[58:61], v[154:157], v[162:165], v[58:61]
	v_mfma_f32_16x16x32_bf16 v[54:57], v[140:143], v[170:173], v[54:57]
	v_mfma_f32_16x16x32_bf16 v[46:49], v[154:157], v[170:173], v[46:49]
	v_mfma_f32_16x16x32_bf16 v[38:41], v[140:143], v[178:181], v[38:41]
	v_mfma_f32_16x16x32_bf16 v[30:33], v[154:157], v[178:181], v[30:33]
	v_mfma_f32_16x16x32_bf16 v[22:25], v[140:143], v[186:189], v[22:25]
	v_mfma_f32_16x16x32_bf16 v[14:17], v[154:157], v[186:189], v[14:17]
	v_mfma_f32_16x16x32_bf16 v[62:65], v[150:153], v[166:169], v[62:65]
	v_mfma_f32_16x16x32_bf16 v[58:61], v[158:161], v[166:169], v[58:61]
	v_mfma_f32_16x16x32_bf16 v[54:57], v[150:153], v[174:177], v[54:57]
	v_mfma_f32_16x16x32_bf16 v[46:49], v[158:161], v[174:177], v[46:49]
	v_mfma_f32_16x16x32_bf16 v[38:41], v[150:153], v[182:185], v[38:41]
	v_mfma_f32_16x16x32_bf16 v[30:33], v[158:161], v[182:185], v[30:33]
	v_mfma_f32_16x16x32_bf16 v[22:25], v[150:153], v[190:193], v[22:25]
	v_mfma_f32_16x16x32_bf16 v[14:17], v[158:161], v[190:193], v[14:17]
	s_barrier
	s_add_u32 s10, s52, 0x80080
	s_addc_u32 s11, s53, 0
	s_mov_b32 m0, s67
	s_nop 0
	global_load_lds_dwordx4 v194, s[10:11]
	s_mov_b32 m0, s17
	s_nop 0
	global_load_lds_dwordx4 v134, s[10:11]
	s_waitcnt vmcnt(6)
	s_barrier
	v_mfma_f32_16x16x32_bf16 v[50:53], v[206:209], v[162:165], v[50:53]
	v_mfma_f32_16x16x32_bf16 v[42:45], v[214:217], v[162:165], v[42:45]
	v_mfma_f32_16x16x32_bf16 v[34:37], v[206:209], v[170:173], v[34:37]
	v_mfma_f32_16x16x32_bf16 v[26:29], v[214:217], v[170:173], v[26:29]
	v_mfma_f32_16x16x32_bf16 v[18:21], v[206:209], v[178:181], v[18:21]
	v_mfma_f32_16x16x32_bf16 v[10:13], v[214:217], v[178:181], v[10:13]
	v_mfma_f32_16x16x32_bf16 v[6:9], v[206:209], v[186:189], v[6:9]
	v_mfma_f32_16x16x32_bf16 v[2:5], v[214:217], v[186:189], v[2:5]
	v_mfma_f32_16x16x32_bf16 v[50:53], v[210:213], v[166:169], v[50:53]
	v_mfma_f32_16x16x32_bf16 v[42:45], v[218:221], v[166:169], v[42:45]
	v_mfma_f32_16x16x32_bf16 v[34:37], v[210:213], v[174:177], v[34:37]
	v_mfma_f32_16x16x32_bf16 v[26:29], v[218:221], v[174:177], v[26:29]
	v_mfma_f32_16x16x32_bf16 v[18:21], v[210:213], v[182:185], v[18:21]
	v_mfma_f32_16x16x32_bf16 v[10:13], v[218:221], v[182:185], v[10:13]
	v_mfma_f32_16x16x32_bf16 v[6:9], v[210:213], v[190:193], v[6:9]
	v_mfma_f32_16x16x32_bf16 v[2:5], v[218:221], v[190:193], v[2:5]
	s_add_i32 s41, s41, 2
	s_add_u32 s6, s6, 0x100
	s_addc_u32 s7, s7, 0
	s_add_u32 s28, s28, 0x100
	s_addc_u32 s29, s29, 0
	s_cmp_gt_u32 s41, 29
	s_barrier
	s_cbranch_scc0 .LBB0_139
	s_cmp_gt_i32 s79, 3
	s_mov_b64 s[6:7], -1
	s_cbranch_scc0 .LBB0_146
	s_lshl_b32 s10, s82, 8
	v_lshl_or_b32 v140, s80, 8, v149
	s_cmp_lg_u32 s79, 4
	v_ashrrev_i32_e32 v141, 31, v140
	s_cbranch_scc0 .LBB0_143
	v_readlane_b32 s6, v252, 55
	v_readlane_b32 s7, v252, 56
	v_add_u32_e32 v150, s10, v147
	s_nop 0
	v_mov_b64_e32 v[142:143], s[6:7]
	s_mov_b32 s6, 0x9000
	v_mad_i64_i32 v[142:143], s[6:7], v150, s6, v[142:143]
	v_lshl_add_u64 v[142:143], v[140:141], 1, v[142:143]
	v_cvt_pk_bf16_f32 v150, v126, v127
	v_cvt_pk_bf16_f32 v151, v128, v129
	v_cvt_pk_bf16_f32 v152, v122, v123
	v_cvt_pk_bf16_f32 v153, v124, v125
	global_store_dwordx4 v[142:143], v[150:153], off
	v_add_co_u32_e32 v154, vcc, s44, v142
	s_nop 0
	v_cvt_pk_bf16_f32 v150, v114, v115
	v_cvt_pk_bf16_f32 v151, v116, v117
	v_cvt_pk_bf16_f32 v152, v106, v107
	v_cvt_pk_bf16_f32 v153, v108, v109
	global_store_dwordx4 v[142:143], v[150:153], off offset:256
	v_addc_co_u32_e32 v155, vcc, 0, v143, vcc
	s_nop 0
	v_cvt_pk_bf16_f32 v150, v118, v119
	v_cvt_pk_bf16_f32 v151, v120, v121
	v_cvt_pk_bf16_f32 v152, v110, v111
	v_cvt_pk_bf16_f32 v153, v112, v113
	global_store_dwordx4 v[154:155], v[150:153], off
	s_mov_b64 s[6:7], 0
	s_nop 0
	v_cvt_pk_bf16_f32 v150, v98, v99
	v_cvt_pk_bf16_f32 v151, v100, v101
	v_cvt_pk_bf16_f32 v152, v90, v91
	v_cvt_pk_bf16_f32 v153, v92, v93
	global_store_dwordx4 v[154:155], v[150:153], off offset:256
	v_add_co_u32_e32 v154, vcc, s45, v142
	s_nop 0
	v_cvt_pk_bf16_f32 v150, v102, v103
	v_cvt_pk_bf16_f32 v151, v104, v105
	v_cvt_pk_bf16_f32 v152, v94, v95
	v_cvt_pk_bf16_f32 v153, v96, v97
	s_nop 0
	v_addc_co_u32_e32 v155, vcc, 0, v143, vcc
	global_store_dwordx4 v[154:155], v[150:153], off
	s_nop 1
	v_cvt_pk_bf16_f32 v150, v82, v83
	v_cvt_pk_bf16_f32 v151, v84, v85
	v_cvt_pk_bf16_f32 v152, v74, v75
	v_cvt_pk_bf16_f32 v153, v76, v77
	global_store_dwordx4 v[154:155], v[150:153], off offset:256
	v_add_co_u32_e32 v154, vcc, s90, v142
	s_nop 0
	v_cvt_pk_bf16_f32 v150, v86, v87
	v_cvt_pk_bf16_f32 v151, v88, v89
	v_cvt_pk_bf16_f32 v152, v78, v79
	v_cvt_pk_bf16_f32 v153, v80, v81
	s_nop 0
	v_addc_co_u32_e32 v155, vcc, 0, v143, vcc
	global_store_dwordx4 v[154:155], v[150:153], off
	s_nop 1
	v_cvt_pk_bf16_f32 v150, v70, v71
	v_cvt_pk_bf16_f32 v151, v72, v73
	v_cvt_pk_bf16_f32 v152, v66, v67
	v_cvt_pk_bf16_f32 v153, v68, v69
	global_store_dwordx4 v[154:155], v[150:153], off offset:256
	v_add_co_u32_e32 v154, vcc, s20, v142
	s_nop 0
	v_cvt_pk_bf16_f32 v150, v62, v63
	v_cvt_pk_bf16_f32 v151, v64, v65
	v_cvt_pk_bf16_f32 v152, v58, v59
	v_cvt_pk_bf16_f32 v153, v60, v61
	s_nop 0
	v_addc_co_u32_e32 v155, vcc, 0, v143, vcc
	global_store_dwordx4 v[154:155], v[150:153], off
	s_nop 1
	v_cvt_pk_bf16_f32 v150, v50, v51
	v_cvt_pk_bf16_f32 v151, v52, v53
	v_cvt_pk_bf16_f32 v152, v42, v43
	v_cvt_pk_bf16_f32 v153, v44, v45
	global_store_dwordx4 v[154:155], v[150:153], off offset:256
	v_add_co_u32_e32 v154, vcc, s21, v142
	s_nop 0
	v_cvt_pk_bf16_f32 v150, v54, v55
	v_cvt_pk_bf16_f32 v151, v56, v57
	v_cvt_pk_bf16_f32 v152, v46, v47
	v_cvt_pk_bf16_f32 v153, v48, v49
	s_nop 0
	v_addc_co_u32_e32 v155, vcc, 0, v143, vcc
	global_store_dwordx4 v[154:155], v[150:153], off
	s_nop 1
	v_cvt_pk_bf16_f32 v150, v34, v35
	v_cvt_pk_bf16_f32 v151, v36, v37
	v_cvt_pk_bf16_f32 v152, v26, v27
	v_cvt_pk_bf16_f32 v153, v28, v29
	global_store_dwordx4 v[154:155], v[150:153], off offset:256
	v_add_co_u32_e32 v154, vcc, s22, v142
	s_nop 0
	v_cvt_pk_bf16_f32 v150, v38, v39
	v_cvt_pk_bf16_f32 v151, v40, v41
	v_cvt_pk_bf16_f32 v152, v30, v31
	v_cvt_pk_bf16_f32 v153, v32, v33
	s_nop 0
	v_addc_co_u32_e32 v155, vcc, 0, v143, vcc
	global_store_dwordx4 v[154:155], v[150:153], off
	v_add_co_u32_e32 v142, vcc, s23, v142
	s_nop 0
	v_cvt_pk_bf16_f32 v150, v18, v19
	v_cvt_pk_bf16_f32 v151, v20, v21
	v_cvt_pk_bf16_f32 v152, v10, v11
	v_cvt_pk_bf16_f32 v153, v12, v13
	global_store_dwordx4 v[154:155], v[150:153], off offset:256
	v_addc_co_u32_e32 v143, vcc, 0, v143, vcc
	s_nop 0
	v_cvt_pk_bf16_f32 v150, v22, v23
	v_cvt_pk_bf16_f32 v151, v24, v25
	v_cvt_pk_bf16_f32 v152, v14, v15
	v_cvt_pk_bf16_f32 v153, v16, v17
	global_store_dwordx4 v[142:143], v[150:153], off
	s_nop 1
	v_cvt_pk_bf16_f32 v150, v6, v7
	v_cvt_pk_bf16_f32 v151, v8, v9
	v_cvt_pk_bf16_f32 v152, v2, v3
	v_cvt_pk_bf16_f32 v153, v4, v5
	global_store_dwordx4 v[142:143], v[150:153], off offset:256

.LBB0_204:
	s_add_u32 s80, s54, s62
	s_addc_u32 s81, s55, s63
	s_add_u32 s82, s80, 0x100
	s_addc_u32 s83, s81, 0
	s_and_b64 s[10:11], s[8:9], exec
	s_cselect_b32 s83, s1, s83
	s_cselect_b32 s82, s0, s82
	s_add_u32 s10, s52, s62
	s_addc_u32 s11, s53, s63
	s_add_u32 s10, s10, 0x100
	s_addc_u32 s11, s11, 0
	s_and_b64 s[8:9], s[8:9], exec
	s_cselect_b32 vcc_hi, s7, s11
	s_cselect_b32 vcc_lo, s6, s10
	s_add_u32 s10, s80, 0x10080
	v_add_u32_e32 v253, 0x10000, v142
	s_addc_u32 s11, s81, 0
	s_add_i32 m0, s5, 0xc000
	s_add_i32 s87, s5, 0xe000
	ds_read_b128 v[144:147], v253
	s_add_u32 s80, vcc_lo, 0x340000
	ds_read_b128 v[148:151], v253 offset:1024
	s_addc_u32 s81, vcc_hi, 0
	ds_read_b128 v[152:155], v253 offset:2048
	s_add_u32 s62, s82, 0x10000
	ds_read_b128 v[156:159], v253 offset:3072
	s_addc_u32 s63, s83, 0
	s_add_u32 s8, vcc_lo, 0x340080
	s_addc_u32 s9, vcc_hi, 0
	ds_read_b128 v[160:163], v141
	ds_read_b128 v[164:167], v141 offset:1024
	ds_read_b128 v[168:171], v141 offset:2048
	ds_read_b128 v[172:175], v141 offset:3072
	ds_read_b128 v[176:179], v141 offset:4096
	ds_read_b128 v[180:183], v141 offset:5120
	ds_read_b128 v[184:187], v141 offset:6144
	ds_read_b128 v[188:191], v141 offset:7168
	global_load_lds_dwordx4 v136, s[10:11]
	s_mov_b32 m0, s87
	s_nop 0
	global_load_lds_dwordx4 v132, s[10:11]
	s_waitcnt lgkmcnt(8)
	s_barrier
	s_waitcnt lgkmcnt(0)
	v_mfma_f32_16x16x32_bf16 v[126:129], v[144:147], v[160:163], v[126:129]
	v_mfma_f32_16x16x32_bf16 v[122:125], v[152:155], v[160:163], v[122:125]
	v_mfma_f32_16x16x32_bf16 v[118:121], v[144:147], v[168:171], v[118:121]
	v_mfma_f32_16x16x32_bf16 v[110:113], v[152:155], v[168:171], v[110:113]
	v_mfma_f32_16x16x32_bf16 v[102:105], v[144:147], v[176:179], v[102:105]
	v_mfma_f32_16x16x32_bf16 v[94:97], v[152:155], v[176:179], v[94:97]
	v_mfma_f32_16x16x32_bf16 v[86:89], v[144:147], v[184:187], v[86:89]
	v_mfma_f32_16x16x32_bf16 v[78:81], v[152:155], v[184:187], v[78:81]
	v_mfma_f32_16x16x32_bf16 v[126:129], v[148:151], v[164:167], v[126:129]
	v_mfma_f32_16x16x32_bf16 v[122:125], v[156:159], v[164:167], v[122:125]
	v_mfma_f32_16x16x32_bf16 v[118:121], v[148:151], v[172:175], v[118:121]
	v_mfma_f32_16x16x32_bf16 v[110:113], v[156:159], v[172:175], v[110:113]
	v_mfma_f32_16x16x32_bf16 v[102:105], v[148:151], v[180:183], v[102:105]
	v_mfma_f32_16x16x32_bf16 v[94:97], v[156:159], v[180:183], v[94:97]
	v_mfma_f32_16x16x32_bf16 v[86:89], v[148:151], v[188:191], v[86:89]
	v_mfma_f32_16x16x32_bf16 v[78:81], v[156:159], v[188:191], v[78:81]
	s_barrier
	ds_read_b128 v[206:209], v253 offset:16384
	ds_read_b128 v[210:213], v253 offset:17408
	s_mov_b32 m0, s12
	ds_read_b128 v[214:217], v253 offset:18432
	ds_read_b128 v[218:221], v253 offset:19456
	v_lshl_add_u64 v[138:139], vcc, 0, v[134:135]
	global_load_lds_dwordx4 v[138:139], off
	v_lshl_add_u64 v[192:193], vcc, 0, v[130:131]
	s_mov_b32 m0, s17
	s_nop 0
	global_load_lds_dwordx4 v[192:193], off
	s_barrier
	s_waitcnt lgkmcnt(0)
	v_mfma_f32_16x16x32_bf16 v[114:117], v[206:209], v[160:163], v[114:117]
	v_mfma_f32_16x16x32_bf16 v[106:109], v[214:217], v[160:163], v[106:109]
	v_mfma_f32_16x16x32_bf16 v[98:101], v[206:209], v[168:171], v[98:101]
	v_mfma_f32_16x16x32_bf16 v[90:93], v[214:217], v[168:171], v[90:93]
	v_mfma_f32_16x16x32_bf16 v[82:85], v[206:209], v[176:179], v[82:85]
	v_mfma_f32_16x16x32_bf16 v[74:77], v[214:217], v[176:179], v[74:77]
	v_mfma_f32_16x16x32_bf16 v[70:73], v[206:209], v[184:187], v[70:73]
	v_mfma_f32_16x16x32_bf16 v[66:69], v[214:217], v[184:187], v[66:69]
	v_mfma_f32_16x16x32_bf16 v[114:117], v[210:213], v[164:167], v[114:117]
	v_mfma_f32_16x16x32_bf16 v[106:109], v[218:221], v[164:167], v[106:109]
	v_mfma_f32_16x16x32_bf16 v[98:101], v[210:213], v[172:175], v[98:101]
	v_mfma_f32_16x16x32_bf16 v[90:93], v[218:221], v[172:175], v[90:93]
	v_mfma_f32_16x16x32_bf16 v[82:85], v[210:213], v[180:183], v[82:85]
	v_mfma_f32_16x16x32_bf16 v[74:77], v[218:221], v[180:183], v[74:77]
	s_mov_b32 m0, s5
	v_mfma_f32_16x16x32_bf16 v[70:73], v[210:213], v[188:191], v[70:73]
	v_lshl_add_u64 v[222:223], s[82:83], 0, v[136:137]
	v_mfma_f32_16x16x32_bf16 v[66:69], v[218:221], v[188:191], v[66:69]
	s_barrier
	ds_read_b128 v[160:163], v141 offset:16384
	ds_read_b128 v[164:167], v141 offset:17408
	ds_read_b128 v[168:171], v141 offset:18432
	ds_read_b128 v[172:175], v141 offset:19456
	ds_read_b128 v[176:179], v141 offset:20480
	ds_read_b128 v[180:183], v141 offset:21504
	ds_read_b128 v[184:187], v141 offset:22528
	ds_read_b128 v[188:191], v141 offset:23552
	global_load_lds_dwordx4 v[222:223], off
	v_lshl_add_u64 v[224:225], s[82:83], 0, v[132:133]
	s_mov_b32 m0, s26
	s_nop 0
	global_load_lds_dwordx4 v[224:225], off
	s_barrier
	s_waitcnt lgkmcnt(0)
	v_mfma_f32_16x16x32_bf16 v[62:65], v[144:147], v[160:163], v[62:65]
	v_mfma_f32_16x16x32_bf16 v[58:61], v[152:155], v[160:163], v[58:61]
	v_mfma_f32_16x16x32_bf16 v[54:57], v[144:147], v[168:171], v[54:57]
	v_mfma_f32_16x16x32_bf16 v[46:49], v[152:155], v[168:171], v[46:49]
	v_mfma_f32_16x16x32_bf16 v[38:41], v[144:147], v[176:179], v[38:41]
	v_mfma_f32_16x16x32_bf16 v[30:33], v[152:155], v[176:179], v[30:33]
	v_mfma_f32_16x16x32_bf16 v[22:25], v[144:147], v[184:187], v[22:25]
	v_mfma_f32_16x16x32_bf16 v[14:17], v[152:155], v[184:187], v[14:17]
	v_mfma_f32_16x16x32_bf16 v[62:65], v[148:151], v[164:167], v[62:65]
	v_mfma_f32_16x16x32_bf16 v[58:61], v[156:159], v[164:167], v[58:61]
	v_mfma_f32_16x16x32_bf16 v[54:57], v[148:151], v[172:175], v[54:57]
	v_mfma_f32_16x16x32_bf16 v[46:49], v[156:159], v[172:175], v[46:49]
	v_mfma_f32_16x16x32_bf16 v[38:41], v[148:151], v[180:183], v[38:41]
	v_mfma_f32_16x16x32_bf16 v[30:33], v[156:159], v[180:183], v[30:33]
	v_mfma_f32_16x16x32_bf16 v[22:25], v[148:151], v[188:191], v[22:25]
	v_mfma_f32_16x16x32_bf16 v[14:17], v[156:159], v[188:191], v[14:17]
	s_barrier
	s_mov_b32 m0, s34
	s_nop 0
	global_load_lds_dwordx4 v134, s[80:81]
	s_mov_b32 m0, s35
	s_nop 0
	global_load_lds_dwordx4 v130, s[80:81]
	s_waitcnt vmcnt(6)
	s_barrier
	v_mfma_f32_16x16x32_bf16 v[50:53], v[206:209], v[160:163], v[50:53]
	v_mfma_f32_16x16x32_bf16 v[42:45], v[214:217], v[160:163], v[42:45]
	v_mfma_f32_16x16x32_bf16 v[34:37], v[206:209], v[168:171], v[34:37]
	v_mfma_f32_16x16x32_bf16 v[26:29], v[214:217], v[168:171], v[26:29]
	v_mfma_f32_16x16x32_bf16 v[18:21], v[206:209], v[176:179], v[18:21]
	v_mfma_f32_16x16x32_bf16 v[10:13], v[214:217], v[176:179], v[10:13]
	v_mfma_f32_16x16x32_bf16 v[6:9], v[206:209], v[184:187], v[6:9]
	v_mfma_f32_16x16x32_bf16 v[2:5], v[214:217], v[184:187], v[2:5]
	v_mfma_f32_16x16x32_bf16 v[50:53], v[210:213], v[164:167], v[50:53]
	v_mfma_f32_16x16x32_bf16 v[42:45], v[218:221], v[164:167], v[42:45]
	v_mfma_f32_16x16x32_bf16 v[34:37], v[210:213], v[172:175], v[34:37]
	v_mfma_f32_16x16x32_bf16 v[26:29], v[218:221], v[172:175], v[26:29]
	v_mfma_f32_16x16x32_bf16 v[18:21], v[210:213], v[180:183], v[18:21]
	v_mfma_f32_16x16x32_bf16 v[10:13], v[218:221], v[180:183], v[10:13]
	v_mfma_f32_16x16x32_bf16 v[6:9], v[210:213], v[188:191], v[6:9]
	v_mfma_f32_16x16x32_bf16 v[2:5], v[218:221], v[188:191], v[2:5]
	s_barrier
	ds_read_b128 v[144:147], v253 offset:32768
	ds_read_b128 v[148:151], v253 offset:33792
	ds_read_b128 v[152:155], v253 offset:34816
	ds_read_b128 v[156:159], v253 offset:35840
	s_mov_b32 m0, s56
	ds_read_b128 v[160:163], v141 offset:32768
	ds_read_b128 v[164:167], v141 offset:33792
	ds_read_b128 v[168:171], v141 offset:34816
	ds_read_b128 v[172:175], v141 offset:35840
	ds_read_b128 v[176:179], v141 offset:36864
	ds_read_b128 v[180:183], v141 offset:37888
	ds_read_b128 v[184:187], v141 offset:38912
	ds_read_b128 v[188:191], v141 offset:39936
	global_load_lds_dwordx4 v136, s[62:63]
	s_mov_b32 m0, s57
	s_nop 0
	global_load_lds_dwordx4 v132, s[62:63]
	s_waitcnt lgkmcnt(8)
	s_barrier
	s_waitcnt lgkmcnt(0)
	v_mfma_f32_16x16x32_bf16 v[126:129], v[144:147], v[160:163], v[126:129]
	v_mfma_f32_16x16x32_bf16 v[122:125], v[152:155], v[160:163], v[122:125]
	v_mfma_f32_16x16x32_bf16 v[118:121], v[144:147], v[168:171], v[118:121]
	v_mfma_f32_16x16x32_bf16 v[110:113], v[152:155], v[168:171], v[110:113]
	v_mfma_f32_16x16x32_bf16 v[102:105], v[144:147], v[176:179], v[102:105]
	v_mfma_f32_16x16x32_bf16 v[94:97], v[152:155], v[176:179], v[94:97]
	v_mfma_f32_16x16x32_bf16 v[86:89], v[144:147], v[184:187], v[86:89]
	v_mfma_f32_16x16x32_bf16 v[78:81], v[152:155], v[184:187], v[78:81]
	v_mfma_f32_16x16x32_bf16 v[126:129], v[148:151], v[164:167], v[126:129]
	v_mfma_f32_16x16x32_bf16 v[122:125], v[156:159], v[164:167], v[122:125]
	v_mfma_f32_16x16x32_bf16 v[118:121], v[148:151], v[172:175], v[118:121]
	v_mfma_f32_16x16x32_bf16 v[110:113], v[156:159], v[172:175], v[110:113]
	v_mfma_f32_16x16x32_bf16 v[102:105], v[148:151], v[180:183], v[102:105]
	v_mfma_f32_16x16x32_bf16 v[94:97], v[156:159], v[180:183], v[94:97]
	v_mfma_f32_16x16x32_bf16 v[86:89], v[148:151], v[188:191], v[86:89]
	v_mfma_f32_16x16x32_bf16 v[78:81], v[156:159], v[188:191], v[78:81]
	s_barrier
	s_mov_b32 m0, s58
	ds_read_b128 v[206:209], v253 offset:49152
	ds_read_b128 v[210:213], v253 offset:50176
	v_lshl_add_u64 v[138:139], v[138:139], 0, s[76:77]
	ds_read_b128 v[214:217], v253 offset:51200
	ds_read_b128 v[218:221], v253 offset:52224
	global_load_lds_dwordx4 v[138:139], off
	v_lshl_add_u64 v[138:139], v[192:193], 0, s[76:77]
	s_mov_b32 m0, s59
	s_nop 0
	global_load_lds_dwordx4 v[138:139], off
	s_barrier
	s_waitcnt lgkmcnt(0)
	v_mfma_f32_16x16x32_bf16 v[114:117], v[206:209], v[160:163], v[114:117]
	v_mfma_f32_16x16x32_bf16 v[106:109], v[214:217], v[160:163], v[106:109]
	v_mfma_f32_16x16x32_bf16 v[98:101], v[206:209], v[168:171], v[98:101]
	v_mfma_f32_16x16x32_bf16 v[90:93], v[214:217], v[168:171], v[90:93]
	v_mfma_f32_16x16x32_bf16 v[82:85], v[206:209], v[176:179], v[82:85]
	v_mfma_f32_16x16x32_bf16 v[74:77], v[214:217], v[176:179], v[74:77]
	v_mfma_f32_16x16x32_bf16 v[70:73], v[206:209], v[184:187], v[70:73]
	v_mfma_f32_16x16x32_bf16 v[66:69], v[214:217], v[184:187], v[66:69]
	v_mfma_f32_16x16x32_bf16 v[114:117], v[210:213], v[164:167], v[114:117]
	v_mfma_f32_16x16x32_bf16 v[106:109], v[218:221], v[164:167], v[106:109]
	v_mfma_f32_16x16x32_bf16 v[98:101], v[210:213], v[172:175], v[98:101]
	v_mfma_f32_16x16x32_bf16 v[90:93], v[218:221], v[172:175], v[90:93]
	v_mfma_f32_16x16x32_bf16 v[82:85], v[210:213], v[180:183], v[82:85]
	v_mfma_f32_16x16x32_bf16 v[74:77], v[218:221], v[180:183], v[74:77]
	s_mov_b32 m0, s67
	v_mfma_f32_16x16x32_bf16 v[70:73], v[210:213], v[188:191], v[70:73]
	v_lshl_add_u64 v[138:139], v[222:223], 0, s[76:77]
	v_mfma_f32_16x16x32_bf16 v[66:69], v[218:221], v[188:191], v[66:69]
	s_barrier
	ds_read_b128 v[160:163], v141 offset:49152
	ds_read_b128 v[164:167], v141 offset:50176
	ds_read_b128 v[168:171], v141 offset:51200
	ds_read_b128 v[172:175], v141 offset:52224
	ds_read_b128 v[176:179], v141 offset:53248
	ds_read_b128 v[180:183], v141 offset:54272
	ds_read_b128 v[184:187], v141 offset:55296
	ds_read_b128 v[188:191], v141 offset:56320
	global_load_lds_dwordx4 v[138:139], off
	v_lshl_add_u64 v[138:139], v[224:225], 0, s[76:77]
	s_mov_b32 m0, s70
	s_nop 0
	global_load_lds_dwordx4 v[138:139], off
	s_barrier
	s_waitcnt lgkmcnt(0)
	v_mfma_f32_16x16x32_bf16 v[62:65], v[144:147], v[160:163], v[62:65]
	v_mfma_f32_16x16x32_bf16 v[58:61], v[152:155], v[160:163], v[58:61]
	v_mfma_f32_16x16x32_bf16 v[54:57], v[144:147], v[168:171], v[54:57]
	v_mfma_f32_16x16x32_bf16 v[46:49], v[152:155], v[168:171], v[46:49]
	v_mfma_f32_16x16x32_bf16 v[38:41], v[144:147], v[176:179], v[38:41]
	v_mfma_f32_16x16x32_bf16 v[30:33], v[152:155], v[176:179], v[30:33]
	v_mfma_f32_16x16x32_bf16 v[22:25], v[144:147], v[184:187], v[22:25]
	v_mfma_f32_16x16x32_bf16 v[14:17], v[152:155], v[184:187], v[14:17]
	v_mfma_f32_16x16x32_bf16 v[62:65], v[148:151], v[164:167], v[62:65]
	v_mfma_f32_16x16x32_bf16 v[58:61], v[156:159], v[164:167], v[58:61]
	v_mfma_f32_16x16x32_bf16 v[54:57], v[148:151], v[172:175], v[54:57]
	v_mfma_f32_16x16x32_bf16 v[46:49], v[156:159], v[172:175], v[46:49]
	v_mfma_f32_16x16x32_bf16 v[38:41], v[148:151], v[180:183], v[38:41]
	v_mfma_f32_16x16x32_bf16 v[30:33], v[156:159], v[180:183], v[30:33]
	v_mfma_f32_16x16x32_bf16 v[22:25], v[148:151], v[188:191], v[22:25]
	v_mfma_f32_16x16x32_bf16 v[14:17], v[156:159], v[188:191], v[14:17]
	s_barrier
	s_mov_b32 m0, s71
	s_nop 0
	global_load_lds_dwordx4 v134, s[8:9]
	s_mov_b32 m0, s78
	s_nop 0
	global_load_lds_dwordx4 v130, s[8:9]
	s_waitcnt vmcnt(6)
	s_barrier
	v_mfma_f32_16x16x32_bf16 v[50:53], v[206:209], v[160:163], v[50:53]
	v_mfma_f32_16x16x32_bf16 v[42:45], v[214:217], v[160:163], v[42:45]
	v_mfma_f32_16x16x32_bf16 v[34:37], v[206:209], v[168:171], v[34:37]
	v_mfma_f32_16x16x32_bf16 v[26:29], v[214:217], v[168:171], v[26:29]
	v_mfma_f32_16x16x32_bf16 v[18:21], v[206:209], v[176:179], v[18:21]
	v_mfma_f32_16x16x32_bf16 v[10:13], v[214:217], v[176:179], v[10:13]
	v_mfma_f32_16x16x32_bf16 v[6:9], v[206:209], v[184:187], v[6:9]
	v_mfma_f32_16x16x32_bf16 v[2:5], v[214:217], v[184:187], v[2:5]
	v_mfma_f32_16x16x32_bf16 v[50:53], v[210:213], v[164:167], v[50:53]
	v_mfma_f32_16x16x32_bf16 v[42:45], v[218:221], v[164:167], v[42:45]
	v_mfma_f32_16x16x32_bf16 v[34:37], v[210:213], v[172:175], v[34:37]
	v_mfma_f32_16x16x32_bf16 v[26:29], v[218:221], v[172:175], v[26:29]
	v_mfma_f32_16x16x32_bf16 v[18:21], v[210:213], v[180:183], v[18:21]
	v_mfma_f32_16x16x32_bf16 v[10:13], v[218:221], v[180:183], v[10:13]
	v_mfma_f32_16x16x32_bf16 v[6:9], v[210:213], v[188:191], v[6:9]
	v_mfma_f32_16x16x32_bf16 v[2:5], v[218:221], v[188:191], v[2:5]
	s_andn2_b64 vcc, exec, s[60:61]
	s_mov_b64 s[8:9], -1
	s_mov_b64 s[60:61], 0
	s_mov_b64 s[62:63], 0x100
	s_barrier
	s_cbranch_vccz .LBB0_204
	s_cmp_gt_i32 s29, 63
	s_cbranch_scc0 .LBB0_207
	s_lshl_b32 s8, s29, 10
	s_lshl_b32 s9, s94, 8
	s_add_i32 s9, s9, s8
	v_add_u32_e32 v138, s9, v143
	v_ashrrev_i32_e32 v139, 31, v138
	v_lshlrev_b64 v[138:139], 10, v[138:139]
	s_lshl_b32 s8, s42, 8
	v_lshl_add_u64 v[138:139], s[64:65], 0, v[138:139]
	s_ashr_i32 s9, s8, 31
	v_lshl_add_u64 v[138:139], s[8:9], 1, v[138:139]
	s_mov_b64 s[8:9], 0

.LBB0_255:
	v_add_u32_e32 v253, 0x10000, v182
	ds_read_b128 v[130:133], v253
	ds_read_b128 v[134:137], v253 offset:1024
	ds_read_b128 v[138:141], v253 offset:2048
	ds_read_b128 v[142:145], v253 offset:3072
	s_add_u32 s8, s6, 0xfff00080
	s_addc_u32 s9, s7, -1
	s_cmp_eq_u32 s79, 60
	s_cselect_b32 s11, s53, s9
	s_cselect_b32 s10, s52, s8
	s_cselect_b32 s9, s61, s78
	s_cselect_b32 s8, s60, s1
	s_add_i32 m0, s5, 0xc000
	ds_read_b128 v[146:149], v181
	ds_read_b128 v[150:153], v181 offset:1024
	ds_read_b128 v[154:157], v181 offset:2048
	ds_read_b128 v[170:173], v181 offset:3072
	ds_read_b128 v[174:177], v181 offset:4096
	ds_read_b128 v[184:187], v181 offset:5120
	ds_read_b128 v[188:191], v181 offset:6144
	ds_read_b128 v[206:209], v181 offset:7168
	global_load_lds_dwordx4 v166, s[6:7]
	s_add_i32 m0, s5, 0xe000
	s_nop 0
	global_load_lds_dwordx4 v168, s[6:7]
	s_waitcnt lgkmcnt(8)
	s_barrier
	s_waitcnt lgkmcnt(0)
	v_mfma_f32_16x16x32_bf16 v[126:129], v[130:133], v[146:149], v[126:129]
	v_mfma_f32_16x16x32_bf16 v[122:125], v[138:141], v[146:149], v[122:125]
	v_mfma_f32_16x16x32_bf16 v[110:113], v[130:133], v[154:157], v[110:113]
	v_mfma_f32_16x16x32_bf16 v[106:109], v[138:141], v[154:157], v[106:109]
	v_mfma_f32_16x16x32_bf16 v[94:97], v[130:133], v[174:177], v[94:97]
	v_mfma_f32_16x16x32_bf16 v[90:93], v[138:141], v[174:177], v[90:93]
	v_mfma_f32_16x16x32_bf16 v[78:81], v[130:133], v[188:191], v[78:81]
	v_mfma_f32_16x16x32_bf16 v[74:77], v[138:141], v[188:191], v[74:77]
	v_mfma_f32_16x16x32_bf16 v[126:129], v[134:137], v[150:153], v[126:129]
	v_mfma_f32_16x16x32_bf16 v[122:125], v[142:145], v[150:153], v[122:125]
	v_mfma_f32_16x16x32_bf16 v[110:113], v[134:137], v[170:173], v[110:113]
	v_mfma_f32_16x16x32_bf16 v[106:109], v[142:145], v[170:173], v[106:109]
	v_mfma_f32_16x16x32_bf16 v[94:97], v[134:137], v[184:187], v[94:97]
	v_mfma_f32_16x16x32_bf16 v[90:93], v[142:145], v[184:187], v[90:93]
	v_mfma_f32_16x16x32_bf16 v[78:81], v[134:137], v[206:209], v[78:81]
	v_mfma_f32_16x16x32_bf16 v[74:77], v[142:145], v[206:209], v[74:77]
	s_barrier
	ds_read_b128 v[210:213], v253 offset:16384
	ds_read_b128 v[214:217], v253 offset:17408
	s_mov_b32 m0, s12
	ds_read_b128 v[218:221], v253 offset:18432
	ds_read_b128 v[222:225], v253 offset:19456
	global_load_lds_dwordx4 v162, s[8:9]
	s_mov_b32 m0, s17
	s_nop 0
	global_load_lds_dwordx4 v158, s[8:9]
	s_barrier
	s_waitcnt lgkmcnt(0)
	v_mfma_f32_16x16x32_bf16 v[118:121], v[210:213], v[146:149], v[118:121]
	v_mfma_f32_16x16x32_bf16 v[114:117], v[218:221], v[146:149], v[114:117]
	v_mfma_f32_16x16x32_bf16 v[102:105], v[210:213], v[154:157], v[102:105]
	v_mfma_f32_16x16x32_bf16 v[98:101], v[218:221], v[154:157], v[98:101]
	v_mfma_f32_16x16x32_bf16 v[86:89], v[210:213], v[174:177], v[86:89]
	v_mfma_f32_16x16x32_bf16 v[82:85], v[218:221], v[174:177], v[82:85]
	v_mfma_f32_16x16x32_bf16 v[70:73], v[210:213], v[188:191], v[70:73]
	v_mfma_f32_16x16x32_bf16 v[66:69], v[218:221], v[188:191], v[66:69]
	v_mfma_f32_16x16x32_bf16 v[118:121], v[214:217], v[150:153], v[118:121]
	v_mfma_f32_16x16x32_bf16 v[114:117], v[222:225], v[150:153], v[114:117]
	v_mfma_f32_16x16x32_bf16 v[102:105], v[214:217], v[170:173], v[102:105]
	v_mfma_f32_16x16x32_bf16 v[98:101], v[222:225], v[170:173], v[98:101]
	v_mfma_f32_16x16x32_bf16 v[86:89], v[214:217], v[184:187], v[86:89]
	v_mfma_f32_16x16x32_bf16 v[82:85], v[222:225], v[184:187], v[82:85]
	v_mfma_f32_16x16x32_bf16 v[70:73], v[214:217], v[206:209], v[70:73]
	s_mov_b32 m0, s5
	v_mfma_f32_16x16x32_bf16 v[66:69], v[222:225], v[206:209], v[66:69]
	s_barrier
	ds_read_b128 v[146:149], v181 offset:16384
	ds_read_b128 v[150:153], v181 offset:17408
	ds_read_b128 v[154:157], v181 offset:18432
	ds_read_b128 v[170:173], v181 offset:19456
	ds_read_b128 v[174:177], v181 offset:20480
	ds_read_b128 v[184:187], v181 offset:21504
	ds_read_b128 v[188:191], v181 offset:22528
	ds_read_b128 v[206:209], v181 offset:23552
	global_load_lds_dwordx4 v164, s[10:11]
	s_mov_b32 m0, s26
	s_nop 0
	global_load_lds_dwordx4 v160, s[10:11]
	s_barrier
	s_waitcnt lgkmcnt(0)
	v_mfma_f32_16x16x32_bf16 v[62:65], v[130:133], v[146:149], v[62:65]
	v_mfma_f32_16x16x32_bf16 v[58:61], v[138:141], v[146:149], v[58:61]
	v_mfma_f32_16x16x32_bf16 v[46:49], v[130:133], v[154:157], v[46:49]
	v_mfma_f32_16x16x32_bf16 v[42:45], v[138:141], v[154:157], v[42:45]
	v_mfma_f32_16x16x32_bf16 v[30:33], v[130:133], v[174:177], v[30:33]
	v_mfma_f32_16x16x32_bf16 v[26:29], v[138:141], v[174:177], v[26:29]
	v_mfma_f32_16x16x32_bf16 v[14:17], v[130:133], v[188:191], v[14:17]
	v_mfma_f32_16x16x32_bf16 v[10:13], v[138:141], v[188:191], v[10:13]
	v_mfma_f32_16x16x32_bf16 v[62:65], v[134:137], v[150:153], v[62:65]
	v_mfma_f32_16x16x32_bf16 v[58:61], v[142:145], v[150:153], v[58:61]
	v_mfma_f32_16x16x32_bf16 v[46:49], v[134:137], v[170:173], v[46:49]
	v_mfma_f32_16x16x32_bf16 v[42:45], v[142:145], v[170:173], v[42:45]
	v_mfma_f32_16x16x32_bf16 v[30:33], v[134:137], v[184:187], v[30:33]
	v_mfma_f32_16x16x32_bf16 v[26:29], v[142:145], v[184:187], v[26:29]
	v_mfma_f32_16x16x32_bf16 v[14:17], v[134:137], v[206:209], v[14:17]
	v_mfma_f32_16x16x32_bf16 v[10:13], v[142:145], v[206:209], v[10:13]
	s_barrier
	s_add_u32 s80, s8, 0x100000
	s_addc_u32 s81, s9, 0
	s_mov_b32 m0, s34
	s_nop 0
	global_load_lds_dwordx4 v162, s[80:81]
	s_mov_b32 m0, s35
	s_nop 0
	global_load_lds_dwordx4 v158, s[80:81]
	s_waitcnt vmcnt(6)
	s_barrier
	v_mfma_f32_16x16x32_bf16 v[54:57], v[210:213], v[146:149], v[54:57]
	v_mfma_f32_16x16x32_bf16 v[50:53], v[218:221], v[146:149], v[50:53]
	v_mfma_f32_16x16x32_bf16 v[38:41], v[210:213], v[154:157], v[38:41]
	v_mfma_f32_16x16x32_bf16 v[34:37], v[218:221], v[154:157], v[34:37]
	v_mfma_f32_16x16x32_bf16 v[22:25], v[210:213], v[174:177], v[22:25]
	v_mfma_f32_16x16x32_bf16 v[18:21], v[218:221], v[174:177], v[18:21]
	v_mfma_f32_16x16x32_bf16 v[6:9], v[210:213], v[188:191], v[6:9]
	v_mfma_f32_16x16x32_bf16 v[2:5], v[218:221], v[188:191], v[2:5]
	v_mfma_f32_16x16x32_bf16 v[54:57], v[214:217], v[150:153], v[54:57]
	v_mfma_f32_16x16x32_bf16 v[50:53], v[222:225], v[150:153], v[50:53]
	v_mfma_f32_16x16x32_bf16 v[38:41], v[214:217], v[170:173], v[38:41]
	v_mfma_f32_16x16x32_bf16 v[34:37], v[222:225], v[170:173], v[34:37]
	v_mfma_f32_16x16x32_bf16 v[22:25], v[214:217], v[184:187], v[22:25]
	v_mfma_f32_16x16x32_bf16 v[18:21], v[222:225], v[184:187], v[18:21]
	v_mfma_f32_16x16x32_bf16 v[6:9], v[214:217], v[206:209], v[6:9]
	v_mfma_f32_16x16x32_bf16 v[2:5], v[222:225], v[206:209], v[2:5]
	s_barrier
	ds_read_b128 v[130:133], v253 offset:32768
	ds_read_b128 v[134:137], v253 offset:33792
	ds_read_b128 v[138:141], v253 offset:34816
	ds_read_b128 v[142:145], v253 offset:35840
	s_add_u32 s10, s10, 0x100000
	s_addc_u32 s11, s11, 0
	s_mov_b32 m0, s42
	ds_read_b128 v[146:149], v181 offset:32768
	ds_read_b128 v[150:153], v181 offset:33792
	ds_read_b128 v[154:157], v181 offset:34816
	ds_read_b128 v[170:173], v181 offset:35840
	ds_read_b128 v[174:177], v181 offset:36864
	ds_read_b128 v[184:187], v181 offset:37888
	ds_read_b128 v[188:191], v181 offset:38912
	ds_read_b128 v[206:209], v181 offset:39936
	global_load_lds_dwordx4 v164, s[10:11]
	s_mov_b32 m0, s54
	s_nop 0
	global_load_lds_dwordx4 v160, s[10:11]
	s_waitcnt lgkmcnt(8)
	s_barrier
	s_waitcnt lgkmcnt(0)
	v_mfma_f32_16x16x32_bf16 v[126:129], v[130:133], v[146:149], v[126:129]
	v_mfma_f32_16x16x32_bf16 v[122:125], v[138:141], v[146:149], v[122:125]
	v_mfma_f32_16x16x32_bf16 v[110:113], v[130:133], v[154:157], v[110:113]
	v_mfma_f32_16x16x32_bf16 v[106:109], v[138:141], v[154:157], v[106:109]
	v_mfma_f32_16x16x32_bf16 v[94:97], v[130:133], v[174:177], v[94:97]
	v_mfma_f32_16x16x32_bf16 v[90:93], v[138:141], v[174:177], v[90:93]
	v_mfma_f32_16x16x32_bf16 v[78:81], v[130:133], v[188:191], v[78:81]
	v_mfma_f32_16x16x32_bf16 v[74:77], v[138:141], v[188:191], v[74:77]
	v_mfma_f32_16x16x32_bf16 v[126:129], v[134:137], v[150:153], v[126:129]
	v_mfma_f32_16x16x32_bf16 v[122:125], v[142:145], v[150:153], v[122:125]
	v_mfma_f32_16x16x32_bf16 v[110:113], v[134:137], v[170:173], v[110:113]
	v_mfma_f32_16x16x32_bf16 v[106:109], v[142:145], v[170:173], v[106:109]
	v_mfma_f32_16x16x32_bf16 v[94:97], v[134:137], v[184:187], v[94:97]
	v_mfma_f32_16x16x32_bf16 v[90:93], v[142:145], v[184:187], v[90:93]
	v_mfma_f32_16x16x32_bf16 v[78:81], v[134:137], v[206:209], v[78:81]
	v_mfma_f32_16x16x32_bf16 v[74:77], v[142:145], v[206:209], v[74:77]
	s_barrier
	s_mov_b32 m0, s55
	ds_read_b128 v[210:213], v253 offset:49152
	ds_read_b128 v[214:217], v253 offset:50176
	ds_read_b128 v[218:221], v253 offset:51200
	ds_read_b128 v[222:225], v253 offset:52224
	s_add_u32 s98, s8, 0x80
	s_addc_u32 s99, s9, 0
	global_load_lds_dwordx4 v162, s[98:99]
	s_mov_b32 m0, s56
	s_nop 0
	global_load_lds_dwordx4 v158, s[98:99]
	s_barrier
	s_waitcnt lgkmcnt(0)
	v_mfma_f32_16x16x32_bf16 v[118:121], v[210:213], v[146:149], v[118:121]
	v_mfma_f32_16x16x32_bf16 v[114:117], v[218:221], v[146:149], v[114:117]
	v_mfma_f32_16x16x32_bf16 v[102:105], v[210:213], v[154:157], v[102:105]
	v_mfma_f32_16x16x32_bf16 v[98:101], v[218:221], v[154:157], v[98:101]
	v_mfma_f32_16x16x32_bf16 v[86:89], v[210:213], v[174:177], v[86:89]
	v_mfma_f32_16x16x32_bf16 v[82:85], v[218:221], v[174:177], v[82:85]
	v_mfma_f32_16x16x32_bf16 v[70:73], v[210:213], v[188:191], v[70:73]
	v_mfma_f32_16x16x32_bf16 v[66:69], v[218:221], v[188:191], v[66:69]
	v_mfma_f32_16x16x32_bf16 v[118:121], v[214:217], v[150:153], v[118:121]
	v_mfma_f32_16x16x32_bf16 v[114:117], v[222:225], v[150:153], v[114:117]
	v_mfma_f32_16x16x32_bf16 v[102:105], v[214:217], v[170:173], v[102:105]
	v_mfma_f32_16x16x32_bf16 v[98:101], v[222:225], v[170:173], v[98:101]
	v_mfma_f32_16x16x32_bf16 v[86:89], v[214:217], v[184:187], v[86:89]
	v_mfma_f32_16x16x32_bf16 v[82:85], v[222:225], v[184:187], v[82:85]
	v_mfma_f32_16x16x32_bf16 v[70:73], v[214:217], v[206:209], v[70:73]
	s_mov_b32 m0, s57
	v_mfma_f32_16x16x32_bf16 v[66:69], v[222:225], v[206:209], v[66:69]
	s_barrier
	ds_read_b128 v[146:149], v181 offset:49152
	ds_read_b128 v[150:153], v181 offset:50176
	ds_read_b128 v[154:157], v181 offset:51200
	ds_read_b128 v[170:173], v181 offset:52224
	ds_read_b128 v[174:177], v181 offset:53248
	ds_read_b128 v[184:187], v181 offset:54272
	ds_read_b128 v[188:191], v181 offset:55296
	ds_read_b128 v[206:209], v181 offset:56320
	s_add_u32 s100, s10, 0xfff00080
	s_addc_u32 s101, s11, -1
	global_load_lds_dwordx4 v164, s[100:101]
	s_mov_b32 m0, s58
	s_nop 0
	global_load_lds_dwordx4 v160, s[100:101]
	s_barrier
	s_waitcnt lgkmcnt(0)
	v_mfma_f32_16x16x32_bf16 v[62:65], v[130:133], v[146:149], v[62:65]
	v_mfma_f32_16x16x32_bf16 v[58:61], v[138:141], v[146:149], v[58:61]
	v_mfma_f32_16x16x32_bf16 v[46:49], v[130:133], v[154:157], v[46:49]
	v_mfma_f32_16x16x32_bf16 v[42:45], v[138:141], v[154:157], v[42:45]
	v_mfma_f32_16x16x32_bf16 v[30:33], v[130:133], v[174:177], v[30:33]
	v_mfma_f32_16x16x32_bf16 v[26:29], v[138:141], v[174:177], v[26:29]
	v_mfma_f32_16x16x32_bf16 v[14:17], v[130:133], v[188:191], v[14:17]
	v_mfma_f32_16x16x32_bf16 v[10:13], v[138:141], v[188:191], v[10:13]
	v_mfma_f32_16x16x32_bf16 v[62:65], v[134:137], v[150:153], v[62:65]
	v_mfma_f32_16x16x32_bf16 v[58:61], v[142:145], v[150:153], v[58:61]
	v_mfma_f32_16x16x32_bf16 v[46:49], v[134:137], v[170:173], v[46:49]
	v_mfma_f32_16x16x32_bf16 v[42:45], v[142:145], v[170:173], v[42:45]
	v_mfma_f32_16x16x32_bf16 v[30:33], v[134:137], v[184:187], v[30:33]
	v_mfma_f32_16x16x32_bf16 v[26:29], v[142:145], v[184:187], v[26:29]
	v_mfma_f32_16x16x32_bf16 v[14:17], v[134:137], v[206:209], v[14:17]
	v_mfma_f32_16x16x32_bf16 v[10:13], v[142:145], v[206:209], v[10:13]
	s_barrier
	s_add_u32 s8, s8, 0x100080
	s_addc_u32 s9, s9, 0
	s_mov_b32 m0, s59
	s_nop 0
	global_load_lds_dwordx4 v162, s[8:9]
	s_mov_b32 m0, s67
	s_nop 0
	global_load_lds_dwordx4 v158, s[8:9]
	s_waitcnt vmcnt(6)
	s_barrier
	v_mfma_f32_16x16x32_bf16 v[54:57], v[210:213], v[146:149], v[54:57]
	v_mfma_f32_16x16x32_bf16 v[50:53], v[218:221], v[146:149], v[50:53]
	v_mfma_f32_16x16x32_bf16 v[38:41], v[210:213], v[154:157], v[38:41]
	v_mfma_f32_16x16x32_bf16 v[34:37], v[218:221], v[154:157], v[34:37]
	v_mfma_f32_16x16x32_bf16 v[22:25], v[210:213], v[174:177], v[22:25]
	v_mfma_f32_16x16x32_bf16 v[18:21], v[218:221], v[174:177], v[18:21]
	v_mfma_f32_16x16x32_bf16 v[6:9], v[210:213], v[188:191], v[6:9]
	v_mfma_f32_16x16x32_bf16 v[2:5], v[218:221], v[188:191], v[2:5]
	v_mfma_f32_16x16x32_bf16 v[54:57], v[214:217], v[150:153], v[54:57]
	v_mfma_f32_16x16x32_bf16 v[50:53], v[222:225], v[150:153], v[50:53]
	v_mfma_f32_16x16x32_bf16 v[38:41], v[214:217], v[170:173], v[38:41]
	v_mfma_f32_16x16x32_bf16 v[34:37], v[222:225], v[170:173], v[34:37]
	v_mfma_f32_16x16x32_bf16 v[22:25], v[214:217], v[184:187], v[22:25]
	v_mfma_f32_16x16x32_bf16 v[18:21], v[222:225], v[184:187], v[18:21]
	v_mfma_f32_16x16x32_bf16 v[6:9], v[214:217], v[206:209], v[6:9]
	v_mfma_f32_16x16x32_bf16 v[2:5], v[222:225], v[206:209], v[2:5]
	s_add_i32 s79, s79, 2
	s_add_u32 s6, s6, 0x100
	s_addc_u32 s7, s7, 0
	s_add_u32 s1, s1, 0x100
	s_addc_u32 s78, s78, 0
	s_cmp_gt_u32 s79, 61
	s_barrier
	s_cbranch_scc0 .LBB0_255
	s_lshl_b32 s1, s28, 9
	s_and_b32 s1, s1, 0xfffff800
	s_lshl_b32 s6, s29, 8
	s_add_i32 s1, s1, s6
	v_add_u32_e32 v172, s1, v180
	s_lshl_b32 s1, s28, 8
	s_and_b32 s1, s1, 0x300
	v_or_b32_e32 v132, s1, v183
	v_mov_b64_e32 v[170:171], s[50:51]
	v_mad_i64_i32 v[130:131], s[6:7], v172, s37, v[170:171]
	v_lshlrev_b32_e32 v194, 1, v132
	v_lshl_add_u64 v[130:131], v[130:131], 0, v[194:195]
	v_lshl_add_u64 v[132:133], v[130:131], 0, s[84:85]
	v_add_co_u32_e32 v130, vcc, s16, v130
	v_or_b32_e32 v178, 16, v172
	s_nop 0
	v_addc_co_u32_e32 v131, vcc, 0, v131, vcc
	global_load_dwordx4 v[184:187], v[130:131], off offset:2048
	global_load_dwordx4 v[154:157], v[132:133], off offset:256
	v_mad_i64_i32 v[130:131], s[6:7], v178, s37, v[170:171]
	v_lshl_add_u64 v[130:131], v[130:131], 0, v[194:195]
	v_lshl_add_u64 v[132:133], v[130:131], 0, s[84:85]
	v_add_co_u32_e32 v130, vcc, s16, v130
	v_or_b32_e32 v176, 32, v172
	s_nop 0
	v_addc_co_u32_e32 v131, vcc, 0, v131, vcc
	global_load_dwordx4 v[150:153], v[130:131], off offset:2048
	global_load_dwordx4 v[146:149], v[132:133], off offset:256
	v_mad_i64_i32 v[130:131], s[6:7], v176, s37, v[170:171]
	v_lshl_add_u64 v[130:131], v[130:131], 0, v[194:195]
	v_lshl_add_u64 v[132:133], v[130:131], 0, s[84:85]
	v_add_co_u32_e32 v130, vcc, s16, v130
	v_or_b32_e32 v174, 48, v172
	s_nop 0
	v_addc_co_u32_e32 v131, vcc, 0, v131, vcc
	global_load_dwordx4 v[142:145], v[130:131], off offset:2048
	global_load_dwordx4 v[138:141], v[132:133], off offset:256
	v_mad_i64_i32 v[130:131], s[6:7], v174, s37, v[170:171]
	v_lshl_add_u64 v[130:131], v[130:131], 0, v[194:195]
	v_lshl_add_u64 v[132:133], v[130:131], 0, s[84:85]
	v_add_co_u32_e32 v130, vcc, s16, v130
	v_pk_mul_f32 v[126:127], v[126:127], s[72:73] op_sel_hi:[1,0]
	s_nop 0
	v_addc_co_u32_e32 v131, vcc, 0, v131, vcc
	global_load_dwordx4 v[134:137], v[130:131], off offset:2048
	s_nop 0
	global_load_dwordx4 v[130:133], v[132:133], off offset:256
	v_pk_mul_f32 v[190:191], v[124:125], s[72:73] op_sel_hi:[1,0]
	v_pk_mul_f32 v[128:129], v[128:129], s[72:73] op_sel_hi:[1,0]
	v_pk_mul_f32 v[122:123], v[122:123], s[72:73] op_sel_hi:[1,0]
	v_ashrrev_i32_e32 v173, 31, v172
	v_lshlrev_b64 v[188:189], 11, v[172:173]
	v_pk_mul_f32 v[118:119], v[118:119], s[72:73] op_sel_hi:[1,0]
	v_pk_mul_f32 v[120:121], v[120:121], s[72:73] op_sel_hi:[1,0]
	v_pk_mul_f32 v[110:111], v[110:111], s[72:73] op_sel_hi:[1,0]
	v_pk_mul_f32 v[112:113], v[112:113], s[72:73] op_sel_hi:[1,0]
	v_ashrrev_i32_e32 v179, 31, v178
	v_pk_mul_f32 v[102:103], v[102:103], s[72:73] op_sel_hi:[1,0]
	v_pk_mul_f32 v[104:105], v[104:105], s[72:73] op_sel_hi:[1,0]
	v_pk_mul_f32 v[94:95], v[94:95], s[72:73] op_sel_hi:[1,0]
	v_pk_mul_f32 v[96:97], v[96:97], s[72:73] op_sel_hi:[1,0]
	v_ashrrev_i32_e32 v177, 31, v176
	v_pk_mul_f32 v[86:87], v[86:87], s[72:73] op_sel_hi:[1,0]
	v_pk_mul_f32 v[88:89], v[88:89], s[72:73] op_sel_hi:[1,0]
	v_pk_mul_f32 v[78:79], v[78:79], s[72:73] op_sel_hi:[1,0]
	v_pk_mul_f32 v[80:81], v[80:81], s[72:73] op_sel_hi:[1,0]
	v_ashrrev_i32_e32 v175, 31, v174
	v_pk_mul_f32 v[70:71], v[70:71], s[72:73] op_sel_hi:[1,0]
	v_pk_mul_f32 v[72:73], v[72:73], s[72:73] op_sel_hi:[1,0]
	s_waitcnt vmcnt(0)
	v_lshlrev_b32_e32 v124, 16, v184
	v_and_b32_e32 v125, 0xffff0000, v184
	v_mul_f32_e32 v124, v126, v124
	v_mul_f32_e32 v125, v127, v125
	v_cvt_pk_bf16_f32 v124, v124, v125
	v_lshlrev_b32_e32 v125, 16, v185
	v_and_b32_e32 v126, 0xffff0000, v185
	v_mul_f32_e32 v125, v128, v125
	v_mul_f32_e32 v126, v129, v126
	v_cvt_pk_bf16_f32 v125, v125, v126
	v_lshlrev_b32_e32 v126, 16, v186
	v_mul_f32_e32 v122, v122, v126
	v_and_b32_e32 v126, 0xffff0000, v186
	v_mul_f32_e32 v123, v123, v126
	v_cvt_pk_bf16_f32 v126, v122, v123
	v_lshlrev_b32_e32 v122, 16, v187
	v_and_b32_e32 v123, 0xffff0000, v187
	v_mul_f32_e32 v122, v190, v122
	v_mul_f32_e32 v123, v191, v123
	v_cvt_pk_bf16_f32 v127, v122, v123
	v_lshl_add_u64 v[122:123], s[74:75], 0, v[188:189]
	v_lshl_add_u64 v[122:123], v[122:123], 0, v[194:195]
	global_store_dwordx4 v[122:123], v[124:127], off
	s_nop 1
	v_pk_mul_f32 v[124:125], v[116:117], s[72:73] op_sel_hi:[1,0]
	v_pk_mul_f32 v[116:117], v[114:115], s[72:73] op_sel_hi:[1,0]
	v_lshlrev_b32_e32 v114, 16, v154
	v_and_b32_e32 v115, 0xffff0000, v154
	v_mul_f32_e32 v114, v118, v114
	v_mul_f32_e32 v115, v119, v115
	v_cvt_pk_bf16_f32 v114, v114, v115
	v_lshlrev_b32_e32 v115, 16, v155
	v_and_b32_e32 v118, 0xffff0000, v155
	v_mul_f32_e32 v115, v120, v115
	v_mul_f32_e32 v118, v121, v118
	v_cvt_pk_bf16_f32 v115, v115, v118
	v_lshlrev_b32_e32 v118, 16, v156
	v_mul_f32_e32 v116, v116, v118
	v_and_b32_e32 v118, 0xffff0000, v156
	v_mul_f32_e32 v117, v117, v118
	v_cvt_pk_bf16_f32 v116, v116, v117
	v_lshlrev_b32_e32 v117, 16, v157
	v_mul_f32_e32 v117, v124, v117
	v_and_b32_e32 v118, 0xffff0000, v157
	v_mul_f32_e32 v118, v125, v118
	v_cvt_pk_bf16_f32 v117, v117, v118
	global_store_dwordx4 v[122:123], v[114:117], off offset:256
	s_nop 1
	v_pk_mul_f32 v[116:117], v[108:109], s[72:73] op_sel_hi:[1,0]
	v_pk_mul_f32 v[108:109], v[106:107], s[72:73] op_sel_hi:[1,0]
	v_lshlrev_b32_e32 v106, 16, v150
	v_and_b32_e32 v107, 0xffff0000, v150
	v_mul_f32_e32 v106, v110, v106
	v_mul_f32_e32 v107, v111, v107
	v_cvt_pk_bf16_f32 v106, v106, v107
	v_lshlrev_b32_e32 v107, 16, v151
	v_and_b32_e32 v110, 0xffff0000, v151
	v_mul_f32_e32 v107, v112, v107
	v_mul_f32_e32 v110, v113, v110
	v_cvt_pk_bf16_f32 v107, v107, v110
	v_lshlrev_b32_e32 v110, 16, v152
	v_mul_f32_e32 v108, v108, v110
	v_and_b32_e32 v110, 0xffff0000, v152
	v_mul_f32_e32 v109, v109, v110
	v_cvt_pk_bf16_f32 v108, v108, v109
	v_lshlrev_b32_e32 v109, 16, v153
	v_and_b32_e32 v110, 0xffff0000, v153
	v_lshlrev_b64 v[114:115], 11, v[178:179]
	v_mul_f32_e32 v109, v116, v109
	v_mul_f32_e32 v110, v117, v110
	v_cvt_pk_bf16_f32 v109, v109, v110
	v_lshl_add_u64 v[110:111], s[74:75], 0, v[114:115]
	v_lshl_add_u64 v[110:111], v[110:111], 0, v[194:195]
	global_store_dwordx4 v[110:111], v[106:109], off
	s_nop 1
	v_pk_mul_f32 v[106:107], v[100:101], s[72:73] op_sel_hi:[1,0]
	v_pk_mul_f32 v[100:101], v[98:99], s[72:73] op_sel_hi:[1,0]
	v_lshlrev_b32_e32 v98, 16, v146
	v_and_b32_e32 v99, 0xffff0000, v146
	v_mul_f32_e32 v98, v102, v98
	v_mul_f32_e32 v99, v103, v99
	v_cvt_pk_bf16_f32 v98, v98, v99
	v_lshlrev_b32_e32 v99, 16, v147
	v_and_b32_e32 v102, 0xffff0000, v147
	v_mul_f32_e32 v99, v104, v99
	v_mul_f32_e32 v102, v105, v102
	v_cvt_pk_bf16_f32 v99, v99, v102
	v_lshlrev_b32_e32 v102, 16, v148
	v_mul_f32_e32 v100, v100, v102
	v_and_b32_e32 v102, 0xffff0000, v148
	v_mul_f32_e32 v101, v101, v102
	v_cvt_pk_bf16_f32 v100, v100, v101
	v_lshlrev_b32_e32 v101, 16, v149
	v_mul_f32_e32 v101, v106, v101
	v_and_b32_e32 v102, 0xffff0000, v149
	v_mul_f32_e32 v102, v107, v102
	v_cvt_pk_bf16_f32 v101, v101, v102
	global_store_dwordx4 v[110:111], v[98:101], off offset:256
	s_nop 1
	v_pk_mul_f32 v[100:101], v[92:93], s[72:73] op_sel_hi:[1,0]
	v_pk_mul_f32 v[92:93], v[90:91], s[72:73] op_sel_hi:[1,0]
	v_lshlrev_b32_e32 v90, 16, v142
	v_and_b32_e32 v91, 0xffff0000, v142
	v_mul_f32_e32 v90, v94, v90
	v_mul_f32_e32 v91, v95, v91
	v_cvt_pk_bf16_f32 v90, v90, v91
	v_lshlrev_b32_e32 v91, 16, v143
	v_and_b32_e32 v94, 0xffff0000, v143
	v_mul_f32_e32 v91, v96, v91
	v_mul_f32_e32 v94, v97, v94
	v_cvt_pk_bf16_f32 v91, v91, v94
	v_lshlrev_b32_e32 v94, 16, v144
	v_mul_f32_e32 v92, v92, v94
	v_and_b32_e32 v94, 0xffff0000, v144
	v_mul_f32_e32 v93, v93, v94
	v_cvt_pk_bf16_f32 v92, v92, v93
	v_lshlrev_b32_e32 v93, 16, v145
	v_and_b32_e32 v94, 0xffff0000, v145
	v_lshlrev_b64 v[98:99], 11, v[176:177]
	v_mul_f32_e32 v93, v100, v93
	v_mul_f32_e32 v94, v101, v94
	v_cvt_pk_bf16_f32 v93, v93, v94
	v_lshl_add_u64 v[94:95], s[74:75], 0, v[98:99]
	v_lshl_add_u64 v[94:95], v[94:95], 0, v[194:195]
	global_store_dwordx4 v[94:95], v[90:93], off
	s_nop 1
	v_pk_mul_f32 v[90:91], v[84:85], s[72:73] op_sel_hi:[1,0]
	v_pk_mul_f32 v[84:85], v[82:83], s[72:73] op_sel_hi:[1,0]
	v_lshlrev_b32_e32 v82, 16, v138
	v_and_b32_e32 v83, 0xffff0000, v138
	v_mul_f32_e32 v82, v86, v82
	v_mul_f32_e32 v83, v87, v83
	v_cvt_pk_bf16_f32 v82, v82, v83
	v_lshlrev_b32_e32 v83, 16, v139
	v_and_b32_e32 v86, 0xffff0000, v139
	v_mul_f32_e32 v83, v88, v83
	v_mul_f32_e32 v86, v89, v86
	v_cvt_pk_bf16_f32 v83, v83, v86
	v_lshlrev_b32_e32 v86, 16, v140
	v_mul_f32_e32 v84, v84, v86
	v_and_b32_e32 v86, 0xffff0000, v140
	v_mul_f32_e32 v85, v85, v86
	v_cvt_pk_bf16_f32 v84, v84, v85
	v_lshlrev_b32_e32 v85, 16, v141
	v_mul_f32_e32 v85, v90, v85
	v_and_b32_e32 v86, 0xffff0000, v141
	v_mul_f32_e32 v86, v91, v86
	v_cvt_pk_bf16_f32 v85, v85, v86
	global_store_dwordx4 v[94:95], v[82:85], off offset:256
	s_nop 1
	v_pk_mul_f32 v[84:85], v[76:77], s[72:73] op_sel_hi:[1,0]
	v_pk_mul_f32 v[76:77], v[74:75], s[72:73] op_sel_hi:[1,0]
	v_lshlrev_b32_e32 v74, 16, v134
	v_and_b32_e32 v75, 0xffff0000, v134
	v_mul_f32_e32 v74, v78, v74
	v_mul_f32_e32 v75, v79, v75
	v_cvt_pk_bf16_f32 v74, v74, v75
	v_lshlrev_b32_e32 v75, 16, v135
	v_and_b32_e32 v78, 0xffff0000, v135
	v_mul_f32_e32 v75, v80, v75
	v_mul_f32_e32 v78, v81, v78
	v_cvt_pk_bf16_f32 v75, v75, v78
	v_lshlrev_b32_e32 v78, 16, v136
	v_mul_f32_e32 v76, v76, v78
	v_and_b32_e32 v78, 0xffff0000, v136
	v_mul_f32_e32 v77, v77, v78
	v_cvt_pk_bf16_f32 v76, v76, v77
	v_lshlrev_b32_e32 v77, 16, v137
	v_and_b32_e32 v78, 0xffff0000, v137
	v_lshlrev_b64 v[82:83], 11, v[174:175]
	v_mul_f32_e32 v77, v84, v77
	v_mul_f32_e32 v78, v85, v78
	v_cvt_pk_bf16_f32 v77, v77, v78
	v_lshl_add_u64 v[78:79], s[74:75], 0, v[82:83]
	v_lshl_add_u64 v[78:79], v[78:79], 0, v[194:195]
	global_store_dwordx4 v[78:79], v[74:77], off
	s_nop 1
	v_pk_mul_f32 v[74:75], v[68:69], s[72:73] op_sel_hi:[1,0]
	v_pk_mul_f32 v[68:69], v[66:67], s[72:73] op_sel_hi:[1,0]
	v_lshlrev_b32_e32 v66, 16, v130
	v_and_b32_e32 v67, 0xffff0000, v130
	v_mul_f32_e32 v66, v70, v66
	v_mul_f32_e32 v67, v71, v67
	v_cvt_pk_bf16_f32 v66, v66, v67
	v_lshlrev_b32_e32 v67, 16, v131
	v_and_b32_e32 v70, 0xffff0000, v131
	v_mul_f32_e32 v67, v72, v67
	v_mul_f32_e32 v70, v73, v70
	v_cvt_pk_bf16_f32 v67, v67, v70
	v_lshlrev_b32_e32 v70, 16, v132
	v_mul_f32_e32 v68, v68, v70
	v_and_b32_e32 v70, 0xffff0000, v132
	v_mul_f32_e32 v69, v69, v70
	v_cvt_pk_bf16_f32 v68, v68, v69
	v_lshlrev_b32_e32 v69, 16, v133
	v_mul_f32_e32 v69, v74, v69
	v_and_b32_e32 v70, 0xffff0000, v133
	v_mul_f32_e32 v70, v75, v70
	v_cvt_pk_bf16_f32 v69, v69, v70
	global_store_dwordx4 v[78:79], v[66:69], off offset:256
	v_add_u32_e32 v78, 0x80, v172
	s_nop 0
	v_mad_i64_i32 v[66:67], s[6:7], v78, s37, v[170:171]
	v_lshl_add_u64 v[66:67], v[66:67], 0, v[194:195]
	v_add_co_u32_e32 v68, vcc, s16, v66
	v_add_u32_e32 v86, 0x90, v172
	s_nop 0
	v_addc_co_u32_e32 v69, vcc, 0, v67, vcc
	global_load_dwordx4 v[70:73], v[68:69], off offset:2048
	v_lshl_add_u64 v[66:67], v[66:67], 0, s[84:85]
	global_load_dwordx4 v[74:77], v[66:67], off offset:256
	v_pk_mul_f32 v[96:97], v[56:57], s[72:73] op_sel_hi:[1,0]
	v_mad_i64_i32 v[56:57], s[6:7], v86, s37, v[170:171]
	v_lshl_add_u64 v[56:57], v[56:57], 0, v[194:195]
	v_pk_mul_f32 v[94:95], v[58:59], s[72:73] op_sel_hi:[1,0]
	v_add_co_u32_e32 v58, vcc, s16, v56
	v_pk_mul_f32 v[92:93], v[60:61], s[72:73] op_sel_hi:[1,0]
	s_nop 0
	v_addc_co_u32_e32 v59, vcc, 0, v57, vcc
	global_load_dwordx4 v[58:61], v[58:59], off offset:2048
	v_add_u32_e32 v68, 0xa0, v172
	v_pk_mul_f32 v[102:103], v[50:51], s[72:73] op_sel_hi:[1,0]
	v_mad_i64_i32 v[50:51], s[6:7], v68, s37, v[170:171]
	v_add_u32_e32 v66, 0xb0, v172
	v_lshl_add_u64 v[50:51], v[50:51], 0, v[194:195]
	v_pk_mul_f32 v[100:101], v[52:53], s[72:73] op_sel_hi:[1,0]
	v_mad_i64_i32 v[52:53], s[6:7], v66, s37, v[170:171]
	v_lshl_add_u64 v[82:83], v[50:51], 0, s[84:85]
	v_add_co_u32_e32 v50, vcc, s16, v50
	v_lshl_add_u64 v[52:53], v[52:53], 0, v[194:195]
	s_nop 0
	v_addc_co_u32_e32 v51, vcc, 0, v51, vcc
	v_ashrrev_i32_e32 v79, 31, v78
	v_lshl_add_u64 v[104:105], v[52:53], 0, s[84:85]
	v_add_co_u32_e32 v52, vcc, s16, v52
	v_pk_mul_f32 v[98:99], v[54:55], s[72:73] op_sel_hi:[1,0]
	v_lshlrev_b64 v[54:55], 11, v[78:79]
	v_lshl_add_u64 v[56:57], v[56:57], 0, s[84:85]
	v_addc_co_u32_e32 v53, vcc, 0, v53, vcc
	v_pk_mul_f32 v[88:89], v[64:65], s[72:73] op_sel_hi:[1,0]
	v_pk_mul_f32 v[90:91], v[62:63], s[72:73] op_sel_hi:[1,0]
	v_lshl_add_u64 v[106:107], s[74:75], 0, v[54:55]
	global_load_dwordx4 v[62:65], v[56:57], off offset:256
	global_load_dwordx4 v[78:81], v[50:51], off offset:2048
	s_nop 0
	global_load_dwordx4 v[82:85], v[82:83], off offset:256
	s_nop 0
	global_load_dwordx4 v[54:57], v[52:53], off offset:2048
	s_nop 0
	global_load_dwordx4 v[50:53], v[104:105], off offset:256
	v_lshl_add_u64 v[104:105], v[106:107], 0, v[194:195]
	v_pk_mul_f32 v[46:47], v[46:47], s[72:73] op_sel_hi:[1,0]
	v_pk_mul_f32 v[48:49], v[48:49], s[72:73] op_sel_hi:[1,0]
	v_ashrrev_i32_e32 v87, 31, v86
	v_pk_mul_f32 v[38:39], v[38:39], s[72:73] op_sel_hi:[1,0]
	v_pk_mul_f32 v[40:41], v[40:41], s[72:73] op_sel_hi:[1,0]
	v_pk_mul_f32 v[30:31], v[30:31], s[72:73] op_sel_hi:[1,0]
	v_pk_mul_f32 v[32:33], v[32:33], s[72:73] op_sel_hi:[1,0]
	v_ashrrev_i32_e32 v69, 31, v68
	v_pk_mul_f32 v[22:23], v[22:23], s[72:73] op_sel_hi:[1,0]
	v_pk_mul_f32 v[24:25], v[24:25], s[72:73] op_sel_hi:[1,0]
	v_pk_mul_f32 v[14:15], v[14:15], s[72:73] op_sel_hi:[1,0]
	v_pk_mul_f32 v[16:17], v[16:17], s[72:73] op_sel_hi:[1,0]
	v_ashrrev_i32_e32 v67, 31, v66
	v_pk_mul_f32 v[6:7], v[6:7], s[72:73] op_sel_hi:[1,0]
	v_pk_mul_f32 v[8:9], v[8:9], s[72:73] op_sel_hi:[1,0]
	s_waitcnt vmcnt(0)
	v_lshlrev_b32_e32 v106, 16, v70
	v_and_b32_e32 v70, 0xffff0000, v70
	v_lshlrev_b32_e32 v107, 16, v71
	v_and_b32_e32 v71, 0xffff0000, v71
	v_lshlrev_b32_e32 v108, 16, v72
	v_and_b32_e32 v72, 0xffff0000, v72
	v_lshlrev_b32_e32 v109, 16, v73
	v_and_b32_e32 v73, 0xffff0000, v73
	v_mul_f32_e32 v70, v91, v70
	v_mul_f32_e32 v71, v89, v71
	v_mul_f32_e32 v72, v95, v72
	v_mul_f32_e32 v73, v93, v73
	v_mul_f32_e32 v90, v90, v106
	v_mul_f32_e32 v88, v88, v107
	v_mul_f32_e32 v89, v94, v108
	v_mul_f32_e32 v91, v92, v109
	v_cvt_pk_bf16_f32 v70, v90, v70
	v_cvt_pk_bf16_f32 v71, v88, v71
	v_cvt_pk_bf16_f32 v72, v89, v72
	v_cvt_pk_bf16_f32 v73, v91, v73
	v_lshlrev_b32_e32 v111, 16, v75
	v_and_b32_e32 v75, 0xffff0000, v75
	global_store_dwordx4 v[104:105], v[70:73], off
	v_lshlrev_b32_e32 v110, 16, v74
	v_and_b32_e32 v74, 0xffff0000, v74
	v_lshlrev_b32_e32 v72, 16, v76
	v_and_b32_e32 v73, 0xffff0000, v76
	v_mul_f32_e32 v71, v97, v75
	v_mul_f32_e32 v72, v102, v72
	v_mul_f32_e32 v73, v103, v73
	v_mul_f32_e32 v92, v98, v110
	v_mul_f32_e32 v74, v99, v74
	v_mul_f32_e32 v93, v96, v111
	v_cvt_pk_bf16_f32 v70, v92, v74
	v_cvt_pk_bf16_f32 v71, v93, v71
	v_cvt_pk_bf16_f32 v72, v72, v73
	v_lshlrev_b32_e32 v73, 16, v77
	v_mul_f32_e32 v73, v100, v73
	v_and_b32_e32 v74, 0xffff0000, v77
	v_mul_f32_e32 v74, v101, v74
	v_cvt_pk_bf16_f32 v73, v73, v74
	global_store_dwordx4 v[104:105], v[70:73], off offset:256
	s_nop 1
	v_pk_mul_f32 v[72:73], v[44:45], s[72:73] op_sel_hi:[1,0]
	v_pk_mul_f32 v[44:45], v[42:43], s[72:73] op_sel_hi:[1,0]
	v_lshlrev_b32_e32 v42, 16, v58
	v_and_b32_e32 v43, 0xffff0000, v58
	v_mul_f32_e32 v42, v46, v42
	v_mul_f32_e32 v43, v47, v43
	v_cvt_pk_bf16_f32 v42, v42, v43
	v_lshlrev_b32_e32 v43, 16, v59
	v_and_b32_e32 v46, 0xffff0000, v59
	v_mul_f32_e32 v43, v48, v43
	v_mul_f32_e32 v46, v49, v46
	v_cvt_pk_bf16_f32 v43, v43, v46
	v_lshlrev_b32_e32 v46, 16, v60
	v_mul_f32_e32 v44, v44, v46
	v_and_b32_e32 v46, 0xffff0000, v60
	v_mul_f32_e32 v45, v45, v46
	v_cvt_pk_bf16_f32 v44, v44, v45
	v_lshlrev_b32_e32 v45, 16, v61
	v_and_b32_e32 v46, 0xffff0000, v61
	v_lshlrev_b64 v[70:71], 11, v[86:87]
	v_mul_f32_e32 v45, v72, v45
	v_mul_f32_e32 v46, v73, v46
	v_cvt_pk_bf16_f32 v45, v45, v46
	v_lshl_add_u64 v[46:47], s[74:75], 0, v[70:71]
	v_lshl_add_u64 v[46:47], v[46:47], 0, v[194:195]
	global_store_dwordx4 v[46:47], v[42:45], off
	s_nop 1
	v_pk_mul_f32 v[42:43], v[36:37], s[72:73] op_sel_hi:[1,0]
	v_pk_mul_f32 v[36:37], v[34:35], s[72:73] op_sel_hi:[1,0]
	v_lshlrev_b32_e32 v34, 16, v62
	v_and_b32_e32 v35, 0xffff0000, v62
	v_mul_f32_e32 v34, v38, v34
	v_mul_f32_e32 v35, v39, v35
	v_cvt_pk_bf16_f32 v34, v34, v35
	v_lshlrev_b32_e32 v35, 16, v63
	v_and_b32_e32 v38, 0xffff0000, v63
	v_mul_f32_e32 v35, v40, v35
	v_mul_f32_e32 v38, v41, v38
	v_cvt_pk_bf16_f32 v35, v35, v38
	v_lshlrev_b32_e32 v38, 16, v64
	v_mul_f32_e32 v36, v36, v38
	v_and_b32_e32 v38, 0xffff0000, v64
	v_mul_f32_e32 v37, v37, v38
	v_cvt_pk_bf16_f32 v36, v36, v37
	v_lshlrev_b32_e32 v37, 16, v65
	v_mul_f32_e32 v37, v42, v37
	v_and_b32_e32 v38, 0xffff0000, v65
	v_mul_f32_e32 v38, v43, v38
	v_cvt_pk_bf16_f32 v37, v37, v38
	global_store_dwordx4 v[46:47], v[34:37], off offset:256
	s_nop 1
	v_pk_mul_f32 v[36:37], v[28:29], s[72:73] op_sel_hi:[1,0]
	v_pk_mul_f32 v[28:29], v[26:27], s[72:73] op_sel_hi:[1,0]
	v_lshlrev_b32_e32 v26, 16, v78
	v_and_b32_e32 v27, 0xffff0000, v78
	v_mul_f32_e32 v26, v30, v26
	v_mul_f32_e32 v27, v31, v27
	v_cvt_pk_bf16_f32 v26, v26, v27
	v_lshlrev_b32_e32 v27, 16, v79
	v_and_b32_e32 v30, 0xffff0000, v79
	v_mul_f32_e32 v27, v32, v27
	v_mul_f32_e32 v30, v33, v30
	v_cvt_pk_bf16_f32 v27, v27, v30
	v_lshlrev_b32_e32 v30, 16, v80
	v_mul_f32_e32 v28, v28, v30
	v_and_b32_e32 v30, 0xffff0000, v80
	v_mul_f32_e32 v29, v29, v30
	v_cvt_pk_bf16_f32 v28, v28, v29
	v_lshlrev_b32_e32 v29, 16, v81
	v_and_b32_e32 v30, 0xffff0000, v81
	v_lshlrev_b64 v[34:35], 11, v[68:69]
	v_mul_f32_e32 v29, v36, v29
	v_mul_f32_e32 v30, v37, v30
	v_cvt_pk_bf16_f32 v29, v29, v30
	v_lshl_add_u64 v[30:31], s[74:75], 0, v[34:35]
	v_lshl_add_u64 v[30:31], v[30:31], 0, v[194:195]
	global_store_dwordx4 v[30:31], v[26:29], off
	s_nop 1
	v_pk_mul_f32 v[26:27], v[20:21], s[72:73] op_sel_hi:[1,0]
	v_pk_mul_f32 v[20:21], v[18:19], s[72:73] op_sel_hi:[1,0]
	v_lshlrev_b32_e32 v18, 16, v82
	v_and_b32_e32 v19, 0xffff0000, v82
	v_mul_f32_e32 v18, v22, v18
	v_mul_f32_e32 v19, v23, v19
	v_cvt_pk_bf16_f32 v18, v18, v19
	v_lshlrev_b32_e32 v19, 16, v83
	v_and_b32_e32 v22, 0xffff0000, v83
	v_mul_f32_e32 v19, v24, v19
	v_mul_f32_e32 v22, v25, v22
	v_cvt_pk_bf16_f32 v19, v19, v22
	v_lshlrev_b32_e32 v22, 16, v84
	v_mul_f32_e32 v20, v20, v22
	v_and_b32_e32 v22, 0xffff0000, v84
	v_mul_f32_e32 v21, v21, v22
	v_cvt_pk_bf16_f32 v20, v20, v21
	v_lshlrev_b32_e32 v21, 16, v85
	v_mul_f32_e32 v21, v26, v21
	v_and_b32_e32 v22, 0xffff0000, v85
	v_mul_f32_e32 v22, v27, v22
	v_cvt_pk_bf16_f32 v21, v21, v22
	global_store_dwordx4 v[30:31], v[18:21], off offset:256
	s_nop 1
	v_pk_mul_f32 v[20:21], v[12:13], s[72:73] op_sel_hi:[1,0]
	v_pk_mul_f32 v[12:13], v[10:11], s[72:73] op_sel_hi:[1,0]
	v_lshlrev_b32_e32 v10, 16, v54
	v_and_b32_e32 v11, 0xffff0000, v54
	v_mul_f32_e32 v10, v14, v10
	v_mul_f32_e32 v11, v15, v11
	v_cvt_pk_bf16_f32 v10, v10, v11
	v_lshlrev_b32_e32 v11, 16, v55
	v_and_b32_e32 v14, 0xffff0000, v55
	v_mul_f32_e32 v11, v16, v11
	v_mul_f32_e32 v14, v17, v14
	v_cvt_pk_bf16_f32 v11, v11, v14
	v_lshlrev_b32_e32 v14, 16, v56
	v_mul_f32_e32 v12, v12, v14
	v_and_b32_e32 v14, 0xffff0000, v56
	v_mul_f32_e32 v13, v13, v14
	v_cvt_pk_bf16_f32 v12, v12, v13
	v_lshlrev_b32_e32 v13, 16, v57
	v_and_b32_e32 v14, 0xffff0000, v57
	v_lshlrev_b64 v[18:19], 11, v[66:67]
	v_mul_f32_e32 v13, v20, v13
	v_mul_f32_e32 v14, v21, v14
	v_cvt_pk_bf16_f32 v13, v13, v14
	v_lshl_add_u64 v[14:15], s[74:75], 0, v[18:19]
	v_lshl_add_u64 v[14:15], v[14:15], 0, v[194:195]
	global_store_dwordx4 v[14:15], v[10:13], off
	s_nop 1
	v_pk_mul_f32 v[10:11], v[4:5], s[72:73] op_sel_hi:[1,0]
	v_pk_mul_f32 v[4:5], v[2:3], s[72:73] op_sel_hi:[1,0]
	v_lshlrev_b32_e32 v2, 16, v50
	v_and_b32_e32 v3, 0xffff0000, v50
	v_mul_f32_e32 v2, v6, v2
	v_mul_f32_e32 v3, v7, v3
	v_cvt_pk_bf16_f32 v2, v2, v3
	v_lshlrev_b32_e32 v3, 16, v51
	v_and_b32_e32 v6, 0xffff0000, v51
	v_mul_f32_e32 v3, v8, v3
	v_mul_f32_e32 v6, v9, v6
	v_cvt_pk_bf16_f32 v3, v3, v6
	v_lshlrev_b32_e32 v6, 16, v52
	v_mul_f32_e32 v4, v4, v6
	v_and_b32_e32 v6, 0xffff0000, v52
	v_mul_f32_e32 v5, v5, v6
	v_cvt_pk_bf16_f32 v4, v4, v5
	v_lshlrev_b32_e32 v5, 16, v53
	v_mul_f32_e32 v5, v10, v5
	v_and_b32_e32 v6, 0xffff0000, v53
	v_mul_f32_e32 v6, v11, v6
	v_cvt_pk_bf16_f32 v5, v5, v6
	global_store_dwordx4 v[14:15], v[2:5], off offset:256
	s_and_b64 vcc, exec, s[62:63]
	s_mov_b32 s29, s71
	s_mov_b32 s28, s0
	s_mov_b64 s[8:9], s[60:61]
	s_mov_b64 s[6:7], s[52:53]
	s_cbranch_vccz .LBB0_252
	s_waitcnt vmcnt(0)
	v_readlane_b32 s28, v250, 12
	s_cmpk_gt_u32 s4, 0xff
	v_readlane_b32 s29, v250, 13
	s_mov_b32 s70, 0x800000
	s_cbranch_scc1 .LBB0_259
	s_barrier

.LBB0_266:
	s_add_u32 s8, s6, 0x100
	s_addc_u32 s9, s7, 0
	v_add_u32_e32 v253, 0x10000, v147
	s_add_u32 s10, s71, s6
	ds_read_b128 v[142:145], v253
	ds_read_b128 v[150:153], v253 offset:1024
	ds_read_b128 v[154:157], v253 offset:2048
	ds_read_b128 v[158:161], v253 offset:3072
	s_addc_u32 s11, s78, s7
	s_cmp_eq_u32 s79, 4
	s_cselect_b32 s81, 0, s8
	s_cselect_b32 s80, 0, s9
	s_cselect_b32 s54, s29, s10
	s_cselect_b32 s55, s5, s11
	s_add_u32 s10, s18, s81
	s_addc_u32 s11, s19, s80
	v_lshl_add_u64 v[206:207], v[138:139], 0, s[6:7]
	s_add_i32 m0, s17, 0xc000
	ds_read_b128 v[162:165], v146
	ds_read_b128 v[166:169], v146 offset:1024
	ds_read_b128 v[170:173], v146 offset:2048
	ds_read_b128 v[174:177], v146 offset:3072
	ds_read_b128 v[178:181], v146 offset:4096
	ds_read_b128 v[182:185], v146 offset:5120
	ds_read_b128 v[186:189], v146 offset:6144
	ds_read_b128 v[190:193], v146 offset:7168
	global_load_lds_dwordx4 v[206:207], off
	v_lshl_add_u64 v[206:207], v[140:141], 0, s[6:7]
	s_add_i32 m0, s17, 0xe000
	s_nop 0
	global_load_lds_dwordx4 v[206:207], off
	s_waitcnt lgkmcnt(8)
	s_barrier
	s_waitcnt lgkmcnt(0)
	v_mfma_f32_16x16x32_bf16 v[126:129], v[142:145], v[162:165], v[126:129]
	v_mfma_f32_16x16x32_bf16 v[122:125], v[154:157], v[162:165], v[122:125]
	v_mfma_f32_16x16x32_bf16 v[110:113], v[142:145], v[170:173], v[110:113]
	v_mfma_f32_16x16x32_bf16 v[106:109], v[154:157], v[170:173], v[106:109]
	v_mfma_f32_16x16x32_bf16 v[94:97], v[142:145], v[178:181], v[94:97]
	v_mfma_f32_16x16x32_bf16 v[90:93], v[154:157], v[178:181], v[90:93]
	v_mfma_f32_16x16x32_bf16 v[78:81], v[142:145], v[186:189], v[78:81]
	v_mfma_f32_16x16x32_bf16 v[74:77], v[154:157], v[186:189], v[74:77]
	v_mfma_f32_16x16x32_bf16 v[126:129], v[150:153], v[166:169], v[126:129]
	v_mfma_f32_16x16x32_bf16 v[122:125], v[158:161], v[166:169], v[122:125]
	v_mfma_f32_16x16x32_bf16 v[110:113], v[150:153], v[174:177], v[110:113]
	v_mfma_f32_16x16x32_bf16 v[106:109], v[158:161], v[174:177], v[106:109]
	v_mfma_f32_16x16x32_bf16 v[94:97], v[150:153], v[182:185], v[94:97]
	v_mfma_f32_16x16x32_bf16 v[90:93], v[158:161], v[182:185], v[90:93]
	v_mfma_f32_16x16x32_bf16 v[78:81], v[150:153], v[190:193], v[78:81]
	v_mfma_f32_16x16x32_bf16 v[74:77], v[158:161], v[190:193], v[74:77]
	s_barrier
	s_mov_b32 m0, s26
	ds_read_b128 v[206:209], v253 offset:16384
	ds_read_b128 v[210:213], v253 offset:17408
	v_lshl_add_u64 v[222:223], s[54:55], 0, v[134:135]
	ds_read_b128 v[214:217], v253 offset:18432
	ds_read_b128 v[218:221], v253 offset:19456
	global_load_lds_dwordx4 v[222:223], off
	v_lshl_add_u64 v[224:225], s[54:55], 0, v[130:131]
	s_mov_b32 m0, s34
	s_nop 0
	global_load_lds_dwordx4 v[224:225], off
	s_barrier
	s_waitcnt lgkmcnt(0)
	v_mfma_f32_16x16x32_bf16 v[118:121], v[206:209], v[162:165], v[118:121]
	v_mfma_f32_16x16x32_bf16 v[114:117], v[214:217], v[162:165], v[114:117]
	v_mfma_f32_16x16x32_bf16 v[102:105], v[206:209], v[170:173], v[102:105]
	v_mfma_f32_16x16x32_bf16 v[98:101], v[214:217], v[170:173], v[98:101]
	v_mfma_f32_16x16x32_bf16 v[86:89], v[206:209], v[178:181], v[86:89]
	v_mfma_f32_16x16x32_bf16 v[82:85], v[214:217], v[178:181], v[82:85]
	v_mfma_f32_16x16x32_bf16 v[70:73], v[206:209], v[186:189], v[70:73]
	v_mfma_f32_16x16x32_bf16 v[66:69], v[214:217], v[186:189], v[66:69]
	v_mfma_f32_16x16x32_bf16 v[118:121], v[210:213], v[166:169], v[118:121]
	v_mfma_f32_16x16x32_bf16 v[114:117], v[218:221], v[166:169], v[114:117]
	v_mfma_f32_16x16x32_bf16 v[102:105], v[210:213], v[174:177], v[102:105]
	v_mfma_f32_16x16x32_bf16 v[98:101], v[218:221], v[174:177], v[98:101]
	v_mfma_f32_16x16x32_bf16 v[86:89], v[210:213], v[182:185], v[86:89]
	v_mfma_f32_16x16x32_bf16 v[82:85], v[218:221], v[182:185], v[82:85]
	s_mov_b32 m0, s17
	v_mfma_f32_16x16x32_bf16 v[70:73], v[210:213], v[190:193], v[70:73]
	v_lshl_add_u64 v[226:227], s[10:11], 0, v[136:137]
	v_mfma_f32_16x16x32_bf16 v[66:69], v[218:221], v[190:193], v[66:69]
	s_barrier
	ds_read_b128 v[162:165], v146 offset:16384
	ds_read_b128 v[166:169], v146 offset:17408
	ds_read_b128 v[170:173], v146 offset:18432
	ds_read_b128 v[174:177], v146 offset:19456
	ds_read_b128 v[178:181], v146 offset:20480
	ds_read_b128 v[182:185], v146 offset:21504
	ds_read_b128 v[186:189], v146 offset:22528
	ds_read_b128 v[190:193], v146 offset:23552
	global_load_lds_dwordx4 v[226:227], off
	v_lshl_add_u64 v[228:229], s[10:11], 0, v[132:133]
	s_mov_b32 m0, s35
	s_nop 0
	global_load_lds_dwordx4 v[228:229], off
	s_barrier
	s_waitcnt lgkmcnt(0)
	v_mfma_f32_16x16x32_bf16 v[62:65], v[142:145], v[162:165], v[62:65]
	v_mfma_f32_16x16x32_bf16 v[58:61], v[154:157], v[162:165], v[58:61]
	v_mfma_f32_16x16x32_bf16 v[46:49], v[142:145], v[170:173], v[46:49]
	v_mfma_f32_16x16x32_bf16 v[42:45], v[154:157], v[170:173], v[42:45]
	v_mfma_f32_16x16x32_bf16 v[30:33], v[142:145], v[178:181], v[30:33]
	v_mfma_f32_16x16x32_bf16 v[26:29], v[154:157], v[178:181], v[26:29]
	v_mfma_f32_16x16x32_bf16 v[14:17], v[142:145], v[186:189], v[14:17]
	v_mfma_f32_16x16x32_bf16 v[10:13], v[154:157], v[186:189], v[10:13]
	v_mfma_f32_16x16x32_bf16 v[62:65], v[150:153], v[166:169], v[62:65]
	v_mfma_f32_16x16x32_bf16 v[58:61], v[158:161], v[166:169], v[58:61]
	v_mfma_f32_16x16x32_bf16 v[46:49], v[150:153], v[174:177], v[46:49]
	v_mfma_f32_16x16x32_bf16 v[42:45], v[158:161], v[174:177], v[42:45]
	v_mfma_f32_16x16x32_bf16 v[30:33], v[150:153], v[182:185], v[30:33]
	v_mfma_f32_16x16x32_bf16 v[26:29], v[158:161], v[182:185], v[26:29]
	v_mfma_f32_16x16x32_bf16 v[14:17], v[150:153], v[190:193], v[14:17]
	v_mfma_f32_16x16x32_bf16 v[10:13], v[158:161], v[190:193], v[10:13]
	s_barrier
	s_add_u32 s6, s54, 0x20000
	s_addc_u32 s7, s55, 0
	s_mov_b32 m0, s42
	s_nop 0
	global_load_lds_dwordx4 v134, s[6:7]
	s_mov_b32 m0, s56
	s_nop 0
	global_load_lds_dwordx4 v130, s[6:7]
	s_waitcnt vmcnt(6)
	s_barrier
	v_mfma_f32_16x16x32_bf16 v[54:57], v[206:209], v[162:165], v[54:57]
	v_mfma_f32_16x16x32_bf16 v[50:53], v[214:217], v[162:165], v[50:53]
	v_mfma_f32_16x16x32_bf16 v[38:41], v[206:209], v[170:173], v[38:41]
	v_mfma_f32_16x16x32_bf16 v[34:37], v[214:217], v[170:173], v[34:37]
	v_mfma_f32_16x16x32_bf16 v[22:25], v[206:209], v[178:181], v[22:25]
	v_mfma_f32_16x16x32_bf16 v[18:21], v[214:217], v[178:181], v[18:21]
	v_mfma_f32_16x16x32_bf16 v[6:9], v[206:209], v[186:189], v[6:9]
	v_mfma_f32_16x16x32_bf16 v[2:5], v[214:217], v[186:189], v[2:5]
	v_mfma_f32_16x16x32_bf16 v[54:57], v[210:213], v[166:169], v[54:57]
	v_mfma_f32_16x16x32_bf16 v[50:53], v[218:221], v[166:169], v[50:53]
	v_mfma_f32_16x16x32_bf16 v[38:41], v[210:213], v[174:177], v[38:41]
	v_mfma_f32_16x16x32_bf16 v[34:37], v[218:221], v[174:177], v[34:37]
	v_mfma_f32_16x16x32_bf16 v[22:25], v[210:213], v[182:185], v[22:25]
	v_mfma_f32_16x16x32_bf16 v[18:21], v[218:221], v[182:185], v[18:21]
	v_mfma_f32_16x16x32_bf16 v[6:9], v[210:213], v[190:193], v[6:9]
	v_mfma_f32_16x16x32_bf16 v[2:5], v[218:221], v[190:193], v[2:5]
	s_barrier
	ds_read_b128 v[142:145], v253 offset:32768
	ds_read_b128 v[150:153], v253 offset:33792
	ds_read_b128 v[154:157], v253 offset:34816
	ds_read_b128 v[158:161], v253 offset:35840
	s_add_u32 s6, s10, 0x20000
	s_addc_u32 s7, s11, 0
	s_mov_b32 m0, s57
	ds_read_b128 v[162:165], v146 offset:32768
	ds_read_b128 v[166:169], v146 offset:33792
	ds_read_b128 v[170:173], v146 offset:34816
	ds_read_b128 v[174:177], v146 offset:35840
	ds_read_b128 v[178:181], v146 offset:36864
	ds_read_b128 v[182:185], v146 offset:37888
	ds_read_b128 v[186:189], v146 offset:38912
	ds_read_b128 v[190:193], v146 offset:39936
	global_load_lds_dwordx4 v136, s[6:7]
	s_mov_b32 m0, s58
	s_nop 0
	global_load_lds_dwordx4 v132, s[6:7]
	s_waitcnt lgkmcnt(8)
	s_barrier
	s_waitcnt lgkmcnt(0)
	v_mfma_f32_16x16x32_bf16 v[126:129], v[142:145], v[162:165], v[126:129]
	v_mfma_f32_16x16x32_bf16 v[122:125], v[154:157], v[162:165], v[122:125]
	v_mfma_f32_16x16x32_bf16 v[110:113], v[142:145], v[170:173], v[110:113]
	v_mfma_f32_16x16x32_bf16 v[106:109], v[154:157], v[170:173], v[106:109]
	v_mfma_f32_16x16x32_bf16 v[94:97], v[142:145], v[178:181], v[94:97]
	v_mfma_f32_16x16x32_bf16 v[90:93], v[154:157], v[178:181], v[90:93]
	v_mfma_f32_16x16x32_bf16 v[78:81], v[142:145], v[186:189], v[78:81]
	v_mfma_f32_16x16x32_bf16 v[74:77], v[154:157], v[186:189], v[74:77]
	v_mfma_f32_16x16x32_bf16 v[126:129], v[150:153], v[166:169], v[126:129]
	v_mfma_f32_16x16x32_bf16 v[122:125], v[158:161], v[166:169], v[122:125]
	v_mfma_f32_16x16x32_bf16 v[110:113], v[150:153], v[174:177], v[110:113]
	v_mfma_f32_16x16x32_bf16 v[106:109], v[158:161], v[174:177], v[106:109]
	v_mfma_f32_16x16x32_bf16 v[94:97], v[150:153], v[182:185], v[94:97]
	v_mfma_f32_16x16x32_bf16 v[90:93], v[158:161], v[182:185], v[90:93]
	v_mfma_f32_16x16x32_bf16 v[78:81], v[150:153], v[190:193], v[78:81]
	v_mfma_f32_16x16x32_bf16 v[74:77], v[158:161], v[190:193], v[74:77]
	s_barrier
	s_mov_b32 m0, s59
	ds_read_b128 v[206:209], v253 offset:49152
	ds_read_b128 v[210:213], v253 offset:50176
	v_lshl_add_u64 v[222:223], v[222:223], 0, s[76:77]
	ds_read_b128 v[214:217], v253 offset:51200
	ds_read_b128 v[218:221], v253 offset:52224
	global_load_lds_dwordx4 v[222:223], off
	v_lshl_add_u64 v[222:223], v[224:225], 0, s[76:77]
	s_mov_b32 m0, s60
	s_nop 0
	global_load_lds_dwordx4 v[222:223], off
	s_barrier
	s_waitcnt lgkmcnt(0)
	v_mfma_f32_16x16x32_bf16 v[118:121], v[206:209], v[162:165], v[118:121]
	v_mfma_f32_16x16x32_bf16 v[114:117], v[214:217], v[162:165], v[114:117]
	v_mfma_f32_16x16x32_bf16 v[102:105], v[206:209], v[170:173], v[102:105]
	v_mfma_f32_16x16x32_bf16 v[98:101], v[214:217], v[170:173], v[98:101]
	v_mfma_f32_16x16x32_bf16 v[86:89], v[206:209], v[178:181], v[86:89]
	v_mfma_f32_16x16x32_bf16 v[82:85], v[214:217], v[178:181], v[82:85]
	v_mfma_f32_16x16x32_bf16 v[70:73], v[206:209], v[186:189], v[70:73]
	v_mfma_f32_16x16x32_bf16 v[66:69], v[214:217], v[186:189], v[66:69]
	v_mfma_f32_16x16x32_bf16 v[118:121], v[210:213], v[166:169], v[118:121]
	v_mfma_f32_16x16x32_bf16 v[114:117], v[218:221], v[166:169], v[114:117]
	v_mfma_f32_16x16x32_bf16 v[102:105], v[210:213], v[174:177], v[102:105]
	v_mfma_f32_16x16x32_bf16 v[98:101], v[218:221], v[174:177], v[98:101]
	v_mfma_f32_16x16x32_bf16 v[86:89], v[210:213], v[182:185], v[86:89]
	v_mfma_f32_16x16x32_bf16 v[82:85], v[218:221], v[182:185], v[82:85]
	s_mov_b32 m0, s61
	v_mfma_f32_16x16x32_bf16 v[70:73], v[210:213], v[190:193], v[70:73]
	v_lshl_add_u64 v[222:223], v[226:227], 0, s[76:77]
	v_mfma_f32_16x16x32_bf16 v[66:69], v[218:221], v[190:193], v[66:69]
	s_barrier
	ds_read_b128 v[162:165], v146 offset:49152
	ds_read_b128 v[166:169], v146 offset:50176
	ds_read_b128 v[170:173], v146 offset:51200
	ds_read_b128 v[174:177], v146 offset:52224
	ds_read_b128 v[178:181], v146 offset:53248
	ds_read_b128 v[182:185], v146 offset:54272
	ds_read_b128 v[186:189], v146 offset:55296
	ds_read_b128 v[190:193], v146 offset:56320
	global_load_lds_dwordx4 v[222:223], off
	v_lshl_add_u64 v[222:223], v[228:229], 0, s[76:77]
	s_mov_b32 m0, s62
	s_nop 0
	global_load_lds_dwordx4 v[222:223], off
	s_barrier
	s_waitcnt lgkmcnt(0)
	v_mfma_f32_16x16x32_bf16 v[62:65], v[142:145], v[162:165], v[62:65]
	v_mfma_f32_16x16x32_bf16 v[58:61], v[154:157], v[162:165], v[58:61]
	v_mfma_f32_16x16x32_bf16 v[46:49], v[142:145], v[170:173], v[46:49]
	v_mfma_f32_16x16x32_bf16 v[42:45], v[154:157], v[170:173], v[42:45]
	v_mfma_f32_16x16x32_bf16 v[30:33], v[142:145], v[178:181], v[30:33]
	v_mfma_f32_16x16x32_bf16 v[26:29], v[154:157], v[178:181], v[26:29]
	v_mfma_f32_16x16x32_bf16 v[14:17], v[142:145], v[186:189], v[14:17]
	v_mfma_f32_16x16x32_bf16 v[10:13], v[154:157], v[186:189], v[10:13]
	v_mfma_f32_16x16x32_bf16 v[62:65], v[150:153], v[166:169], v[62:65]
	v_mfma_f32_16x16x32_bf16 v[58:61], v[158:161], v[166:169], v[58:61]
	v_mfma_f32_16x16x32_bf16 v[46:49], v[150:153], v[174:177], v[46:49]
	v_mfma_f32_16x16x32_bf16 v[42:45], v[158:161], v[174:177], v[42:45]
	v_mfma_f32_16x16x32_bf16 v[30:33], v[150:153], v[182:185], v[30:33]
	v_mfma_f32_16x16x32_bf16 v[26:29], v[158:161], v[182:185], v[26:29]
	v_mfma_f32_16x16x32_bf16 v[14:17], v[150:153], v[190:193], v[14:17]
	v_mfma_f32_16x16x32_bf16 v[10:13], v[158:161], v[190:193], v[10:13]
	s_barrier
	s_add_u32 s6, s54, 0x20080
	s_addc_u32 s7, s55, 0
	s_mov_b32 m0, s63
	s_nop 0
	global_load_lds_dwordx4 v134, s[6:7]
	s_mov_b32 m0, s67
	s_nop 0
	global_load_lds_dwordx4 v130, s[6:7]
	s_waitcnt vmcnt(6)
	s_barrier
	v_mfma_f32_16x16x32_bf16 v[54:57], v[206:209], v[162:165], v[54:57]
	v_mfma_f32_16x16x32_bf16 v[50:53], v[214:217], v[162:165], v[50:53]
	v_mfma_f32_16x16x32_bf16 v[38:41], v[206:209], v[170:173], v[38:41]
	v_mfma_f32_16x16x32_bf16 v[34:37], v[214:217], v[170:173], v[34:37]
	v_mfma_f32_16x16x32_bf16 v[22:25], v[206:209], v[178:181], v[22:25]
	v_mfma_f32_16x16x32_bf16 v[18:21], v[214:217], v[178:181], v[18:21]
	v_mfma_f32_16x16x32_bf16 v[6:9], v[206:209], v[186:189], v[6:9]
	v_mfma_f32_16x16x32_bf16 v[2:5], v[214:217], v[186:189], v[2:5]
	v_mfma_f32_16x16x32_bf16 v[54:57], v[210:213], v[166:169], v[54:57]
	v_mfma_f32_16x16x32_bf16 v[50:53], v[218:221], v[166:169], v[50:53]
	v_mfma_f32_16x16x32_bf16 v[38:41], v[210:213], v[174:177], v[38:41]
	v_mfma_f32_16x16x32_bf16 v[34:37], v[218:221], v[174:177], v[34:37]
	v_mfma_f32_16x16x32_bf16 v[22:25], v[210:213], v[182:185], v[22:25]
	v_mfma_f32_16x16x32_bf16 v[18:21], v[218:221], v[182:185], v[18:21]
	v_mfma_f32_16x16x32_bf16 v[6:9], v[210:213], v[190:193], v[6:9]
	v_mfma_f32_16x16x32_bf16 v[2:5], v[218:221], v[190:193], v[2:5]
	s_add_i32 s79, s79, 2
	s_cmp_gt_u32 s79, 5
	s_mov_b64 s[6:7], s[8:9]
	s_barrier
	s_cbranch_scc0 .LBB0_266
	s_lshl_b32 s5, s28, 6
	s_and_b32 s5, s5, 0xffffff00
	v_add_u32_e32 v144, s5, v148
	s_lshl_b32 s5, s28, 8
	s_and_b32 s5, s5, 0x300
	v_or_b32_e32 v145, s5, v149
	v_mov_b64_e32 v[142:143], s[50:51]
	v_mad_i64_i32 v[150:151], s[6:7], v144, s37, v[142:143]
	v_lshlrev_b32_e32 v194, 1, v145
	v_lshl_add_u64 v[154:155], v[150:151], 0, v[194:195]
	v_add_co_u32_e32 v150, vcc, 0x1000, v154
	v_or_b32_e32 v184, 16, v144
	s_nop 0
	v_addc_co_u32_e32 v151, vcc, 0, v155, vcc
	global_load_dwordx4 v[150:153], v[150:151], off offset:2048
	v_lshl_add_u64 v[154:155], v[154:155], 0, s[84:85]
	global_load_dwordx4 v[154:157], v[154:155], off offset:256
	v_pk_mul_f32 v[182:183], v[114:115], s[36:37] op_sel_hi:[1,0]
	v_mad_i64_i32 v[114:115], s[6:7], v184, s37, v[142:143]
	v_lshl_add_u64 v[114:115], v[114:115], 0, v[194:195]
	v_pk_mul_f32 v[180:181], v[116:117], s[36:37] op_sel_hi:[1,0]
	v_add_co_u32_e32 v116, vcc, 0x1000, v114
	v_pk_mul_f32 v[170:171], v[126:127], s[36:37] op_sel_hi:[1,0]
	s_nop 0
	v_addc_co_u32_e32 v117, vcc, 0, v115, vcc
	v_pk_mul_f32 v[172:173], v[124:125], s[36:37] op_sel_hi:[1,0]
	global_load_dwordx4 v[124:127], v[116:117], off offset:2048
	v_lshl_add_u64 v[114:115], v[114:115], 0, s[84:85]
	global_load_dwordx4 v[158:161], v[114:115], off offset:256
	v_or_b32_e32 v186, 32, v144
	v_mad_i64_i32 v[116:117], s[6:7], v186, s37, v[142:143]
	v_lshl_add_u64 v[116:117], v[116:117], 0, v[194:195]
	v_lshl_add_u64 v[166:167], v[116:117], 0, s[84:85]
	v_add_co_u32_e32 v116, vcc, 0x1000, v116
	v_pk_mul_f32 v[174:175], v[122:123], s[36:37] op_sel_hi:[1,0]
	s_nop 0
	v_addc_co_u32_e32 v117, vcc, 0, v117, vcc
	global_load_dwordx4 v[162:165], v[116:117], off offset:2048
	s_nop 0
	global_load_dwordx4 v[166:169], v[166:167], off offset:256
	v_or_b32_e32 v122, 48, v144
	v_pk_mul_f32 v[178:179], v[118:119], s[36:37] op_sel_hi:[1,0]
	v_mad_i64_i32 v[118:119], s[6:7], v122, s37, v[142:143]
	v_ashrrev_i32_e32 v145, 31, v144
	v_lshl_add_u64 v[118:119], v[118:119], 0, v[194:195]
	v_pk_mul_f32 v[176:177], v[120:121], s[36:37] op_sel_hi:[1,0]
	v_lshlrev_b64 v[120:121], 11, v[144:145]
	v_add_co_u32_e32 v114, vcc, 0x1000, v118
	v_lshl_add_u64 v[120:121], s[74:75], 0, v[120:121]
	s_nop 0
	v_addc_co_u32_e32 v115, vcc, 0, v119, vcc
	v_lshl_add_u64 v[188:189], v[118:119], 0, s[84:85]
	v_lshl_add_u64 v[190:191], v[120:121], 0, v[194:195]
	global_load_dwordx4 v[118:121], v[114:115], off offset:2048
	s_nop 0
	global_load_dwordx4 v[114:117], v[188:189], off offset:256
	v_pk_mul_f32 v[128:129], v[128:129], s[36:37] op_sel_hi:[1,0]
	v_pk_mul_f32 v[110:111], v[110:111], s[36:37] op_sel_hi:[1,0]
	v_pk_mul_f32 v[112:113], v[112:113], s[36:37] op_sel_hi:[1,0]
	v_ashrrev_i32_e32 v185, 31, v184
	v_pk_mul_f32 v[102:103], v[102:103], s[36:37] op_sel_hi:[1,0]
	v_pk_mul_f32 v[104:105], v[104:105], s[36:37] op_sel_hi:[1,0]
	v_pk_mul_f32 v[94:95], v[94:95], s[36:37] op_sel_hi:[1,0]
	v_pk_mul_f32 v[96:97], v[96:97], s[36:37] op_sel_hi:[1,0]
	v_ashrrev_i32_e32 v187, 31, v186
	v_pk_mul_f32 v[86:87], v[86:87], s[36:37] op_sel_hi:[1,0]
	v_pk_mul_f32 v[88:89], v[88:89], s[36:37] op_sel_hi:[1,0]
	v_pk_mul_f32 v[78:79], v[78:79], s[36:37] op_sel_hi:[1,0]
	v_pk_mul_f32 v[80:81], v[80:81], s[36:37] op_sel_hi:[1,0]
	v_ashrrev_i32_e32 v123, 31, v122
	v_pk_mul_f32 v[70:71], v[70:71], s[36:37] op_sel_hi:[1,0]
	v_pk_mul_f32 v[72:73], v[72:73], s[36:37] op_sel_hi:[1,0]
	s_waitcnt vmcnt(0)
	v_lshlrev_b32_e32 v145, 16, v150
	v_and_b32_e32 v150, 0xffff0000, v150
	v_lshlrev_b32_e32 v188, 16, v151
	v_and_b32_e32 v151, 0xffff0000, v151
	v_mul_f32_e32 v150, v171, v150
	v_mul_f32_e32 v128, v128, v188
	v_mul_f32_e32 v129, v129, v151
	v_lshlrev_b32_e32 v189, 16, v152
	v_and_b32_e32 v152, 0xffff0000, v152
	v_lshlrev_b32_e32 v192, 16, v153
	v_and_b32_e32 v153, 0xffff0000, v153
	v_mul_f32_e32 v145, v170, v145
	v_cvt_pk_bf16_f32 v150, v145, v150
	v_cvt_pk_bf16_f32 v151, v128, v129
	v_lshlrev_b32_e32 v128, 16, v154
	v_and_b32_e32 v129, 0xffff0000, v154
	v_mul_f32_e32 v152, v175, v152
	v_mul_f32_e32 v153, v173, v153
	v_mul_f32_e32 v128, v178, v128
	v_mul_f32_e32 v129, v179, v129
	v_mul_f32_e32 v170, v174, v189
	v_mul_f32_e32 v171, v172, v192
	v_cvt_pk_bf16_f32 v152, v170, v152
	v_cvt_pk_bf16_f32 v153, v171, v153
	global_store_dwordx4 v[190:191], v[150:153], off
	s_nop 1
	v_cvt_pk_bf16_f32 v150, v128, v129
	v_lshlrev_b32_e32 v128, 16, v155
	v_and_b32_e32 v129, 0xffff0000, v155
	v_mul_f32_e32 v128, v176, v128
	v_mul_f32_e32 v129, v177, v129
	v_cvt_pk_bf16_f32 v151, v128, v129
	v_lshlrev_b32_e32 v128, 16, v156
	v_and_b32_e32 v129, 0xffff0000, v156
	v_mul_f32_e32 v128, v182, v128
	v_mul_f32_e32 v129, v183, v129
	v_cvt_pk_bf16_f32 v152, v128, v129
	v_lshlrev_b32_e32 v128, 16, v157
	v_and_b32_e32 v129, 0xffff0000, v157
	v_mul_f32_e32 v128, v180, v128
	v_mul_f32_e32 v129, v181, v129
	v_cvt_pk_bf16_f32 v153, v128, v129
	global_store_dwordx4 v[190:191], v[150:153], off offset:256
	v_lshlrev_b64 v[128:129], 11, v[184:185]
	s_nop 0
	v_pk_mul_f32 v[150:151], v[108:109], s[36:37] op_sel_hi:[1,0]
	v_pk_mul_f32 v[108:109], v[106:107], s[36:37] op_sel_hi:[1,0]
	v_lshlrev_b32_e32 v106, 16, v124
	v_and_b32_e32 v107, 0xffff0000, v124
	v_mul_f32_e32 v106, v110, v106
	v_mul_f32_e32 v107, v111, v107
	v_cvt_pk_bf16_f32 v106, v106, v107
	v_lshlrev_b32_e32 v107, 16, v125
	v_and_b32_e32 v110, 0xffff0000, v125
	v_mul_f32_e32 v107, v112, v107
	v_mul_f32_e32 v110, v113, v110
	v_cvt_pk_bf16_f32 v107, v107, v110
	v_lshlrev_b32_e32 v110, 16, v126
	v_mul_f32_e32 v108, v108, v110
	v_and_b32_e32 v110, 0xffff0000, v126
	v_mul_f32_e32 v109, v109, v110
	v_cvt_pk_bf16_f32 v108, v108, v109
	v_lshlrev_b32_e32 v109, 16, v127
	v_and_b32_e32 v110, 0xffff0000, v127
	v_mul_f32_e32 v109, v150, v109
	v_mul_f32_e32 v110, v151, v110
	v_cvt_pk_bf16_f32 v109, v109, v110
	v_lshl_add_u64 v[110:111], s[74:75], 0, v[128:129]
	v_lshl_add_u64 v[110:111], v[110:111], 0, v[194:195]
	global_store_dwordx4 v[110:111], v[106:109], off
	s_nop 1
	v_pk_mul_f32 v[106:107], v[100:101], s[36:37] op_sel_hi:[1,0]
	v_pk_mul_f32 v[100:101], v[98:99], s[36:37] op_sel_hi:[1,0]
	v_lshlrev_b32_e32 v98, 16, v158
	v_and_b32_e32 v99, 0xffff0000, v158
	v_mul_f32_e32 v98, v102, v98
	v_mul_f32_e32 v99, v103, v99
	v_cvt_pk_bf16_f32 v98, v98, v99
	v_lshlrev_b32_e32 v99, 16, v159
	v_and_b32_e32 v102, 0xffff0000, v159
	v_mul_f32_e32 v99, v104, v99
	v_mul_f32_e32 v102, v105, v102
	v_cvt_pk_bf16_f32 v99, v99, v102
	v_lshlrev_b32_e32 v102, 16, v160
	v_mul_f32_e32 v100, v100, v102
	v_and_b32_e32 v102, 0xffff0000, v160
	v_mul_f32_e32 v101, v101, v102
	v_cvt_pk_bf16_f32 v100, v100, v101
	v_lshlrev_b32_e32 v101, 16, v161
	v_mul_f32_e32 v101, v106, v101
	v_and_b32_e32 v102, 0xffff0000, v161
	v_mul_f32_e32 v102, v107, v102
	v_cvt_pk_bf16_f32 v101, v101, v102
	global_store_dwordx4 v[110:111], v[98:101], off offset:256
	s_nop 1
	v_pk_mul_f32 v[100:101], v[92:93], s[36:37] op_sel_hi:[1,0]
	v_pk_mul_f32 v[92:93], v[90:91], s[36:37] op_sel_hi:[1,0]
	v_lshlrev_b32_e32 v90, 16, v162
	v_and_b32_e32 v91, 0xffff0000, v162
	v_mul_f32_e32 v90, v94, v90
	v_mul_f32_e32 v91, v95, v91
	v_cvt_pk_bf16_f32 v90, v90, v91
	v_lshlrev_b32_e32 v91, 16, v163
	v_and_b32_e32 v94, 0xffff0000, v163
	v_mul_f32_e32 v91, v96, v91
	v_mul_f32_e32 v94, v97, v94
	v_cvt_pk_bf16_f32 v91, v91, v94
	v_lshlrev_b32_e32 v94, 16, v164
	v_mul_f32_e32 v92, v92, v94
	v_and_b32_e32 v94, 0xffff0000, v164
	v_mul_f32_e32 v93, v93, v94
	v_cvt_pk_bf16_f32 v92, v92, v93
	v_lshlrev_b32_e32 v93, 16, v165
	v_and_b32_e32 v94, 0xffff0000, v165
	v_lshlrev_b64 v[98:99], 11, v[186:187]
	v_mul_f32_e32 v93, v100, v93
	v_mul_f32_e32 v94, v101, v94
	v_cvt_pk_bf16_f32 v93, v93, v94
	v_lshl_add_u64 v[94:95], s[74:75], 0, v[98:99]
	v_lshl_add_u64 v[94:95], v[94:95], 0, v[194:195]
	global_store_dwordx4 v[94:95], v[90:93], off
	s_nop 1
	v_pk_mul_f32 v[90:91], v[84:85], s[36:37] op_sel_hi:[1,0]
	v_pk_mul_f32 v[84:85], v[82:83], s[36:37] op_sel_hi:[1,0]
	v_lshlrev_b32_e32 v82, 16, v166
	v_and_b32_e32 v83, 0xffff0000, v166
	v_mul_f32_e32 v82, v86, v82
	v_mul_f32_e32 v83, v87, v83
	v_cvt_pk_bf16_f32 v82, v82, v83
	v_lshlrev_b32_e32 v83, 16, v167
	v_and_b32_e32 v86, 0xffff0000, v167
	v_mul_f32_e32 v83, v88, v83
	v_mul_f32_e32 v86, v89, v86
	v_cvt_pk_bf16_f32 v83, v83, v86
	v_lshlrev_b32_e32 v86, 16, v168
	v_mul_f32_e32 v84, v84, v86
	v_and_b32_e32 v86, 0xffff0000, v168
	v_mul_f32_e32 v85, v85, v86
	v_cvt_pk_bf16_f32 v84, v84, v85
	v_lshlrev_b32_e32 v85, 16, v169
	v_mul_f32_e32 v85, v90, v85
	v_and_b32_e32 v86, 0xffff0000, v169
	v_mul_f32_e32 v86, v91, v86
	v_cvt_pk_bf16_f32 v85, v85, v86
	global_store_dwordx4 v[94:95], v[82:85], off offset:256
	s_nop 1
	v_pk_mul_f32 v[84:85], v[76:77], s[36:37] op_sel_hi:[1,0]
	v_pk_mul_f32 v[76:77], v[74:75], s[36:37] op_sel_hi:[1,0]
	v_lshlrev_b32_e32 v74, 16, v118
	v_and_b32_e32 v75, 0xffff0000, v118
	v_mul_f32_e32 v74, v78, v74
	v_mul_f32_e32 v75, v79, v75
	v_cvt_pk_bf16_f32 v74, v74, v75
	v_lshlrev_b32_e32 v75, 16, v119
	v_and_b32_e32 v78, 0xffff0000, v119
	v_mul_f32_e32 v75, v80, v75
	v_mul_f32_e32 v78, v81, v78
	v_cvt_pk_bf16_f32 v75, v75, v78
	v_lshlrev_b32_e32 v78, 16, v120
	v_mul_f32_e32 v76, v76, v78
	v_and_b32_e32 v78, 0xffff0000, v120
	v_mul_f32_e32 v77, v77, v78
	v_cvt_pk_bf16_f32 v76, v76, v77
	v_lshlrev_b32_e32 v77, 16, v121
	v_and_b32_e32 v78, 0xffff0000, v121
	v_lshlrev_b64 v[82:83], 11, v[122:123]
	v_mul_f32_e32 v77, v84, v77
	v_mul_f32_e32 v78, v85, v78
	v_cvt_pk_bf16_f32 v77, v77, v78
	v_lshl_add_u64 v[78:79], s[74:75], 0, v[82:83]
	v_lshl_add_u64 v[78:79], v[78:79], 0, v[194:195]
	global_store_dwordx4 v[78:79], v[74:77], off
	s_nop 1
	v_pk_mul_f32 v[74:75], v[68:69], s[36:37] op_sel_hi:[1,0]
	v_pk_mul_f32 v[68:69], v[66:67], s[36:37] op_sel_hi:[1,0]
	v_lshlrev_b32_e32 v66, 16, v114
	v_and_b32_e32 v67, 0xffff0000, v114
	v_mul_f32_e32 v66, v70, v66
	v_mul_f32_e32 v67, v71, v67
	v_cvt_pk_bf16_f32 v66, v66, v67
	v_lshlrev_b32_e32 v67, 16, v115
	v_and_b32_e32 v70, 0xffff0000, v115
	v_mul_f32_e32 v67, v72, v67
	v_mul_f32_e32 v70, v73, v70
	v_cvt_pk_bf16_f32 v67, v67, v70
	v_lshlrev_b32_e32 v70, 16, v116
	v_mul_f32_e32 v68, v68, v70
	v_and_b32_e32 v70, 0xffff0000, v116
	v_mul_f32_e32 v69, v69, v70
	v_cvt_pk_bf16_f32 v68, v68, v69
	v_lshlrev_b32_e32 v69, 16, v117
	v_mul_f32_e32 v69, v74, v69
	v_and_b32_e32 v70, 0xffff0000, v117
	v_mul_f32_e32 v70, v75, v70
	v_cvt_pk_bf16_f32 v69, v69, v70
	global_store_dwordx4 v[78:79], v[66:69], off offset:256
	v_add_u32_e32 v78, 0x80, v144
	s_nop 0
	v_mad_i64_i32 v[66:67], s[6:7], v78, s37, v[142:143]
	v_lshl_add_u64 v[66:67], v[66:67], 0, v[194:195]
	v_add_co_u32_e32 v68, vcc, s16, v66
	v_add_u32_e32 v86, 0x90, v144
	s_nop 0
	v_addc_co_u32_e32 v69, vcc, 0, v67, vcc
	global_load_dwordx4 v[70:73], v[68:69], off offset:2048
	v_lshl_add_u64 v[66:67], v[66:67], 0, s[84:85]
	global_load_dwordx4 v[74:77], v[66:67], off offset:256
	v_pk_mul_f32 v[96:97], v[56:57], s[36:37] op_sel_hi:[1,0]
	v_mad_i64_i32 v[56:57], s[6:7], v86, s37, v[142:143]
	v_lshl_add_u64 v[56:57], v[56:57], 0, v[194:195]
	v_pk_mul_f32 v[94:95], v[58:59], s[36:37] op_sel_hi:[1,0]
	v_add_co_u32_e32 v58, vcc, s16, v56
	v_pk_mul_f32 v[92:93], v[60:61], s[36:37] op_sel_hi:[1,0]
	s_nop 0
	v_addc_co_u32_e32 v59, vcc, 0, v57, vcc
	global_load_dwordx4 v[58:61], v[58:59], off offset:2048
	v_add_u32_e32 v68, 0xa0, v144
	v_pk_mul_f32 v[102:103], v[50:51], s[36:37] op_sel_hi:[1,0]
	v_mad_i64_i32 v[50:51], s[6:7], v68, s37, v[142:143]
	v_add_u32_e32 v66, 0xb0, v144
	v_lshl_add_u64 v[50:51], v[50:51], 0, v[194:195]
	v_pk_mul_f32 v[100:101], v[52:53], s[36:37] op_sel_hi:[1,0]
	v_mad_i64_i32 v[52:53], s[6:7], v66, s37, v[142:143]
	v_lshl_add_u64 v[82:83], v[50:51], 0, s[84:85]
	v_add_co_u32_e32 v50, vcc, s16, v50
	v_lshl_add_u64 v[52:53], v[52:53], 0, v[194:195]
	s_nop 0
	v_addc_co_u32_e32 v51, vcc, 0, v51, vcc
	v_ashrrev_i32_e32 v79, 31, v78
	v_lshl_add_u64 v[104:105], v[52:53], 0, s[84:85]
	v_add_co_u32_e32 v52, vcc, s16, v52
	v_pk_mul_f32 v[98:99], v[54:55], s[36:37] op_sel_hi:[1,0]
	v_lshlrev_b64 v[54:55], 11, v[78:79]
	v_lshl_add_u64 v[56:57], v[56:57], 0, s[84:85]
	v_addc_co_u32_e32 v53, vcc, 0, v53, vcc
	v_pk_mul_f32 v[88:89], v[64:65], s[36:37] op_sel_hi:[1,0]
	v_pk_mul_f32 v[90:91], v[62:63], s[36:37] op_sel_hi:[1,0]
	v_lshl_add_u64 v[106:107], s[74:75], 0, v[54:55]
	global_load_dwordx4 v[62:65], v[56:57], off offset:256
	global_load_dwordx4 v[78:81], v[50:51], off offset:2048
	s_nop 0
	global_load_dwordx4 v[82:85], v[82:83], off offset:256
	s_nop 0
	global_load_dwordx4 v[54:57], v[52:53], off offset:2048
	s_nop 0
	global_load_dwordx4 v[50:53], v[104:105], off offset:256
	v_lshl_add_u64 v[104:105], v[106:107], 0, v[194:195]
	v_pk_mul_f32 v[46:47], v[46:47], s[36:37] op_sel_hi:[1,0]
	v_pk_mul_f32 v[48:49], v[48:49], s[36:37] op_sel_hi:[1,0]
	v_ashrrev_i32_e32 v87, 31, v86
	v_pk_mul_f32 v[38:39], v[38:39], s[36:37] op_sel_hi:[1,0]
	v_pk_mul_f32 v[40:41], v[40:41], s[36:37] op_sel_hi:[1,0]
	v_pk_mul_f32 v[30:31], v[30:31], s[36:37] op_sel_hi:[1,0]
	v_pk_mul_f32 v[32:33], v[32:33], s[36:37] op_sel_hi:[1,0]
	v_ashrrev_i32_e32 v69, 31, v68
	v_pk_mul_f32 v[22:23], v[22:23], s[36:37] op_sel_hi:[1,0]
	v_pk_mul_f32 v[24:25], v[24:25], s[36:37] op_sel_hi:[1,0]
	v_pk_mul_f32 v[14:15], v[14:15], s[36:37] op_sel_hi:[1,0]
	v_pk_mul_f32 v[16:17], v[16:17], s[36:37] op_sel_hi:[1,0]
	v_ashrrev_i32_e32 v67, 31, v66
	v_pk_mul_f32 v[6:7], v[6:7], s[36:37] op_sel_hi:[1,0]
	v_pk_mul_f32 v[8:9], v[8:9], s[36:37] op_sel_hi:[1,0]
	s_waitcnt vmcnt(0)
	v_lshlrev_b32_e32 v106, 16, v70
	v_and_b32_e32 v70, 0xffff0000, v70
	v_lshlrev_b32_e32 v107, 16, v71
	v_and_b32_e32 v71, 0xffff0000, v71
	v_lshlrev_b32_e32 v108, 16, v72
	v_and_b32_e32 v72, 0xffff0000, v72
	v_lshlrev_b32_e32 v109, 16, v73
	v_and_b32_e32 v73, 0xffff0000, v73
	v_mul_f32_e32 v70, v91, v70
	v_mul_f32_e32 v71, v89, v71
	v_mul_f32_e32 v72, v95, v72
	v_mul_f32_e32 v73, v93, v73
	v_mul_f32_e32 v90, v90, v106
	v_mul_f32_e32 v88, v88, v107
	v_mul_f32_e32 v89, v94, v108
	v_mul_f32_e32 v91, v92, v109
	v_cvt_pk_bf16_f32 v70, v90, v70
	v_cvt_pk_bf16_f32 v71, v88, v71
	v_cvt_pk_bf16_f32 v72, v89, v72
	v_cvt_pk_bf16_f32 v73, v91, v73
	v_lshlrev_b32_e32 v111, 16, v75
	v_and_b32_e32 v75, 0xffff0000, v75
	global_store_dwordx4 v[104:105], v[70:73], off
	v_lshlrev_b32_e32 v110, 16, v74
	v_and_b32_e32 v74, 0xffff0000, v74
	v_lshlrev_b32_e32 v72, 16, v76
	v_and_b32_e32 v73, 0xffff0000, v76
	v_mul_f32_e32 v71, v97, v75
	v_mul_f32_e32 v72, v102, v72
	v_mul_f32_e32 v73, v103, v73
	v_mul_f32_e32 v92, v98, v110
	v_mul_f32_e32 v74, v99, v74
	v_mul_f32_e32 v93, v96, v111
	v_cvt_pk_bf16_f32 v70, v92, v74
	v_cvt_pk_bf16_f32 v71, v93, v71
	v_cvt_pk_bf16_f32 v72, v72, v73
	v_lshlrev_b32_e32 v73, 16, v77
	v_mul_f32_e32 v73, v100, v73
	v_and_b32_e32 v74, 0xffff0000, v77
	v_mul_f32_e32 v74, v101, v74
	v_cvt_pk_bf16_f32 v73, v73, v74
	global_store_dwordx4 v[104:105], v[70:73], off offset:256
	s_nop 1
	v_pk_mul_f32 v[72:73], v[44:45], s[36:37] op_sel_hi:[1,0]
	v_pk_mul_f32 v[44:45], v[42:43], s[36:37] op_sel_hi:[1,0]
	v_lshlrev_b32_e32 v42, 16, v58
	v_and_b32_e32 v43, 0xffff0000, v58
	v_mul_f32_e32 v42, v46, v42
	v_mul_f32_e32 v43, v47, v43
	v_cvt_pk_bf16_f32 v42, v42, v43
	v_lshlrev_b32_e32 v43, 16, v59
	v_and_b32_e32 v46, 0xffff0000, v59
	v_mul_f32_e32 v43, v48, v43
	v_mul_f32_e32 v46, v49, v46
	v_cvt_pk_bf16_f32 v43, v43, v46
	v_lshlrev_b32_e32 v46, 16, v60
	v_mul_f32_e32 v44, v44, v46
	v_and_b32_e32 v46, 0xffff0000, v60
	v_mul_f32_e32 v45, v45, v46
	v_cvt_pk_bf16_f32 v44, v44, v45
	v_lshlrev_b32_e32 v45, 16, v61
	v_and_b32_e32 v46, 0xffff0000, v61
	v_lshlrev_b64 v[70:71], 11, v[86:87]
	v_mul_f32_e32 v45, v72, v45
	v_mul_f32_e32 v46, v73, v46
	v_cvt_pk_bf16_f32 v45, v45, v46
	v_lshl_add_u64 v[46:47], s[74:75], 0, v[70:71]
	v_lshl_add_u64 v[46:47], v[46:47], 0, v[194:195]
	global_store_dwordx4 v[46:47], v[42:45], off
	s_nop 1
	v_pk_mul_f32 v[42:43], v[36:37], s[36:37] op_sel_hi:[1,0]
	v_pk_mul_f32 v[36:37], v[34:35], s[36:37] op_sel_hi:[1,0]
	v_lshlrev_b32_e32 v34, 16, v62
	v_and_b32_e32 v35, 0xffff0000, v62
	v_mul_f32_e32 v34, v38, v34
	v_mul_f32_e32 v35, v39, v35
	v_cvt_pk_bf16_f32 v34, v34, v35
	v_lshlrev_b32_e32 v35, 16, v63
	v_and_b32_e32 v38, 0xffff0000, v63
	v_mul_f32_e32 v35, v40, v35
	v_mul_f32_e32 v38, v41, v38
	v_cvt_pk_bf16_f32 v35, v35, v38
	v_lshlrev_b32_e32 v38, 16, v64
	v_mul_f32_e32 v36, v36, v38
	v_and_b32_e32 v38, 0xffff0000, v64
	v_mul_f32_e32 v37, v37, v38
	v_cvt_pk_bf16_f32 v36, v36, v37
	v_lshlrev_b32_e32 v37, 16, v65
	v_mul_f32_e32 v37, v42, v37
	v_and_b32_e32 v38, 0xffff0000, v65
	v_mul_f32_e32 v38, v43, v38
	v_cvt_pk_bf16_f32 v37, v37, v38
	global_store_dwordx4 v[46:47], v[34:37], off offset:256
	s_nop 1
	v_pk_mul_f32 v[36:37], v[28:29], s[36:37] op_sel_hi:[1,0]
	v_pk_mul_f32 v[28:29], v[26:27], s[36:37] op_sel_hi:[1,0]
	v_lshlrev_b32_e32 v26, 16, v78
	v_and_b32_e32 v27, 0xffff0000, v78
	v_mul_f32_e32 v26, v30, v26
	v_mul_f32_e32 v27, v31, v27
	v_cvt_pk_bf16_f32 v26, v26, v27
	v_lshlrev_b32_e32 v27, 16, v79
	v_and_b32_e32 v30, 0xffff0000, v79
	v_mul_f32_e32 v27, v32, v27
	v_mul_f32_e32 v30, v33, v30
	v_cvt_pk_bf16_f32 v27, v27, v30
	v_lshlrev_b32_e32 v30, 16, v80
	v_mul_f32_e32 v28, v28, v30
	v_and_b32_e32 v30, 0xffff0000, v80
	v_mul_f32_e32 v29, v29, v30
	v_cvt_pk_bf16_f32 v28, v28, v29
	v_lshlrev_b32_e32 v29, 16, v81
	v_and_b32_e32 v30, 0xffff0000, v81
	v_lshlrev_b64 v[34:35], 11, v[68:69]
	v_mul_f32_e32 v29, v36, v29
	v_mul_f32_e32 v30, v37, v30
	v_cvt_pk_bf16_f32 v29, v29, v30
	v_lshl_add_u64 v[30:31], s[74:75], 0, v[34:35]
	v_lshl_add_u64 v[30:31], v[30:31], 0, v[194:195]
	global_store_dwordx4 v[30:31], v[26:29], off
	s_nop 1
	v_pk_mul_f32 v[26:27], v[20:21], s[36:37] op_sel_hi:[1,0]
	v_pk_mul_f32 v[20:21], v[18:19], s[36:37] op_sel_hi:[1,0]
	v_lshlrev_b32_e32 v18, 16, v82
	v_and_b32_e32 v19, 0xffff0000, v82
	v_mul_f32_e32 v18, v22, v18
	v_mul_f32_e32 v19, v23, v19
	v_cvt_pk_bf16_f32 v18, v18, v19
	v_lshlrev_b32_e32 v19, 16, v83
	v_and_b32_e32 v22, 0xffff0000, v83
	v_mul_f32_e32 v19, v24, v19
	v_mul_f32_e32 v22, v25, v22
	v_cvt_pk_bf16_f32 v19, v19, v22
	v_lshlrev_b32_e32 v22, 16, v84
	v_mul_f32_e32 v20, v20, v22
	v_and_b32_e32 v22, 0xffff0000, v84
	v_mul_f32_e32 v21, v21, v22
	v_cvt_pk_bf16_f32 v20, v20, v21
	v_lshlrev_b32_e32 v21, 16, v85
	v_mul_f32_e32 v21, v26, v21
	v_and_b32_e32 v22, 0xffff0000, v85
	v_mul_f32_e32 v22, v27, v22
	v_cvt_pk_bf16_f32 v21, v21, v22
	global_store_dwordx4 v[30:31], v[18:21], off offset:256
	s_nop 1
	v_pk_mul_f32 v[20:21], v[12:13], s[36:37] op_sel_hi:[1,0]
	v_pk_mul_f32 v[12:13], v[10:11], s[36:37] op_sel_hi:[1,0]
	v_lshlrev_b32_e32 v10, 16, v54
	v_and_b32_e32 v11, 0xffff0000, v54
	v_mul_f32_e32 v10, v14, v10
	v_mul_f32_e32 v11, v15, v11
	v_cvt_pk_bf16_f32 v10, v10, v11
	v_lshlrev_b32_e32 v11, 16, v55
	v_and_b32_e32 v14, 0xffff0000, v55
	v_mul_f32_e32 v11, v16, v11
	v_mul_f32_e32 v14, v17, v14
	v_cvt_pk_bf16_f32 v11, v11, v14
	v_lshlrev_b32_e32 v14, 16, v56
	v_mul_f32_e32 v12, v12, v14
	v_and_b32_e32 v14, 0xffff0000, v56
	v_mul_f32_e32 v13, v13, v14
	v_cvt_pk_bf16_f32 v12, v12, v13
	v_lshlrev_b32_e32 v13, 16, v57
	v_and_b32_e32 v14, 0xffff0000, v57
	v_lshlrev_b64 v[18:19], 11, v[66:67]
	v_mul_f32_e32 v13, v20, v13
	v_mul_f32_e32 v14, v21, v14
	v_cvt_pk_bf16_f32 v13, v13, v14
	v_lshl_add_u64 v[14:15], s[74:75], 0, v[18:19]
	v_lshl_add_u64 v[14:15], v[14:15], 0, v[194:195]
	global_store_dwordx4 v[14:15], v[10:13], off
	s_nop 1
	v_pk_mul_f32 v[10:11], v[4:5], s[36:37] op_sel_hi:[1,0]
	v_pk_mul_f32 v[4:5], v[2:3], s[36:37] op_sel_hi:[1,0]
	v_lshlrev_b32_e32 v2, 16, v50
	v_and_b32_e32 v3, 0xffff0000, v50
	v_mul_f32_e32 v2, v6, v2
	v_mul_f32_e32 v3, v7, v3
	v_cvt_pk_bf16_f32 v2, v2, v3
	v_lshlrev_b32_e32 v3, 16, v51
	v_and_b32_e32 v6, 0xffff0000, v51
	v_mul_f32_e32 v3, v8, v3
	v_mul_f32_e32 v6, v9, v6
	v_cvt_pk_bf16_f32 v3, v3, v6
	v_lshlrev_b32_e32 v6, 16, v52
	v_mul_f32_e32 v4, v4, v6
	v_and_b32_e32 v6, 0xffff0000, v52
	v_mul_f32_e32 v5, v5, v6
	v_cvt_pk_bf16_f32 v4, v4, v5
	v_lshlrev_b32_e32 v5, 16, v53
	v_mul_f32_e32 v5, v10, v5
	v_and_b32_e32 v6, 0xffff0000, v53
	v_mul_f32_e32 v6, v11, v6
	v_cvt_pk_bf16_f32 v5, v5, v6
	global_store_dwordx4 v[14:15], v[2:5], off offset:256
	s_and_b64 vcc, exec, s[52:53]
	s_mov_b32 s28, s4
	s_cbranch_vccz .LBB0_265
	s_waitcnt vmcnt(0)
	v_readlane_b32 s28, v250, 12
	s_cmpk_gt_u32 s12, 0xff
	v_readlane_b32 s29, v250, 13
	s_mov_b32 s70, 0x800000
	s_cbranch_scc1 .LBB0_270
	s_barrier

.LBB0_368:
	v_add_u32_e32 v253, 0x10000, v201
	ds_read_b128 v[130:133], v253
	ds_read_b128 v[134:137], v253 offset:1024
	ds_read_b128 v[138:141], v253 offset:2048
	ds_read_b128 v[142:145], v253 offset:3072
	s_add_u32 s10, s8, 0xfffc0080
	s_addc_u32 s11, s9, -1
	s_cmp_eq_u32 s29, 12
	s_cselect_b32 s11, s81, s11
	s_cselect_b32 s10, s80, s10
	s_cselect_b32 s53, s83, s28
	s_cselect_b32 s52, s82, s7
	s_add_i32 m0, s34, 0xc000
	ds_read_b128 v[146:149], v199
	ds_read_b128 v[150:153], v199 offset:1024
	ds_read_b128 v[154:157], v199 offset:2048
	ds_read_b128 v[158:161], v199 offset:3072
	ds_read_b128 v[162:165], v199 offset:4096
	ds_read_b128 v[166:169], v199 offset:5120
	ds_read_b128 v[170:173], v199 offset:6144
	ds_read_b128 v[174:177], v199 offset:7168
	global_load_lds_dwordx4 v212, s[8:9]
	s_add_i32 m0, s34, 0xe000
	s_nop 0
	global_load_lds_dwordx4 v214, s[8:9]
	s_waitcnt lgkmcnt(8)
	s_barrier
	s_waitcnt lgkmcnt(0)
	v_mfma_f32_16x16x32_bf16 v[126:129], v[130:133], v[146:149], v[126:129]
	v_mfma_f32_16x16x32_bf16 v[122:125], v[138:141], v[146:149], v[122:125]
	v_mfma_f32_16x16x32_bf16 v[118:121], v[130:133], v[154:157], v[118:121]
	v_mfma_f32_16x16x32_bf16 v[114:117], v[138:141], v[154:157], v[114:117]
	v_mfma_f32_16x16x32_bf16 v[110:113], v[130:133], v[162:165], v[110:113]
	v_mfma_f32_16x16x32_bf16 v[106:109], v[138:141], v[162:165], v[106:109]
	v_mfma_f32_16x16x32_bf16 v[102:105], v[130:133], v[170:173], v[102:105]
	v_mfma_f32_16x16x32_bf16 v[98:101], v[138:141], v[170:173], v[98:101]
	v_mfma_f32_16x16x32_bf16 v[126:129], v[134:137], v[150:153], v[126:129]
	v_mfma_f32_16x16x32_bf16 v[122:125], v[142:145], v[150:153], v[122:125]
	v_mfma_f32_16x16x32_bf16 v[118:121], v[134:137], v[158:161], v[118:121]
	v_mfma_f32_16x16x32_bf16 v[114:117], v[142:145], v[158:161], v[114:117]
	v_mfma_f32_16x16x32_bf16 v[110:113], v[134:137], v[166:169], v[110:113]
	v_mfma_f32_16x16x32_bf16 v[106:109], v[142:145], v[166:169], v[106:109]
	v_mfma_f32_16x16x32_bf16 v[102:105], v[134:137], v[174:177], v[102:105]
	v_mfma_f32_16x16x32_bf16 v[98:101], v[142:145], v[174:177], v[98:101]
	s_barrier
	s_mov_b32 m0, s35
	ds_read_b128 v[178:181], v253 offset:16384
	ds_read_b128 v[182:185], v253 offset:17408
	ds_read_b128 v[186:189], v253 offset:18432
	ds_read_b128 v[190:193], v253 offset:19456
	global_load_lds_dwordx4 v194, s[52:53]
	s_mov_b32 m0, s42
	s_nop 0
	global_load_lds_dwordx4 v210, s[52:53]
	s_barrier
	s_waitcnt lgkmcnt(0)
	v_mfma_f32_16x16x32_bf16 v[94:97], v[178:181], v[146:149], v[94:97]
	v_mfma_f32_16x16x32_bf16 v[90:93], v[186:189], v[146:149], v[90:93]
	v_mfma_f32_16x16x32_bf16 v[86:89], v[178:181], v[154:157], v[86:89]
	v_mfma_f32_16x16x32_bf16 v[82:85], v[186:189], v[154:157], v[82:85]
	v_mfma_f32_16x16x32_bf16 v[78:81], v[178:181], v[162:165], v[78:81]
	v_mfma_f32_16x16x32_bf16 v[74:77], v[186:189], v[162:165], v[74:77]
	v_mfma_f32_16x16x32_bf16 v[70:73], v[178:181], v[170:173], v[70:73]
	v_mfma_f32_16x16x32_bf16 v[66:69], v[186:189], v[170:173], v[66:69]
	v_mfma_f32_16x16x32_bf16 v[94:97], v[182:185], v[150:153], v[94:97]
	v_mfma_f32_16x16x32_bf16 v[90:93], v[190:193], v[150:153], v[90:93]
	v_mfma_f32_16x16x32_bf16 v[86:89], v[182:185], v[158:161], v[86:89]
	v_mfma_f32_16x16x32_bf16 v[82:85], v[190:193], v[158:161], v[82:85]
	v_mfma_f32_16x16x32_bf16 v[78:81], v[182:185], v[166:169], v[78:81]
	v_mfma_f32_16x16x32_bf16 v[74:77], v[190:193], v[166:169], v[74:77]
	v_mfma_f32_16x16x32_bf16 v[70:73], v[182:185], v[174:177], v[70:73]
	s_mov_b32 m0, s34
	v_mfma_f32_16x16x32_bf16 v[66:69], v[190:193], v[174:177], v[66:69]
	s_barrier
	ds_read_b128 v[146:149], v199 offset:16384
	ds_read_b128 v[150:153], v199 offset:17408
	ds_read_b128 v[154:157], v199 offset:18432
	ds_read_b128 v[158:161], v199 offset:19456
	ds_read_b128 v[162:165], v199 offset:20480
	ds_read_b128 v[166:169], v199 offset:21504
	ds_read_b128 v[170:173], v199 offset:22528
	ds_read_b128 v[174:177], v199 offset:23552
	global_load_lds_dwordx4 v206, s[10:11]
	s_mov_b32 m0, s56
	s_nop 0
	global_load_lds_dwordx4 v208, s[10:11]
	s_barrier
	s_waitcnt lgkmcnt(0)
	v_mfma_f32_16x16x32_bf16 v[62:65], v[130:133], v[146:149], v[62:65]
	v_mfma_f32_16x16x32_bf16 v[58:61], v[138:141], v[146:149], v[58:61]
	v_mfma_f32_16x16x32_bf16 v[54:57], v[130:133], v[154:157], v[54:57]
	v_mfma_f32_16x16x32_bf16 v[50:53], v[138:141], v[154:157], v[50:53]
	v_mfma_f32_16x16x32_bf16 v[46:49], v[130:133], v[162:165], v[46:49]
	v_mfma_f32_16x16x32_bf16 v[42:45], v[138:141], v[162:165], v[42:45]
	v_mfma_f32_16x16x32_bf16 v[38:41], v[130:133], v[170:173], v[38:41]
	v_mfma_f32_16x16x32_bf16 v[34:37], v[138:141], v[170:173], v[34:37]
	v_mfma_f32_16x16x32_bf16 v[62:65], v[134:137], v[150:153], v[62:65]
	v_mfma_f32_16x16x32_bf16 v[58:61], v[142:145], v[150:153], v[58:61]
	v_mfma_f32_16x16x32_bf16 v[54:57], v[134:137], v[158:161], v[54:57]
	v_mfma_f32_16x16x32_bf16 v[50:53], v[142:145], v[158:161], v[50:53]
	v_mfma_f32_16x16x32_bf16 v[46:49], v[134:137], v[166:169], v[46:49]
	v_mfma_f32_16x16x32_bf16 v[42:45], v[142:145], v[166:169], v[42:45]
	v_mfma_f32_16x16x32_bf16 v[38:41], v[134:137], v[174:177], v[38:41]
	v_mfma_f32_16x16x32_bf16 v[34:37], v[142:145], v[174:177], v[34:37]
	s_barrier
	s_add_u32 s86, s52, 0x40000
	s_addc_u32 s87, s53, 0
	s_mov_b32 m0, s57
	s_nop 0
	global_load_lds_dwordx4 v194, s[86:87]
	s_mov_b32 m0, s67
	s_nop 0
	global_load_lds_dwordx4 v210, s[86:87]
	s_waitcnt vmcnt(6)
	s_barrier
	v_mfma_f32_16x16x32_bf16 v[30:33], v[178:181], v[146:149], v[30:33]
	v_mfma_f32_16x16x32_bf16 v[26:29], v[186:189], v[146:149], v[26:29]
	v_mfma_f32_16x16x32_bf16 v[22:25], v[178:181], v[154:157], v[22:25]
	v_mfma_f32_16x16x32_bf16 v[18:21], v[186:189], v[154:157], v[18:21]
	v_mfma_f32_16x16x32_bf16 v[14:17], v[178:181], v[162:165], v[14:17]
	v_mfma_f32_16x16x32_bf16 v[10:13], v[186:189], v[162:165], v[10:13]
	v_mfma_f32_16x16x32_bf16 v[6:9], v[178:181], v[170:173], v[6:9]
	v_mfma_f32_16x16x32_bf16 v[2:5], v[186:189], v[170:173], v[2:5]
	v_mfma_f32_16x16x32_bf16 v[30:33], v[182:185], v[150:153], v[30:33]
	v_mfma_f32_16x16x32_bf16 v[26:29], v[190:193], v[150:153], v[26:29]
	v_mfma_f32_16x16x32_bf16 v[22:25], v[182:185], v[158:161], v[22:25]
	v_mfma_f32_16x16x32_bf16 v[18:21], v[190:193], v[158:161], v[18:21]
	v_mfma_f32_16x16x32_bf16 v[14:17], v[182:185], v[166:169], v[14:17]
	v_mfma_f32_16x16x32_bf16 v[10:13], v[190:193], v[166:169], v[10:13]
	v_mfma_f32_16x16x32_bf16 v[6:9], v[182:185], v[174:177], v[6:9]
	v_mfma_f32_16x16x32_bf16 v[2:5], v[190:193], v[174:177], v[2:5]
	s_barrier
	ds_read_b128 v[130:133], v253 offset:32768
	ds_read_b128 v[134:137], v253 offset:33792
	ds_read_b128 v[138:141], v253 offset:34816
	ds_read_b128 v[142:145], v253 offset:35840
	s_add_u32 s10, s10, 0x40000
	s_addc_u32 s11, s11, 0
	s_mov_b32 m0, s70
	ds_read_b128 v[146:149], v199 offset:32768
	ds_read_b128 v[150:153], v199 offset:33792
	ds_read_b128 v[154:157], v199 offset:34816
	ds_read_b128 v[158:161], v199 offset:35840
	ds_read_b128 v[162:165], v199 offset:36864
	ds_read_b128 v[166:169], v199 offset:37888
	ds_read_b128 v[170:173], v199 offset:38912
	ds_read_b128 v[174:177], v199 offset:39936
	global_load_lds_dwordx4 v206, s[10:11]
	s_mov_b32 m0, s71
	s_nop 0
	global_load_lds_dwordx4 v208, s[10:11]
	s_waitcnt lgkmcnt(8)
	s_barrier
	s_waitcnt lgkmcnt(0)
	v_mfma_f32_16x16x32_bf16 v[126:129], v[130:133], v[146:149], v[126:129]
	v_mfma_f32_16x16x32_bf16 v[122:125], v[138:141], v[146:149], v[122:125]
	v_mfma_f32_16x16x32_bf16 v[118:121], v[130:133], v[154:157], v[118:121]
	v_mfma_f32_16x16x32_bf16 v[114:117], v[138:141], v[154:157], v[114:117]
	v_mfma_f32_16x16x32_bf16 v[110:113], v[130:133], v[162:165], v[110:113]
	v_mfma_f32_16x16x32_bf16 v[106:109], v[138:141], v[162:165], v[106:109]
	v_mfma_f32_16x16x32_bf16 v[102:105], v[130:133], v[170:173], v[102:105]
	v_mfma_f32_16x16x32_bf16 v[98:101], v[138:141], v[170:173], v[98:101]
	v_mfma_f32_16x16x32_bf16 v[126:129], v[134:137], v[150:153], v[126:129]
	v_mfma_f32_16x16x32_bf16 v[122:125], v[142:145], v[150:153], v[122:125]
	v_mfma_f32_16x16x32_bf16 v[118:121], v[134:137], v[158:161], v[118:121]
	v_mfma_f32_16x16x32_bf16 v[114:117], v[142:145], v[158:161], v[114:117]
	v_mfma_f32_16x16x32_bf16 v[110:113], v[134:137], v[166:169], v[110:113]
	v_mfma_f32_16x16x32_bf16 v[106:109], v[142:145], v[166:169], v[106:109]
	v_mfma_f32_16x16x32_bf16 v[102:105], v[134:137], v[174:177], v[102:105]
	v_mfma_f32_16x16x32_bf16 v[98:101], v[142:145], v[174:177], v[98:101]
	s_barrier
	s_mov_b32 m0, s78
	ds_read_b128 v[178:181], v253 offset:49152
	ds_read_b128 v[182:185], v253 offset:50176
	ds_read_b128 v[186:189], v253 offset:51200
	ds_read_b128 v[190:193], v253 offset:52224
	s_add_u32 s98, s52, 0x80
	s_addc_u32 s99, s53, 0
	global_load_lds_dwordx4 v194, s[98:99]
	s_mov_b32 m0, s79
	s_nop 0
	global_load_lds_dwordx4 v210, s[98:99]
	s_barrier
	s_waitcnt lgkmcnt(0)
	v_mfma_f32_16x16x32_bf16 v[94:97], v[178:181], v[146:149], v[94:97]
	v_mfma_f32_16x16x32_bf16 v[90:93], v[186:189], v[146:149], v[90:93]
	v_mfma_f32_16x16x32_bf16 v[86:89], v[178:181], v[154:157], v[86:89]
	v_mfma_f32_16x16x32_bf16 v[82:85], v[186:189], v[154:157], v[82:85]
	v_mfma_f32_16x16x32_bf16 v[78:81], v[178:181], v[162:165], v[78:81]
	v_mfma_f32_16x16x32_bf16 v[74:77], v[186:189], v[162:165], v[74:77]
	v_mfma_f32_16x16x32_bf16 v[70:73], v[178:181], v[170:173], v[70:73]
	v_mfma_f32_16x16x32_bf16 v[66:69], v[186:189], v[170:173], v[66:69]
	v_mfma_f32_16x16x32_bf16 v[94:97], v[182:185], v[150:153], v[94:97]
	v_mfma_f32_16x16x32_bf16 v[90:93], v[190:193], v[150:153], v[90:93]
	v_mfma_f32_16x16x32_bf16 v[86:89], v[182:185], v[158:161], v[86:89]
	v_mfma_f32_16x16x32_bf16 v[82:85], v[190:193], v[158:161], v[82:85]
	v_mfma_f32_16x16x32_bf16 v[78:81], v[182:185], v[166:169], v[78:81]
	v_mfma_f32_16x16x32_bf16 v[74:77], v[190:193], v[166:169], v[74:77]
	v_mfma_f32_16x16x32_bf16 v[70:73], v[182:185], v[174:177], v[70:73]
	s_mov_b32 m0, s26
	v_mfma_f32_16x16x32_bf16 v[66:69], v[190:193], v[174:177], v[66:69]
	s_barrier
	ds_read_b128 v[146:149], v199 offset:49152
	ds_read_b128 v[150:153], v199 offset:50176
	ds_read_b128 v[154:157], v199 offset:51200
	ds_read_b128 v[158:161], v199 offset:52224
	ds_read_b128 v[162:165], v199 offset:53248
	ds_read_b128 v[166:169], v199 offset:54272
	ds_read_b128 v[170:173], v199 offset:55296
	ds_read_b128 v[174:177], v199 offset:56320
	s_add_u32 s100, s10, 0xfffc0080
	s_addc_u32 s101, s11, -1
	global_load_lds_dwordx4 v206, s[100:101]
	s_mov_b32 m0, s4
	s_nop 0
	global_load_lds_dwordx4 v208, s[100:101]
	s_barrier
	s_waitcnt lgkmcnt(0)
	v_mfma_f32_16x16x32_bf16 v[62:65], v[130:133], v[146:149], v[62:65]
	v_mfma_f32_16x16x32_bf16 v[58:61], v[138:141], v[146:149], v[58:61]
	v_mfma_f32_16x16x32_bf16 v[54:57], v[130:133], v[154:157], v[54:57]
	v_mfma_f32_16x16x32_bf16 v[50:53], v[138:141], v[154:157], v[50:53]
	v_mfma_f32_16x16x32_bf16 v[46:49], v[130:133], v[162:165], v[46:49]
	v_mfma_f32_16x16x32_bf16 v[42:45], v[138:141], v[162:165], v[42:45]
	v_mfma_f32_16x16x32_bf16 v[38:41], v[130:133], v[170:173], v[38:41]
	v_mfma_f32_16x16x32_bf16 v[34:37], v[138:141], v[170:173], v[34:37]
	v_mfma_f32_16x16x32_bf16 v[62:65], v[134:137], v[150:153], v[62:65]
	v_mfma_f32_16x16x32_bf16 v[58:61], v[142:145], v[150:153], v[58:61]
	v_mfma_f32_16x16x32_bf16 v[54:57], v[134:137], v[158:161], v[54:57]
	v_mfma_f32_16x16x32_bf16 v[50:53], v[142:145], v[158:161], v[50:53]
	v_mfma_f32_16x16x32_bf16 v[46:49], v[134:137], v[166:169], v[46:49]
	v_mfma_f32_16x16x32_bf16 v[42:45], v[142:145], v[166:169], v[42:45]
	v_mfma_f32_16x16x32_bf16 v[38:41], v[134:137], v[174:177], v[38:41]
	v_mfma_f32_16x16x32_bf16 v[34:37], v[142:145], v[174:177], v[34:37]
	s_barrier
	s_add_u32 s10, s52, 0x40080
	s_addc_u32 s11, s53, 0
	s_mov_b32 m0, s5
	s_nop 0
	global_load_lds_dwordx4 v194, s[10:11]
	s_mov_b32 m0, s58
	s_nop 0
	global_load_lds_dwordx4 v210, s[10:11]
	s_waitcnt vmcnt(6)
	s_barrier
	v_mfma_f32_16x16x32_bf16 v[30:33], v[178:181], v[146:149], v[30:33]
	v_mfma_f32_16x16x32_bf16 v[26:29], v[186:189], v[146:149], v[26:29]
	v_mfma_f32_16x16x32_bf16 v[22:25], v[178:181], v[154:157], v[22:25]
	v_mfma_f32_16x16x32_bf16 v[18:21], v[186:189], v[154:157], v[18:21]
	v_mfma_f32_16x16x32_bf16 v[14:17], v[178:181], v[162:165], v[14:17]
	v_mfma_f32_16x16x32_bf16 v[10:13], v[186:189], v[162:165], v[10:13]
	v_mfma_f32_16x16x32_bf16 v[6:9], v[178:181], v[170:173], v[6:9]
	v_mfma_f32_16x16x32_bf16 v[2:5], v[186:189], v[170:173], v[2:5]
	v_mfma_f32_16x16x32_bf16 v[30:33], v[182:185], v[150:153], v[30:33]
	v_mfma_f32_16x16x32_bf16 v[26:29], v[190:193], v[150:153], v[26:29]
	v_mfma_f32_16x16x32_bf16 v[22:25], v[182:185], v[158:161], v[22:25]
	v_mfma_f32_16x16x32_bf16 v[18:21], v[190:193], v[158:161], v[18:21]
	v_mfma_f32_16x16x32_bf16 v[14:17], v[182:185], v[166:169], v[14:17]
	v_mfma_f32_16x16x32_bf16 v[10:13], v[190:193], v[166:169], v[10:13]
	v_mfma_f32_16x16x32_bf16 v[6:9], v[182:185], v[174:177], v[6:9]
	v_mfma_f32_16x16x32_bf16 v[2:5], v[190:193], v[174:177], v[2:5]
	s_add_i32 s29, s29, 2
	s_add_u32 s8, s8, 0x100
	s_addc_u32 s9, s9, 0
	s_add_u32 s7, s7, 0x100
	s_addc_u32 s28, s28, 0
	s_cmp_gt_u32 s29, 13
	s_barrier
	s_cbranch_scc0 .LBB0_368
	s_cmp_gt_i32 s95, 1
	s_cselect_b64 s[52:53], -1, 0
	s_mul_i32 s7, s6, 0x680000
	s_lshl_b32 s8, s95, 12
	s_lshl_b32 s9, s54, 9
	s_add_i32 s7, s7, s8
	s_add_i32 s7, s7, s9
	s_add_i32 s7, s7, 0x3800
	s_add_u32 s20, s50, s7
	s_addc_u32 s21, s51, 0
	s_lshl_b32 s7, s6, 20
	s_add_i32 s7, s7, s9
	s_add_u32 s10, s96, s7
	s_addc_u32 s11, s97, 0
	s_mov_b32 s86, 0xbfb8aa3b
	s_mov_b32 s87, 0xbfb8aa3b
	v_mul_u32_u24_e32 v253, 0x6800, v197
	v_lshlrev_b32_e32 v255, 12, v197
	v_lshl_add_u32 v253, v203, 1, v253
	v_lshl_add_u32 v255, v203, 1, v255
	v_add_u32_e32 v254, 0x1000, v253
	s_cmp_eq_u32 s95, 2
	s_cbranch_scc1 .Lem_br2
	global_load_dwordx4 v[130:133], v253, s[20:21]
	global_load_dwordx4 v[134:137], v254, s[20:21]
	global_load_dwordx4 v[138:141], v253, s[20:21] offset:256
	global_load_dwordx4 v[142:145], v254, s[20:21] offset:256
	s_add_u32 s28, s20, 0x68000
	s_addc_u32 s29, s21, 0
	global_load_dwordx4 v[146:149], v253, s[28:29]
	global_load_dwordx4 v[150:153], v254, s[28:29]
	global_load_dwordx4 v[154:157], v253, s[28:29] offset:256
	global_load_dwordx4 v[158:161], v254, s[28:29] offset:256
	s_add_u32 s28, s20, 0xd0000
	s_addc_u32 s29, s21, 0
	global_load_dwordx4 v[162:165], v253, s[28:29]
	global_load_dwordx4 v[166:169], v254, s[28:29]
	global_load_dwordx4 v[170:173], v253, s[28:29] offset:256
	global_load_dwordx4 v[174:177], v254, s[28:29] offset:256
	s_add_u32 s28, s20, 0x138000
	s_addc_u32 s29, s21, 0
	global_load_dwordx4 v[178:181], v253, s[28:29]
	global_load_dwordx4 v[182:185], v254, s[28:29]
	global_load_dwordx4 v[186:189], v253, s[28:29] offset:256
	global_load_dwordx4 v[190:193], v254, s[28:29] offset:256
	s_waitcnt vmcnt(12)
	v_lshlrev_b32_e32 v216, 16, v130
	v_and_b32_e32 v217, 0xffff0000, v130
	v_lshlrev_b32_e32 v218, 16, v131
	v_and_b32_e32 v219, 0xffff0000, v131
	v_lshlrev_b32_e32 v220, 16, v132
	v_and_b32_e32 v221, 0xffff0000, v132
	v_lshlrev_b32_e32 v222, 16, v133
	v_and_b32_e32 v223, 0xffff0000, v133
	v_pk_mul_f32 v[216:217], v[216:217], s[86:87] op_sel_hi:[1,0]
	v_pk_mul_f32 v[218:219], v[218:219], s[86:87] op_sel_hi:[1,0]
	v_pk_mul_f32 v[220:221], v[220:221], s[86:87] op_sel_hi:[1,0]
	v_pk_mul_f32 v[222:223], v[222:223], s[86:87] op_sel_hi:[1,0]
	v_exp_f32_e32 v216, v216
	v_exp_f32_e32 v217, v217
	v_exp_f32_e32 v218, v218
	v_exp_f32_e32 v219, v219
	v_exp_f32_e32 v220, v220
	v_exp_f32_e32 v221, v221
	v_exp_f32_e32 v222, v222
	v_exp_f32_e32 v223, v223
	v_pk_add_f32 v[216:217], v[216:217], 1.0 op_sel_hi:[1,0]
	v_pk_add_f32 v[218:219], v[218:219], 1.0 op_sel_hi:[1,0]
	v_pk_add_f32 v[220:221], v[220:221], 1.0 op_sel_hi:[1,0]
	v_pk_add_f32 v[222:223], v[222:223], 1.0 op_sel_hi:[1,0]
	v_rcp_f32_e32 v216, v216
	v_rcp_f32_e32 v217, v217
	v_rcp_f32_e32 v218, v218
	v_rcp_f32_e32 v219, v219
	v_rcp_f32_e32 v220, v220
	v_rcp_f32_e32 v221, v221
	v_rcp_f32_e32 v222, v222
	v_rcp_f32_e32 v223, v223
	v_lshlrev_b32_e32 v242, 16, v134
	v_and_b32_e32 v243, 0xffff0000, v134
	v_lshlrev_b32_e32 v244, 16, v135
	v_and_b32_e32 v245, 0xffff0000, v135
	v_lshlrev_b32_e32 v246, 16, v136
	v_and_b32_e32 v247, 0xffff0000, v136
	v_lshlrev_b32_e32 v248, 16, v137
	v_and_b32_e32 v249, 0xffff0000, v137
	v_pk_mul_f32 v[242:243], v[242:243], s[86:87] op_sel_hi:[1,0]
	v_pk_mul_f32 v[244:245], v[244:245], s[86:87] op_sel_hi:[1,0]
	v_pk_mul_f32 v[246:247], v[246:247], s[86:87] op_sel_hi:[1,0]
	v_pk_mul_f32 v[248:249], v[248:249], s[86:87] op_sel_hi:[1,0]
	v_exp_f32_e32 v242, v242
	v_exp_f32_e32 v243, v243
	v_exp_f32_e32 v244, v244
	v_exp_f32_e32 v245, v245
	v_exp_f32_e32 v246, v246
	v_exp_f32_e32 v247, v247
	v_exp_f32_e32 v248, v248
	v_exp_f32_e32 v249, v249
	v_pk_add_f32 v[242:243], v[242:243], 1.0 op_sel_hi:[1,0]
	v_pk_add_f32 v[244:245], v[244:245], 1.0 op_sel_hi:[1,0]
	v_pk_add_f32 v[246:247], v[246:247], 1.0 op_sel_hi:[1,0]
	v_pk_add_f32 v[248:249], v[248:249], 1.0 op_sel_hi:[1,0]
	v_pk_mul_f32 v[216:217], v[216:217], v[242:243]
	v_pk_mul_f32 v[218:219], v[218:219], v[244:245]
	v_pk_mul_f32 v[220:221], v[220:221], v[246:247]
	v_pk_mul_f32 v[222:223], v[222:223], v[248:249]
	v_pk_mul_f32 v[126:127], v[126:127], v[216:217]
	v_pk_mul_f32 v[128:129], v[128:129], v[218:219]
	v_pk_mul_f32 v[122:123], v[122:123], v[220:221]
	v_pk_mul_f32 v[124:125], v[124:125], v[222:223]
	v_lshlrev_b32_e32 v216, 16, v138
	v_and_b32_e32 v217, 0xffff0000, v138
	v_lshlrev_b32_e32 v218, 16, v139
	v_and_b32_e32 v219, 0xffff0000, v139
	v_lshlrev_b32_e32 v220, 16, v140
	v_and_b32_e32 v221, 0xffff0000, v140
	v_lshlrev_b32_e32 v222, 16, v141
	v_and_b32_e32 v223, 0xffff0000, v141
	v_pk_mul_f32 v[216:217], v[216:217], s[86:87] op_sel_hi:[1,0]
	v_pk_mul_f32 v[218:219], v[218:219], s[86:87] op_sel_hi:[1,0]
	v_pk_mul_f32 v[220:221], v[220:221], s[86:87] op_sel_hi:[1,0]
	v_pk_mul_f32 v[222:223], v[222:223], s[86:87] op_sel_hi:[1,0]
	v_exp_f32_e32 v216, v216
	v_exp_f32_e32 v217, v217
	v_exp_f32_e32 v218, v218
	v_exp_f32_e32 v219, v219
	v_exp_f32_e32 v220, v220
	v_exp_f32_e32 v221, v221
	v_exp_f32_e32 v222, v222
	v_exp_f32_e32 v223, v223
	v_pk_add_f32 v[216:217], v[216:217], 1.0 op_sel_hi:[1,0]
	v_pk_add_f32 v[218:219], v[218:219], 1.0 op_sel_hi:[1,0]
	v_pk_add_f32 v[220:221], v[220:221], 1.0 op_sel_hi:[1,0]
	v_pk_add_f32 v[222:223], v[222:223], 1.0 op_sel_hi:[1,0]
	v_rcp_f32_e32 v216, v216
	v_rcp_f32_e32 v217, v217
	v_rcp_f32_e32 v218, v218
	v_rcp_f32_e32 v219, v219
	v_rcp_f32_e32 v220, v220
	v_rcp_f32_e32 v221, v221
	v_rcp_f32_e32 v222, v222
	v_rcp_f32_e32 v223, v223
	v_lshlrev_b32_e32 v242, 16, v142
	v_and_b32_e32 v243, 0xffff0000, v142
	v_lshlrev_b32_e32 v244, 16, v143
	v_and_b32_e32 v245, 0xffff0000, v143
	v_lshlrev_b32_e32 v246, 16, v144
	v_and_b32_e32 v247, 0xffff0000, v144
	v_lshlrev_b32_e32 v248, 16, v145
	v_and_b32_e32 v249, 0xffff0000, v145
	v_pk_mul_f32 v[242:243], v[242:243], s[86:87] op_sel_hi:[1,0]
	v_pk_mul_f32 v[244:245], v[244:245], s[86:87] op_sel_hi:[1,0]
	v_pk_mul_f32 v[246:247], v[246:247], s[86:87] op_sel_hi:[1,0]
	v_pk_mul_f32 v[248:249], v[248:249], s[86:87] op_sel_hi:[1,0]
	v_exp_f32_e32 v242, v242
	v_exp_f32_e32 v243, v243
	v_exp_f32_e32 v244, v244
	v_exp_f32_e32 v245, v245
	v_exp_f32_e32 v246, v246
	v_exp_f32_e32 v247, v247
	v_exp_f32_e32 v248, v248
	v_exp_f32_e32 v249, v249
	v_pk_add_f32 v[242:243], v[242:243], 1.0 op_sel_hi:[1,0]
	v_pk_add_f32 v[244:245], v[244:245], 1.0 op_sel_hi:[1,0]
	v_pk_add_f32 v[246:247], v[246:247], 1.0 op_sel_hi:[1,0]
	v_pk_add_f32 v[248:249], v[248:249], 1.0 op_sel_hi:[1,0]
	v_pk_mul_f32 v[216:217], v[216:217], v[242:243]
	v_pk_mul_f32 v[218:219], v[218:219], v[244:245]
	v_pk_mul_f32 v[220:221], v[220:221], v[246:247]
	v_pk_mul_f32 v[222:223], v[222:223], v[248:249]
	v_pk_mul_f32 v[94:95], v[94:95], v[216:217]
	v_pk_mul_f32 v[96:97], v[96:97], v[218:219]
	v_pk_mul_f32 v[90:91], v[90:91], v[220:221]
	v_pk_mul_f32 v[92:93], v[92:93], v[222:223]
	s_add_u32 s28, s20, 0x340000
	s_addc_u32 s29, s21, 0
	global_load_dwordx4 v[130:133], v253, s[28:29]
	global_load_dwordx4 v[134:137], v254, s[28:29]
	global_load_dwordx4 v[138:141], v253, s[28:29] offset:256
	global_load_dwordx4 v[142:145], v254, s[28:29] offset:256
	s_waitcnt vmcnt(12)
	v_lshlrev_b32_e32 v216, 16, v146
	v_and_b32_e32 v217, 0xffff0000, v146
	v_lshlrev_b32_e32 v218, 16, v147
	v_and_b32_e32 v219, 0xffff0000, v147
	v_lshlrev_b32_e32 v220, 16, v148
	v_and_b32_e32 v221, 0xffff0000, v148
	v_lshlrev_b32_e32 v222, 16, v149
	v_and_b32_e32 v223, 0xffff0000, v149
	v_pk_mul_f32 v[216:217], v[216:217], s[86:87] op_sel_hi:[1,0]
	v_pk_mul_f32 v[218:219], v[218:219], s[86:87] op_sel_hi:[1,0]
	v_pk_mul_f32 v[220:221], v[220:221], s[86:87] op_sel_hi:[1,0]
	v_pk_mul_f32 v[222:223], v[222:223], s[86:87] op_sel_hi:[1,0]
	v_exp_f32_e32 v216, v216
	v_exp_f32_e32 v217, v217
	v_exp_f32_e32 v218, v218
	v_exp_f32_e32 v219, v219
	v_exp_f32_e32 v220, v220
	v_exp_f32_e32 v221, v221
	v_exp_f32_e32 v222, v222
	v_exp_f32_e32 v223, v223
	v_pk_add_f32 v[216:217], v[216:217], 1.0 op_sel_hi:[1,0]
	v_pk_add_f32 v[218:219], v[218:219], 1.0 op_sel_hi:[1,0]
	v_pk_add_f32 v[220:221], v[220:221], 1.0 op_sel_hi:[1,0]
	v_pk_add_f32 v[222:223], v[222:223], 1.0 op_sel_hi:[1,0]
	v_rcp_f32_e32 v216, v216
	v_rcp_f32_e32 v217, v217
	v_rcp_f32_e32 v218, v218
	v_rcp_f32_e32 v219, v219
	v_rcp_f32_e32 v220, v220
	v_rcp_f32_e32 v221, v221
	v_rcp_f32_e32 v222, v222
	v_rcp_f32_e32 v223, v223
	v_lshlrev_b32_e32 v242, 16, v150
	v_and_b32_e32 v243, 0xffff0000, v150
	v_lshlrev_b32_e32 v244, 16, v151
	v_and_b32_e32 v245, 0xffff0000, v151
	v_lshlrev_b32_e32 v246, 16, v152
	v_and_b32_e32 v247, 0xffff0000, v152
	v_lshlrev_b32_e32 v248, 16, v153
	v_and_b32_e32 v249, 0xffff0000, v153
	v_pk_mul_f32 v[242:243], v[242:243], s[86:87] op_sel_hi:[1,0]
	v_pk_mul_f32 v[244:245], v[244:245], s[86:87] op_sel_hi:[1,0]
	v_pk_mul_f32 v[246:247], v[246:247], s[86:87] op_sel_hi:[1,0]
	v_pk_mul_f32 v[248:249], v[248:249], s[86:87] op_sel_hi:[1,0]
	v_exp_f32_e32 v242, v242
	v_exp_f32_e32 v243, v243
	v_exp_f32_e32 v244, v244
	v_exp_f32_e32 v245, v245
	v_exp_f32_e32 v246, v246
	v_exp_f32_e32 v247, v247
	v_exp_f32_e32 v248, v248
	v_exp_f32_e32 v249, v249
	v_pk_add_f32 v[242:243], v[242:243], 1.0 op_sel_hi:[1,0]
	v_pk_add_f32 v[244:245], v[244:245], 1.0 op_sel_hi:[1,0]
	v_pk_add_f32 v[246:247], v[246:247], 1.0 op_sel_hi:[1,0]
	v_pk_add_f32 v[248:249], v[248:249], 1.0 op_sel_hi:[1,0]
	v_pk_mul_f32 v[216:217], v[216:217], v[242:243]
	v_pk_mul_f32 v[218:219], v[218:219], v[244:245]
	v_pk_mul_f32 v[220:221], v[220:221], v[246:247]
	v_pk_mul_f32 v[222:223], v[222:223], v[248:249]
	v_pk_mul_f32 v[118:119], v[118:119], v[216:217]
	v_pk_mul_f32 v[120:121], v[120:121], v[218:219]
	v_pk_mul_f32 v[114:115], v[114:115], v[220:221]
	v_pk_mul_f32 v[116:117], v[116:117], v[222:223]
	v_lshlrev_b32_e32 v216, 16, v154
	v_and_b32_e32 v217, 0xffff0000, v154
	v_lshlrev_b32_e32 v218, 16, v155
	v_and_b32_e32 v219, 0xffff0000, v155
	v_lshlrev_b32_e32 v220, 16, v156
	v_and_b32_e32 v221, 0xffff0000, v156
	v_lshlrev_b32_e32 v222, 16, v157
	v_and_b32_e32 v223, 0xffff0000, v157
	v_pk_mul_f32 v[216:217], v[216:217], s[86:87] op_sel_hi:[1,0]
	v_pk_mul_f32 v[218:219], v[218:219], s[86:87] op_sel_hi:[1,0]
	v_pk_mul_f32 v[220:221], v[220:221], s[86:87] op_sel_hi:[1,0]
	v_pk_mul_f32 v[222:223], v[222:223], s[86:87] op_sel_hi:[1,0]
	v_exp_f32_e32 v216, v216
	v_exp_f32_e32 v217, v217
	v_exp_f32_e32 v218, v218
	v_exp_f32_e32 v219, v219
	v_exp_f32_e32 v220, v220
	v_exp_f32_e32 v221, v221
	v_exp_f32_e32 v222, v222
	v_exp_f32_e32 v223, v223
	v_pk_add_f32 v[216:217], v[216:217], 1.0 op_sel_hi:[1,0]
	v_pk_add_f32 v[218:219], v[218:219], 1.0 op_sel_hi:[1,0]
	v_pk_add_f32 v[220:221], v[220:221], 1.0 op_sel_hi:[1,0]
	v_pk_add_f32 v[222:223], v[222:223], 1.0 op_sel_hi:[1,0]
	v_rcp_f32_e32 v216, v216
	v_rcp_f32_e32 v217, v217
	v_rcp_f32_e32 v218, v218
	v_rcp_f32_e32 v219, v219
	v_rcp_f32_e32 v220, v220
	v_rcp_f32_e32 v221, v221
	v_rcp_f32_e32 v222, v222
	v_rcp_f32_e32 v223, v223
	v_lshlrev_b32_e32 v242, 16, v158
	v_and_b32_e32 v243, 0xffff0000, v158
	v_lshlrev_b32_e32 v244, 16, v159
	v_and_b32_e32 v245, 0xffff0000, v159
	v_lshlrev_b32_e32 v246, 16, v160
	v_and_b32_e32 v247, 0xffff0000, v160
	v_lshlrev_b32_e32 v248, 16, v161
	v_and_b32_e32 v249, 0xffff0000, v161
	v_pk_mul_f32 v[242:243], v[242:243], s[86:87] op_sel_hi:[1,0]
	v_pk_mul_f32 v[244:245], v[244:245], s[86:87] op_sel_hi:[1,0]
	v_pk_mul_f32 v[246:247], v[246:247], s[86:87] op_sel_hi:[1,0]
	v_pk_mul_f32 v[248:249], v[248:249], s[86:87] op_sel_hi:[1,0]
	v_exp_f32_e32 v242, v242
	v_exp_f32_e32 v243, v243
	v_exp_f32_e32 v244, v244
	v_exp_f32_e32 v245, v245
	v_exp_f32_e32 v246, v246
	v_exp_f32_e32 v247, v247
	v_exp_f32_e32 v248, v248
	v_exp_f32_e32 v249, v249
	v_pk_add_f32 v[242:243], v[242:243], 1.0 op_sel_hi:[1,0]
	v_pk_add_f32 v[244:245], v[244:245], 1.0 op_sel_hi:[1,0]
	v_pk_add_f32 v[246:247], v[246:247], 1.0 op_sel_hi:[1,0]
	v_pk_add_f32 v[248:249], v[248:249], 1.0 op_sel_hi:[1,0]
	v_pk_mul_f32 v[216:217], v[216:217], v[242:243]
	v_pk_mul_f32 v[218:219], v[218:219], v[244:245]
	v_pk_mul_f32 v[220:221], v[220:221], v[246:247]
	v_pk_mul_f32 v[222:223], v[222:223], v[248:249]
	v_pk_mul_f32 v[86:87], v[86:87], v[216:217]
	v_pk_mul_f32 v[88:89], v[88:89], v[218:219]
	v_pk_mul_f32 v[82:83], v[82:83], v[220:221]
	v_pk_mul_f32 v[84:85], v[84:85], v[222:223]
	s_add_u32 s28, s20, 0x3a8000
	s_addc_u32 s29, s21, 0
	global_load_dwordx4 v[146:149], v253, s[28:29]
	global_load_dwordx4 v[150:153], v254, s[28:29]
	global_load_dwordx4 v[154:157], v253, s[28:29] offset:256
	global_load_dwordx4 v[158:161], v254, s[28:29] offset:256
	s_waitcnt vmcnt(12)
	v_lshlrev_b32_e32 v216, 16, v162
	v_and_b32_e32 v217, 0xffff0000, v162
	v_lshlrev_b32_e32 v218, 16, v163
	v_and_b32_e32 v219, 0xffff0000, v163
	v_lshlrev_b32_e32 v220, 16, v164
	v_and_b32_e32 v221, 0xffff0000, v164
	v_lshlrev_b32_e32 v222, 16, v165
	v_and_b32_e32 v223, 0xffff0000, v165
	v_pk_mul_f32 v[216:217], v[216:217], s[86:87] op_sel_hi:[1,0]
	v_pk_mul_f32 v[218:219], v[218:219], s[86:87] op_sel_hi:[1,0]
	v_pk_mul_f32 v[220:221], v[220:221], s[86:87] op_sel_hi:[1,0]
	v_pk_mul_f32 v[222:223], v[222:223], s[86:87] op_sel_hi:[1,0]
	v_exp_f32_e32 v216, v216
	v_exp_f32_e32 v217, v217
	v_exp_f32_e32 v218, v218
	v_exp_f32_e32 v219, v219
	v_exp_f32_e32 v220, v220
	v_exp_f32_e32 v221, v221
	v_exp_f32_e32 v222, v222
	v_exp_f32_e32 v223, v223
	v_pk_add_f32 v[216:217], v[216:217], 1.0 op_sel_hi:[1,0]
	v_pk_add_f32 v[218:219], v[218:219], 1.0 op_sel_hi:[1,0]
	v_pk_add_f32 v[220:221], v[220:221], 1.0 op_sel_hi:[1,0]
	v_pk_add_f32 v[222:223], v[222:223], 1.0 op_sel_hi:[1,0]
	v_rcp_f32_e32 v216, v216
	v_rcp_f32_e32 v217, v217
	v_rcp_f32_e32 v218, v218
	v_rcp_f32_e32 v219, v219
	v_rcp_f32_e32 v220, v220
	v_rcp_f32_e32 v221, v221
	v_rcp_f32_e32 v222, v222
	v_rcp_f32_e32 v223, v223
	v_lshlrev_b32_e32 v242, 16, v166
	v_and_b32_e32 v243, 0xffff0000, v166
	v_lshlrev_b32_e32 v244, 16, v167
	v_and_b32_e32 v245, 0xffff0000, v167
	v_lshlrev_b32_e32 v246, 16, v168
	v_and_b32_e32 v247, 0xffff0000, v168
	v_lshlrev_b32_e32 v248, 16, v169
	v_and_b32_e32 v249, 0xffff0000, v169
	v_pk_mul_f32 v[242:243], v[242:243], s[86:87] op_sel_hi:[1,0]
	v_pk_mul_f32 v[244:245], v[244:245], s[86:87] op_sel_hi:[1,0]
	v_pk_mul_f32 v[246:247], v[246:247], s[86:87] op_sel_hi:[1,0]
	v_pk_mul_f32 v[248:249], v[248:249], s[86:87] op_sel_hi:[1,0]
	v_exp_f32_e32 v242, v242
	v_exp_f32_e32 v243, v243
	v_exp_f32_e32 v244, v244
	v_exp_f32_e32 v245, v245
	v_exp_f32_e32 v246, v246
	v_exp_f32_e32 v247, v247
	v_exp_f32_e32 v248, v248
	v_exp_f32_e32 v249, v249
	v_pk_add_f32 v[242:243], v[242:243], 1.0 op_sel_hi:[1,0]
	v_pk_add_f32 v[244:245], v[244:245], 1.0 op_sel_hi:[1,0]
	v_pk_add_f32 v[246:247], v[246:247], 1.0 op_sel_hi:[1,0]
	v_pk_add_f32 v[248:249], v[248:249], 1.0 op_sel_hi:[1,0]
	v_pk_mul_f32 v[216:217], v[216:217], v[242:243]
	v_pk_mul_f32 v[218:219], v[218:219], v[244:245]
	v_pk_mul_f32 v[220:221], v[220:221], v[246:247]
	v_pk_mul_f32 v[222:223], v[222:223], v[248:249]
	v_pk_mul_f32 v[110:111], v[110:111], v[216:217]
	v_pk_mul_f32 v[112:113], v[112:113], v[218:219]
	v_pk_mul_f32 v[106:107], v[106:107], v[220:221]
	v_pk_mul_f32 v[108:109], v[108:109], v[222:223]
	v_lshlrev_b32_e32 v216, 16, v170
	v_and_b32_e32 v217, 0xffff0000, v170
	v_lshlrev_b32_e32 v218, 16, v171
	v_and_b32_e32 v219, 0xffff0000, v171
	v_lshlrev_b32_e32 v220, 16, v172
	v_and_b32_e32 v221, 0xffff0000, v172
	v_lshlrev_b32_e32 v222, 16, v173
	v_and_b32_e32 v223, 0xffff0000, v173
	v_pk_mul_f32 v[216:217], v[216:217], s[86:87] op_sel_hi:[1,0]
	v_pk_mul_f32 v[218:219], v[218:219], s[86:87] op_sel_hi:[1,0]
	v_pk_mul_f32 v[220:221], v[220:221], s[86:87] op_sel_hi:[1,0]
	v_pk_mul_f32 v[222:223], v[222:223], s[86:87] op_sel_hi:[1,0]
	v_exp_f32_e32 v216, v216
	v_exp_f32_e32 v217, v217
	v_exp_f32_e32 v218, v218
	v_exp_f32_e32 v219, v219
	v_exp_f32_e32 v220, v220
	v_exp_f32_e32 v221, v221
	v_exp_f32_e32 v222, v222
	v_exp_f32_e32 v223, v223
	v_pk_add_f32 v[216:217], v[216:217], 1.0 op_sel_hi:[1,0]
	v_pk_add_f32 v[218:219], v[218:219], 1.0 op_sel_hi:[1,0]
	v_pk_add_f32 v[220:221], v[220:221], 1.0 op_sel_hi:[1,0]
	v_pk_add_f32 v[222:223], v[222:223], 1.0 op_sel_hi:[1,0]
	v_rcp_f32_e32 v216, v216
	v_rcp_f32_e32 v217, v217
	v_rcp_f32_e32 v218, v218
	v_rcp_f32_e32 v219, v219
	v_rcp_f32_e32 v220, v220
	v_rcp_f32_e32 v221, v221
	v_rcp_f32_e32 v222, v222
	v_rcp_f32_e32 v223, v223
	v_lshlrev_b32_e32 v242, 16, v174
	v_and_b32_e32 v243, 0xffff0000, v174
	v_lshlrev_b32_e32 v244, 16, v175
	v_and_b32_e32 v245, 0xffff0000, v175
	v_lshlrev_b32_e32 v246, 16, v176
	v_and_b32_e32 v247, 0xffff0000, v176
	v_lshlrev_b32_e32 v248, 16, v177
	v_and_b32_e32 v249, 0xffff0000, v177
	v_pk_mul_f32 v[242:243], v[242:243], s[86:87] op_sel_hi:[1,0]
	v_pk_mul_f32 v[244:245], v[244:245], s[86:87] op_sel_hi:[1,0]
	v_pk_mul_f32 v[246:247], v[246:247], s[86:87] op_sel_hi:[1,0]
	v_pk_mul_f32 v[248:249], v[248:249], s[86:87] op_sel_hi:[1,0]
	v_exp_f32_e32 v242, v242
	v_exp_f32_e32 v243, v243
	v_exp_f32_e32 v244, v244
	v_exp_f32_e32 v245, v245
	v_exp_f32_e32 v246, v246
	v_exp_f32_e32 v247, v247
	v_exp_f32_e32 v248, v248
	v_exp_f32_e32 v249, v249
	v_pk_add_f32 v[242:243], v[242:243], 1.0 op_sel_hi:[1,0]
	v_pk_add_f32 v[244:245], v[244:245], 1.0 op_sel_hi:[1,0]
	v_pk_add_f32 v[246:247], v[246:247], 1.0 op_sel_hi:[1,0]
	v_pk_add_f32 v[248:249], v[248:249], 1.0 op_sel_hi:[1,0]
	v_pk_mul_f32 v[216:217], v[216:217], v[242:243]
	v_pk_mul_f32 v[218:219], v[218:219], v[244:245]
	v_pk_mul_f32 v[220:221], v[220:221], v[246:247]
	v_pk_mul_f32 v[222:223], v[222:223], v[248:249]
	v_pk_mul_f32 v[78:79], v[78:79], v[216:217]
	v_pk_mul_f32 v[80:81], v[80:81], v[218:219]
	v_pk_mul_f32 v[74:75], v[74:75], v[220:221]
	v_pk_mul_f32 v[76:77], v[76:77], v[222:223]
	s_add_u32 s28, s20, 0x410000
	s_addc_u32 s29, s21, 0
	global_load_dwordx4 v[162:165], v253, s[28:29]
	global_load_dwordx4 v[166:169], v254, s[28:29]
	global_load_dwordx4 v[170:173], v253, s[28:29] offset:256
	global_load_dwordx4 v[174:177], v254, s[28:29] offset:256
	s_waitcnt vmcnt(12)
	v_lshlrev_b32_e32 v216, 16, v178
	v_and_b32_e32 v217, 0xffff0000, v178
	v_lshlrev_b32_e32 v218, 16, v179
	v_and_b32_e32 v219, 0xffff0000, v179
	v_lshlrev_b32_e32 v220, 16, v180
	v_and_b32_e32 v221, 0xffff0000, v180
	v_lshlrev_b32_e32 v222, 16, v181
	v_and_b32_e32 v223, 0xffff0000, v181
	v_pk_mul_f32 v[216:217], v[216:217], s[86:87] op_sel_hi:[1,0]
	v_pk_mul_f32 v[218:219], v[218:219], s[86:87] op_sel_hi:[1,0]
	v_pk_mul_f32 v[220:221], v[220:221], s[86:87] op_sel_hi:[1,0]
	v_pk_mul_f32 v[222:223], v[222:223], s[86:87] op_sel_hi:[1,0]
	v_exp_f32_e32 v216, v216
	v_exp_f32_e32 v217, v217
	v_exp_f32_e32 v218, v218
	v_exp_f32_e32 v219, v219
	v_exp_f32_e32 v220, v220
	v_exp_f32_e32 v221, v221
	v_exp_f32_e32 v222, v222
	v_exp_f32_e32 v223, v223
	v_pk_add_f32 v[216:217], v[216:217], 1.0 op_sel_hi:[1,0]
	v_pk_add_f32 v[218:219], v[218:219], 1.0 op_sel_hi:[1,0]
	v_pk_add_f32 v[220:221], v[220:221], 1.0 op_sel_hi:[1,0]
	v_pk_add_f32 v[222:223], v[222:223], 1.0 op_sel_hi:[1,0]
	v_rcp_f32_e32 v216, v216
	v_rcp_f32_e32 v217, v217
	v_rcp_f32_e32 v218, v218
	v_rcp_f32_e32 v219, v219
	v_rcp_f32_e32 v220, v220
	v_rcp_f32_e32 v221, v221
	v_rcp_f32_e32 v222, v222
	v_rcp_f32_e32 v223, v223
	v_lshlrev_b32_e32 v242, 16, v182
	v_and_b32_e32 v243, 0xffff0000, v182
	v_lshlrev_b32_e32 v244, 16, v183
	v_and_b32_e32 v245, 0xffff0000, v183
	v_lshlrev_b32_e32 v246, 16, v184
	v_and_b32_e32 v247, 0xffff0000, v184
	v_lshlrev_b32_e32 v248, 16, v185
	v_and_b32_e32 v249, 0xffff0000, v185
	v_pk_mul_f32 v[242:243], v[242:243], s[86:87] op_sel_hi:[1,0]
	v_pk_mul_f32 v[244:245], v[244:245], s[86:87] op_sel_hi:[1,0]
	v_pk_mul_f32 v[246:247], v[246:247], s[86:87] op_sel_hi:[1,0]
	v_pk_mul_f32 v[248:249], v[248:249], s[86:87] op_sel_hi:[1,0]
	v_exp_f32_e32 v242, v242
	v_exp_f32_e32 v243, v243
	v_exp_f32_e32 v244, v244
	v_exp_f32_e32 v245, v245
	v_exp_f32_e32 v246, v246
	v_exp_f32_e32 v247, v247
	v_exp_f32_e32 v248, v248
	v_exp_f32_e32 v249, v249
	v_pk_add_f32 v[242:243], v[242:243], 1.0 op_sel_hi:[1,0]
	v_pk_add_f32 v[244:245], v[244:245], 1.0 op_sel_hi:[1,0]
	v_pk_add_f32 v[246:247], v[246:247], 1.0 op_sel_hi:[1,0]
	v_pk_add_f32 v[248:249], v[248:249], 1.0 op_sel_hi:[1,0]
	v_pk_mul_f32 v[216:217], v[216:217], v[242:243]
	v_pk_mul_f32 v[218:219], v[218:219], v[244:245]
	v_pk_mul_f32 v[220:221], v[220:221], v[246:247]
	v_pk_mul_f32 v[222:223], v[222:223], v[248:249]
	v_pk_mul_f32 v[102:103], v[102:103], v[216:217]
	v_pk_mul_f32 v[104:105], v[104:105], v[218:219]
	v_pk_mul_f32 v[98:99], v[98:99], v[220:221]
	v_pk_mul_f32 v[100:101], v[100:101], v[222:223]
	v_lshlrev_b32_e32 v216, 16, v186
	v_and_b32_e32 v217, 0xffff0000, v186
	v_lshlrev_b32_e32 v218, 16, v187
	v_and_b32_e32 v219, 0xffff0000, v187
	v_lshlrev_b32_e32 v220, 16, v188
	v_and_b32_e32 v221, 0xffff0000, v188
	v_lshlrev_b32_e32 v222, 16, v189
	v_and_b32_e32 v223, 0xffff0000, v189
	v_pk_mul_f32 v[216:217], v[216:217], s[86:87] op_sel_hi:[1,0]
	v_pk_mul_f32 v[218:219], v[218:219], s[86:87] op_sel_hi:[1,0]
	v_pk_mul_f32 v[220:221], v[220:221], s[86:87] op_sel_hi:[1,0]
	v_pk_mul_f32 v[222:223], v[222:223], s[86:87] op_sel_hi:[1,0]
	v_exp_f32_e32 v216, v216
	v_exp_f32_e32 v217, v217
	v_exp_f32_e32 v218, v218
	v_exp_f32_e32 v219, v219
	v_exp_f32_e32 v220, v220
	v_exp_f32_e32 v221, v221
	v_exp_f32_e32 v222, v222
	v_exp_f32_e32 v223, v223
	v_pk_add_f32 v[216:217], v[216:217], 1.0 op_sel_hi:[1,0]
	v_pk_add_f32 v[218:219], v[218:219], 1.0 op_sel_hi:[1,0]
	v_pk_add_f32 v[220:221], v[220:221], 1.0 op_sel_hi:[1,0]
	v_pk_add_f32 v[222:223], v[222:223], 1.0 op_sel_hi:[1,0]
	v_rcp_f32_e32 v216, v216
	v_rcp_f32_e32 v217, v217
	v_rcp_f32_e32 v218, v218
	v_rcp_f32_e32 v219, v219
	v_rcp_f32_e32 v220, v220
	v_rcp_f32_e32 v221, v221
	v_rcp_f32_e32 v222, v222
	v_rcp_f32_e32 v223, v223
	v_lshlrev_b32_e32 v242, 16, v190
	v_and_b32_e32 v243, 0xffff0000, v190
	v_lshlrev_b32_e32 v244, 16, v191
	v_and_b32_e32 v245, 0xffff0000, v191
	v_lshlrev_b32_e32 v246, 16, v192
	v_and_b32_e32 v247, 0xffff0000, v192
	v_lshlrev_b32_e32 v248, 16, v193
	v_and_b32_e32 v249, 0xffff0000, v193
	v_pk_mul_f32 v[242:243], v[242:243], s[86:87] op_sel_hi:[1,0]
	v_pk_mul_f32 v[244:245], v[244:245], s[86:87] op_sel_hi:[1,0]
	v_pk_mul_f32 v[246:247], v[246:247], s[86:87] op_sel_hi:[1,0]
	v_pk_mul_f32 v[248:249], v[248:249], s[86:87] op_sel_hi:[1,0]
	v_exp_f32_e32 v242, v242
	v_exp_f32_e32 v243, v243
	v_exp_f32_e32 v244, v244
	v_exp_f32_e32 v245, v245
	v_exp_f32_e32 v246, v246
	v_exp_f32_e32 v247, v247
	v_exp_f32_e32 v248, v248
	v_exp_f32_e32 v249, v249
	v_pk_add_f32 v[242:243], v[242:243], 1.0 op_sel_hi:[1,0]
	v_pk_add_f32 v[244:245], v[244:245], 1.0 op_sel_hi:[1,0]
	v_pk_add_f32 v[246:247], v[246:247], 1.0 op_sel_hi:[1,0]
	v_pk_add_f32 v[248:249], v[248:249], 1.0 op_sel_hi:[1,0]
	v_pk_mul_f32 v[216:217], v[216:217], v[242:243]
	v_pk_mul_f32 v[218:219], v[218:219], v[244:245]
	v_pk_mul_f32 v[220:221], v[220:221], v[246:247]
	v_pk_mul_f32 v[222:223], v[222:223], v[248:249]
	v_pk_mul_f32 v[70:71], v[70:71], v[216:217]
	v_pk_mul_f32 v[72:73], v[72:73], v[218:219]
	v_pk_mul_f32 v[66:67], v[66:67], v[220:221]
	v_pk_mul_f32 v[68:69], v[68:69], v[222:223]
	s_add_u32 s28, s20, 0x478000
	s_addc_u32 s29, s21, 0
	global_load_dwordx4 v[178:181], v253, s[28:29]
	global_load_dwordx4 v[182:185], v254, s[28:29]
	global_load_dwordx4 v[186:189], v253, s[28:29] offset:256
	global_load_dwordx4 v[190:193], v254, s[28:29] offset:256
	s_waitcnt vmcnt(12)
	v_lshlrev_b32_e32 v216, 16, v130
	v_and_b32_e32 v217, 0xffff0000, v130
	v_lshlrev_b32_e32 v218, 16, v131
	v_and_b32_e32 v219, 0xffff0000, v131
	v_lshlrev_b32_e32 v220, 16, v132
	v_and_b32_e32 v221, 0xffff0000, v132
	v_lshlrev_b32_e32 v222, 16, v133
	v_and_b32_e32 v223, 0xffff0000, v133
	v_pk_mul_f32 v[216:217], v[216:217], s[86:87] op_sel_hi:[1,0]
	v_pk_mul_f32 v[218:219], v[218:219], s[86:87] op_sel_hi:[1,0]
	v_pk_mul_f32 v[220:221], v[220:221], s[86:87] op_sel_hi:[1,0]
	v_pk_mul_f32 v[222:223], v[222:223], s[86:87] op_sel_hi:[1,0]
	v_exp_f32_e32 v216, v216
	v_exp_f32_e32 v217, v217
	v_exp_f32_e32 v218, v218
	v_exp_f32_e32 v219, v219
	v_exp_f32_e32 v220, v220
	v_exp_f32_e32 v221, v221
	v_exp_f32_e32 v222, v222
	v_exp_f32_e32 v223, v223
	v_pk_add_f32 v[216:217], v[216:217], 1.0 op_sel_hi:[1,0]
	v_pk_add_f32 v[218:219], v[218:219], 1.0 op_sel_hi:[1,0]
	v_pk_add_f32 v[220:221], v[220:221], 1.0 op_sel_hi:[1,0]
	v_pk_add_f32 v[222:223], v[222:223], 1.0 op_sel_hi:[1,0]
	v_rcp_f32_e32 v216, v216
	v_rcp_f32_e32 v217, v217
	v_rcp_f32_e32 v218, v218
	v_rcp_f32_e32 v219, v219
	v_rcp_f32_e32 v220, v220
	v_rcp_f32_e32 v221, v221
	v_rcp_f32_e32 v222, v222
	v_rcp_f32_e32 v223, v223
	v_lshlrev_b32_e32 v242, 16, v134
	v_and_b32_e32 v243, 0xffff0000, v134
	v_lshlrev_b32_e32 v244, 16, v135
	v_and_b32_e32 v245, 0xffff0000, v135
	v_lshlrev_b32_e32 v246, 16, v136
	v_and_b32_e32 v247, 0xffff0000, v136
	v_lshlrev_b32_e32 v248, 16, v137
	v_and_b32_e32 v249, 0xffff0000, v137
	v_pk_mul_f32 v[242:243], v[242:243], s[86:87] op_sel_hi:[1,0]
	v_pk_mul_f32 v[244:245], v[244:245], s[86:87] op_sel_hi:[1,0]
	v_pk_mul_f32 v[246:247], v[246:247], s[86:87] op_sel_hi:[1,0]
	v_pk_mul_f32 v[248:249], v[248:249], s[86:87] op_sel_hi:[1,0]
	v_exp_f32_e32 v242, v242
	v_exp_f32_e32 v243, v243
	v_exp_f32_e32 v244, v244
	v_exp_f32_e32 v245, v245
	v_exp_f32_e32 v246, v246
	v_exp_f32_e32 v247, v247
	v_exp_f32_e32 v248, v248
	v_exp_f32_e32 v249, v249
	v_pk_add_f32 v[242:243], v[242:243], 1.0 op_sel_hi:[1,0]
	v_pk_add_f32 v[244:245], v[244:245], 1.0 op_sel_hi:[1,0]
	v_pk_add_f32 v[246:247], v[246:247], 1.0 op_sel_hi:[1,0]
	v_pk_add_f32 v[248:249], v[248:249], 1.0 op_sel_hi:[1,0]
	v_pk_mul_f32 v[216:217], v[216:217], v[242:243]
	v_pk_mul_f32 v[218:219], v[218:219], v[244:245]
	v_pk_mul_f32 v[220:221], v[220:221], v[246:247]
	v_pk_mul_f32 v[222:223], v[222:223], v[248:249]
	v_pk_mul_f32 v[62:63], v[62:63], v[216:217]
	v_pk_mul_f32 v[64:65], v[64:65], v[218:219]
	v_pk_mul_f32 v[58:59], v[58:59], v[220:221]
	v_pk_mul_f32 v[60:61], v[60:61], v[222:223]
	v_lshlrev_b32_e32 v216, 16, v138
	v_and_b32_e32 v217, 0xffff0000, v138
	v_lshlrev_b32_e32 v218, 16, v139
	v_and_b32_e32 v219, 0xffff0000, v139
	v_lshlrev_b32_e32 v220, 16, v140
	v_and_b32_e32 v221, 0xffff0000, v140
	v_lshlrev_b32_e32 v222, 16, v141
	v_and_b32_e32 v223, 0xffff0000, v141
	v_pk_mul_f32 v[216:217], v[216:217], s[86:87] op_sel_hi:[1,0]
	v_pk_mul_f32 v[218:219], v[218:219], s[86:87] op_sel_hi:[1,0]
	v_pk_mul_f32 v[220:221], v[220:221], s[86:87] op_sel_hi:[1,0]
	v_pk_mul_f32 v[222:223], v[222:223], s[86:87] op_sel_hi:[1,0]
	v_exp_f32_e32 v216, v216
	v_exp_f32_e32 v217, v217
	v_exp_f32_e32 v218, v218
	v_exp_f32_e32 v219, v219
	v_exp_f32_e32 v220, v220
	v_exp_f32_e32 v221, v221
	v_exp_f32_e32 v222, v222
	v_exp_f32_e32 v223, v223
	v_pk_add_f32 v[216:217], v[216:217], 1.0 op_sel_hi:[1,0]
	v_pk_add_f32 v[218:219], v[218:219], 1.0 op_sel_hi:[1,0]
	v_pk_add_f32 v[220:221], v[220:221], 1.0 op_sel_hi:[1,0]
	v_pk_add_f32 v[222:223], v[222:223], 1.0 op_sel_hi:[1,0]
	v_rcp_f32_e32 v216, v216
	v_rcp_f32_e32 v217, v217
	v_rcp_f32_e32 v218, v218
	v_rcp_f32_e32 v219, v219
	v_rcp_f32_e32 v220, v220
	v_rcp_f32_e32 v221, v221
	v_rcp_f32_e32 v222, v222
	v_rcp_f32_e32 v223, v223
	v_lshlrev_b32_e32 v242, 16, v142
	v_and_b32_e32 v243, 0xffff0000, v142
	v_lshlrev_b32_e32 v244, 16, v143
	v_and_b32_e32 v245, 0xffff0000, v143
	v_lshlrev_b32_e32 v246, 16, v144
	v_and_b32_e32 v247, 0xffff0000, v144
	v_lshlrev_b32_e32 v248, 16, v145
	v_and_b32_e32 v249, 0xffff0000, v145
	v_pk_mul_f32 v[242:243], v[242:243], s[86:87] op_sel_hi:[1,0]
	v_pk_mul_f32 v[244:245], v[244:245], s[86:87] op_sel_hi:[1,0]
	v_pk_mul_f32 v[246:247], v[246:247], s[86:87] op_sel_hi:[1,0]
	v_pk_mul_f32 v[248:249], v[248:249], s[86:87] op_sel_hi:[1,0]
	v_exp_f32_e32 v242, v242
	v_exp_f32_e32 v243, v243
	v_exp_f32_e32 v244, v244
	v_exp_f32_e32 v245, v245
	v_exp_f32_e32 v246, v246
	v_exp_f32_e32 v247, v247
	v_exp_f32_e32 v248, v248
	v_exp_f32_e32 v249, v249
	v_pk_add_f32 v[242:243], v[242:243], 1.0 op_sel_hi:[1,0]
	v_pk_add_f32 v[244:245], v[244:245], 1.0 op_sel_hi:[1,0]
	v_pk_add_f32 v[246:247], v[246:247], 1.0 op_sel_hi:[1,0]
	v_pk_add_f32 v[248:249], v[248:249], 1.0 op_sel_hi:[1,0]
	v_pk_mul_f32 v[216:217], v[216:217], v[242:243]
	v_pk_mul_f32 v[218:219], v[218:219], v[244:245]
	v_pk_mul_f32 v[220:221], v[220:221], v[246:247]
	v_pk_mul_f32 v[222:223], v[222:223], v[248:249]
	v_pk_mul_f32 v[30:31], v[30:31], v[216:217]
	v_pk_mul_f32 v[32:33], v[32:33], v[218:219]
	v_pk_mul_f32 v[26:27], v[26:27], v[220:221]
	v_pk_mul_f32 v[28:29], v[28:29], v[222:223]
	s_waitcnt vmcnt(8)
	v_lshlrev_b32_e32 v216, 16, v146
	v_and_b32_e32 v217, 0xffff0000, v146
	v_lshlrev_b32_e32 v218, 16, v147
	v_and_b32_e32 v219, 0xffff0000, v147
	v_lshlrev_b32_e32 v220, 16, v148
	v_and_b32_e32 v221, 0xffff0000, v148
	v_lshlrev_b32_e32 v222, 16, v149
	v_and_b32_e32 v223, 0xffff0000, v149
	v_pk_mul_f32 v[216:217], v[216:217], s[86:87] op_sel_hi:[1,0]
	v_pk_mul_f32 v[218:219], v[218:219], s[86:87] op_sel_hi:[1,0]
	v_pk_mul_f32 v[220:221], v[220:221], s[86:87] op_sel_hi:[1,0]
	v_pk_mul_f32 v[222:223], v[222:223], s[86:87] op_sel_hi:[1,0]
	v_exp_f32_e32 v216, v216
	v_exp_f32_e32 v217, v217
	v_exp_f32_e32 v218, v218
	v_exp_f32_e32 v219, v219
	v_exp_f32_e32 v220, v220
	v_exp_f32_e32 v221, v221
	v_exp_f32_e32 v222, v222
	v_exp_f32_e32 v223, v223
	v_pk_add_f32 v[216:217], v[216:217], 1.0 op_sel_hi:[1,0]
	v_pk_add_f32 v[218:219], v[218:219], 1.0 op_sel_hi:[1,0]
	v_pk_add_f32 v[220:221], v[220:221], 1.0 op_sel_hi:[1,0]
	v_pk_add_f32 v[222:223], v[222:223], 1.0 op_sel_hi:[1,0]
	v_rcp_f32_e32 v216, v216
	v_rcp_f32_e32 v217, v217
	v_rcp_f32_e32 v218, v218
	v_rcp_f32_e32 v219, v219
	v_rcp_f32_e32 v220, v220
	v_rcp_f32_e32 v221, v221
	v_rcp_f32_e32 v222, v222
	v_rcp_f32_e32 v223, v223
	v_lshlrev_b32_e32 v242, 16, v150
	v_and_b32_e32 v243, 0xffff0000, v150
	v_lshlrev_b32_e32 v244, 16, v151
	v_and_b32_e32 v245, 0xffff0000, v151
	v_lshlrev_b32_e32 v246, 16, v152
	v_and_b32_e32 v247, 0xffff0000, v152
	v_lshlrev_b32_e32 v248, 16, v153
	v_and_b32_e32 v249, 0xffff0000, v153
	v_pk_mul_f32 v[242:243], v[242:243], s[86:87] op_sel_hi:[1,0]
	v_pk_mul_f32 v[244:245], v[244:245], s[86:87] op_sel_hi:[1,0]
	v_pk_mul_f32 v[246:247], v[246:247], s[86:87] op_sel_hi:[1,0]
	v_pk_mul_f32 v[248:249], v[248:249], s[86:87] op_sel_hi:[1,0]
	v_exp_f32_e32 v242, v242
	v_exp_f32_e32 v243, v243
	v_exp_f32_e32 v244, v244
	v_exp_f32_e32 v245, v245
	v_exp_f32_e32 v246, v246
	v_exp_f32_e32 v247, v247
	v_exp_f32_e32 v248, v248
	v_exp_f32_e32 v249, v249
	v_pk_add_f32 v[242:243], v[242:243], 1.0 op_sel_hi:[1,0]
	v_pk_add_f32 v[244:245], v[244:245], 1.0 op_sel_hi:[1,0]
	v_pk_add_f32 v[246:247], v[246:247], 1.0 op_sel_hi:[1,0]
	v_pk_add_f32 v[248:249], v[248:249], 1.0 op_sel_hi:[1,0]
	v_pk_mul_f32 v[216:217], v[216:217], v[242:243]
	v_pk_mul_f32 v[218:219], v[218:219], v[244:245]
	v_pk_mul_f32 v[220:221], v[220:221], v[246:247]
	v_pk_mul_f32 v[222:223], v[222:223], v[248:249]
	v_pk_mul_f32 v[54:55], v[54:55], v[216:217]
	v_pk_mul_f32 v[56:57], v[56:57], v[218:219]
	v_pk_mul_f32 v[50:51], v[50:51], v[220:221]
	v_pk_mul_f32 v[52:53], v[52:53], v[222:223]
	v_lshlrev_b32_e32 v216, 16, v154
	v_and_b32_e32 v217, 0xffff0000, v154
	v_lshlrev_b32_e32 v218, 16, v155
	v_and_b32_e32 v219, 0xffff0000, v155
	v_lshlrev_b32_e32 v220, 16, v156
	v_and_b32_e32 v221, 0xffff0000, v156
	v_lshlrev_b32_e32 v222, 16, v157
	v_and_b32_e32 v223, 0xffff0000, v157
	v_pk_mul_f32 v[216:217], v[216:217], s[86:87] op_sel_hi:[1,0]
	v_pk_mul_f32 v[218:219], v[218:219], s[86:87] op_sel_hi:[1,0]
	v_pk_mul_f32 v[220:221], v[220:221], s[86:87] op_sel_hi:[1,0]
	v_pk_mul_f32 v[222:223], v[222:223], s[86:87] op_sel_hi:[1,0]
	v_exp_f32_e32 v216, v216
	v_exp_f32_e32 v217, v217
	v_exp_f32_e32 v218, v218
	v_exp_f32_e32 v219, v219
	v_exp_f32_e32 v220, v220
	v_exp_f32_e32 v221, v221
	v_exp_f32_e32 v222, v222
	v_exp_f32_e32 v223, v223
	v_pk_add_f32 v[216:217], v[216:217], 1.0 op_sel_hi:[1,0]
	v_pk_add_f32 v[218:219], v[218:219], 1.0 op_sel_hi:[1,0]
	v_pk_add_f32 v[220:221], v[220:221], 1.0 op_sel_hi:[1,0]
	v_pk_add_f32 v[222:223], v[222:223], 1.0 op_sel_hi:[1,0]
	v_rcp_f32_e32 v216, v216
	v_rcp_f32_e32 v217, v217
	v_rcp_f32_e32 v218, v218
	v_rcp_f32_e32 v219, v219
	v_rcp_f32_e32 v220, v220
	v_rcp_f32_e32 v221, v221
	v_rcp_f32_e32 v222, v222
	v_rcp_f32_e32 v223, v223
	v_lshlrev_b32_e32 v242, 16, v158
	v_and_b32_e32 v243, 0xffff0000, v158
	v_lshlrev_b32_e32 v244, 16, v159
	v_and_b32_e32 v245, 0xffff0000, v159
	v_lshlrev_b32_e32 v246, 16, v160
	v_and_b32_e32 v247, 0xffff0000, v160
	v_lshlrev_b32_e32 v248, 16, v161
	v_and_b32_e32 v249, 0xffff0000, v161
	v_pk_mul_f32 v[242:243], v[242:243], s[86:87] op_sel_hi:[1,0]
	v_pk_mul_f32 v[244:245], v[244:245], s[86:87] op_sel_hi:[1,0]
	v_pk_mul_f32 v[246:247], v[246:247], s[86:87] op_sel_hi:[1,0]
	v_pk_mul_f32 v[248:249], v[248:249], s[86:87] op_sel_hi:[1,0]
	v_exp_f32_e32 v242, v242
	v_exp_f32_e32 v243, v243
	v_exp_f32_e32 v244, v244
	v_exp_f32_e32 v245, v245
	v_exp_f32_e32 v246, v246
	v_exp_f32_e32 v247, v247
	v_exp_f32_e32 v248, v248
	v_exp_f32_e32 v249, v249
	v_pk_add_f32 v[242:243], v[242:243], 1.0 op_sel_hi:[1,0]
	v_pk_add_f32 v[244:245], v[244:245], 1.0 op_sel_hi:[1,0]
	v_pk_add_f32 v[246:247], v[246:247], 1.0 op_sel_hi:[1,0]
	v_pk_add_f32 v[248:249], v[248:249], 1.0 op_sel_hi:[1,0]
	v_pk_mul_f32 v[216:217], v[216:217], v[242:243]
	v_pk_mul_f32 v[218:219], v[218:219], v[244:245]
	v_pk_mul_f32 v[220:221], v[220:221], v[246:247]
	v_pk_mul_f32 v[222:223], v[222:223], v[248:249]
	v_pk_mul_f32 v[22:23], v[22:23], v[216:217]
	v_pk_mul_f32 v[24:25], v[24:25], v[218:219]
	v_pk_mul_f32 v[18:19], v[18:19], v[220:221]
	v_pk_mul_f32 v[20:21], v[20:21], v[222:223]
	s_waitcnt vmcnt(4)
	v_lshlrev_b32_e32 v216, 16, v162
	v_and_b32_e32 v217, 0xffff0000, v162
	v_lshlrev_b32_e32 v218, 16, v163
	v_and_b32_e32 v219, 0xffff0000, v163
	v_lshlrev_b32_e32 v220, 16, v164
	v_and_b32_e32 v221, 0xffff0000, v164
	v_lshlrev_b32_e32 v222, 16, v165
	v_and_b32_e32 v223, 0xffff0000, v165
	v_pk_mul_f32 v[216:217], v[216:217], s[86:87] op_sel_hi:[1,0]
	v_pk_mul_f32 v[218:219], v[218:219], s[86:87] op_sel_hi:[1,0]
	v_pk_mul_f32 v[220:221], v[220:221], s[86:87] op_sel_hi:[1,0]
	v_pk_mul_f32 v[222:223], v[222:223], s[86:87] op_sel_hi:[1,0]
	v_exp_f32_e32 v216, v216
	v_exp_f32_e32 v217, v217
	v_exp_f32_e32 v218, v218
	v_exp_f32_e32 v219, v219
	v_exp_f32_e32 v220, v220
	v_exp_f32_e32 v221, v221
	v_exp_f32_e32 v222, v222
	v_exp_f32_e32 v223, v223
	v_pk_add_f32 v[216:217], v[216:217], 1.0 op_sel_hi:[1,0]
	v_pk_add_f32 v[218:219], v[218:219], 1.0 op_sel_hi:[1,0]
	v_pk_add_f32 v[220:221], v[220:221], 1.0 op_sel_hi:[1,0]
	v_pk_add_f32 v[222:223], v[222:223], 1.0 op_sel_hi:[1,0]
	v_rcp_f32_e32 v216, v216
	v_rcp_f32_e32 v217, v217
	v_rcp_f32_e32 v218, v218
	v_rcp_f32_e32 v219, v219
	v_rcp_f32_e32 v220, v220
	v_rcp_f32_e32 v221, v221
	v_rcp_f32_e32 v222, v222
	v_rcp_f32_e32 v223, v223
	v_lshlrev_b32_e32 v242, 16, v166
	v_and_b32_e32 v243, 0xffff0000, v166
	v_lshlrev_b32_e32 v244, 16, v167
	v_and_b32_e32 v245, 0xffff0000, v167
	v_lshlrev_b32_e32 v246, 16, v168
	v_and_b32_e32 v247, 0xffff0000, v168
	v_lshlrev_b32_e32 v248, 16, v169
	v_and_b32_e32 v249, 0xffff0000, v169
	v_pk_mul_f32 v[242:243], v[242:243], s[86:87] op_sel_hi:[1,0]
	v_pk_mul_f32 v[244:245], v[244:245], s[86:87] op_sel_hi:[1,0]
	v_pk_mul_f32 v[246:247], v[246:247], s[86:87] op_sel_hi:[1,0]
	v_pk_mul_f32 v[248:249], v[248:249], s[86:87] op_sel_hi:[1,0]
	v_exp_f32_e32 v242, v242
	v_exp_f32_e32 v243, v243
	v_exp_f32_e32 v244, v244
	v_exp_f32_e32 v245, v245
	v_exp_f32_e32 v246, v246
	v_exp_f32_e32 v247, v247
	v_exp_f32_e32 v248, v248
	v_exp_f32_e32 v249, v249
	v_pk_add_f32 v[242:243], v[242:243], 1.0 op_sel_hi:[1,0]
	v_pk_add_f32 v[244:245], v[244:245], 1.0 op_sel_hi:[1,0]
	v_pk_add_f32 v[246:247], v[246:247], 1.0 op_sel_hi:[1,0]
	v_pk_add_f32 v[248:249], v[248:249], 1.0 op_sel_hi:[1,0]
	v_pk_mul_f32 v[216:217], v[216:217], v[242:243]
	v_pk_mul_f32 v[218:219], v[218:219], v[244:245]
	v_pk_mul_f32 v[220:221], v[220:221], v[246:247]
	v_pk_mul_f32 v[222:223], v[222:223], v[248:249]
	v_pk_mul_f32 v[46:47], v[46:47], v[216:217]
	v_pk_mul_f32 v[48:49], v[48:49], v[218:219]
	v_pk_mul_f32 v[42:43], v[42:43], v[220:221]
	v_pk_mul_f32 v[44:45], v[44:45], v[222:223]
	v_lshlrev_b32_e32 v216, 16, v170
	v_and_b32_e32 v217, 0xffff0000, v170
	v_lshlrev_b32_e32 v218, 16, v171
	v_and_b32_e32 v219, 0xffff0000, v171
	v_lshlrev_b32_e32 v220, 16, v172
	v_and_b32_e32 v221, 0xffff0000, v172
	v_lshlrev_b32_e32 v222, 16, v173
	v_and_b32_e32 v223, 0xffff0000, v173
	v_pk_mul_f32 v[216:217], v[216:217], s[86:87] op_sel_hi:[1,0]
	v_pk_mul_f32 v[218:219], v[218:219], s[86:87] op_sel_hi:[1,0]
	v_pk_mul_f32 v[220:221], v[220:221], s[86:87] op_sel_hi:[1,0]
	v_pk_mul_f32 v[222:223], v[222:223], s[86:87] op_sel_hi:[1,0]
	v_exp_f32_e32 v216, v216
	v_exp_f32_e32 v217, v217
	v_exp_f32_e32 v218, v218
	v_exp_f32_e32 v219, v219
	v_exp_f32_e32 v220, v220
	v_exp_f32_e32 v221, v221
	v_exp_f32_e32 v222, v222
	v_exp_f32_e32 v223, v223
	v_pk_add_f32 v[216:217], v[216:217], 1.0 op_sel_hi:[1,0]
	v_pk_add_f32 v[218:219], v[218:219], 1.0 op_sel_hi:[1,0]
	v_pk_add_f32 v[220:221], v[220:221], 1.0 op_sel_hi:[1,0]
	v_pk_add_f32 v[222:223], v[222:223], 1.0 op_sel_hi:[1,0]
	v_rcp_f32_e32 v216, v216
	v_rcp_f32_e32 v217, v217
	v_rcp_f32_e32 v218, v218
	v_rcp_f32_e32 v219, v219
	v_rcp_f32_e32 v220, v220
	v_rcp_f32_e32 v221, v221
	v_rcp_f32_e32 v222, v222
	v_rcp_f32_e32 v223, v223
	v_lshlrev_b32_e32 v242, 16, v174
	v_and_b32_e32 v243, 0xffff0000, v174
	v_lshlrev_b32_e32 v244, 16, v175
	v_and_b32_e32 v245, 0xffff0000, v175
	v_lshlrev_b32_e32 v246, 16, v176
	v_and_b32_e32 v247, 0xffff0000, v176
	v_lshlrev_b32_e32 v248, 16, v177
	v_and_b32_e32 v249, 0xffff0000, v177
	v_pk_mul_f32 v[242:243], v[242:243], s[86:87] op_sel_hi:[1,0]
	v_pk_mul_f32 v[244:245], v[244:245], s[86:87] op_sel_hi:[1,0]
	v_pk_mul_f32 v[246:247], v[246:247], s[86:87] op_sel_hi:[1,0]
	v_pk_mul_f32 v[248:249], v[248:249], s[86:87] op_sel_hi:[1,0]
	v_exp_f32_e32 v242, v242
	v_exp_f32_e32 v243, v243
	v_exp_f32_e32 v244, v244
	v_exp_f32_e32 v245, v245
	v_exp_f32_e32 v246, v246
	v_exp_f32_e32 v247, v247
	v_exp_f32_e32 v248, v248
	v_exp_f32_e32 v249, v249
	v_pk_add_f32 v[242:243], v[242:243], 1.0 op_sel_hi:[1,0]
	v_pk_add_f32 v[244:245], v[244:245], 1.0 op_sel_hi:[1,0]
	v_pk_add_f32 v[246:247], v[246:247], 1.0 op_sel_hi:[1,0]
	v_pk_add_f32 v[248:249], v[248:249], 1.0 op_sel_hi:[1,0]
	v_pk_mul_f32 v[216:217], v[216:217], v[242:243]
	v_pk_mul_f32 v[218:219], v[218:219], v[244:245]
	v_pk_mul_f32 v[220:221], v[220:221], v[246:247]
	v_pk_mul_f32 v[222:223], v[222:223], v[248:249]
	v_pk_mul_f32 v[14:15], v[14:15], v[216:217]
	v_pk_mul_f32 v[16:17], v[16:17], v[218:219]
	v_pk_mul_f32 v[10:11], v[10:11], v[220:221]
	v_pk_mul_f32 v[12:13], v[12:13], v[222:223]
	s_waitcnt vmcnt(0)
	v_lshlrev_b32_e32 v216, 16, v178
	v_and_b32_e32 v217, 0xffff0000, v178
	v_lshlrev_b32_e32 v218, 16, v179
	v_and_b32_e32 v219, 0xffff0000, v179
	v_lshlrev_b32_e32 v220, 16, v180
	v_and_b32_e32 v221, 0xffff0000, v180
	v_lshlrev_b32_e32 v222, 16, v181
	v_and_b32_e32 v223, 0xffff0000, v181
	v_pk_mul_f32 v[216:217], v[216:217], s[86:87] op_sel_hi:[1,0]
	v_pk_mul_f32 v[218:219], v[218:219], s[86:87] op_sel_hi:[1,0]
	v_pk_mul_f32 v[220:221], v[220:221], s[86:87] op_sel_hi:[1,0]
	v_pk_mul_f32 v[222:223], v[222:223], s[86:87] op_sel_hi:[1,0]
	v_exp_f32_e32 v216, v216
	v_exp_f32_e32 v217, v217
	v_exp_f32_e32 v218, v218
	v_exp_f32_e32 v219, v219
	v_exp_f32_e32 v220, v220
	v_exp_f32_e32 v221, v221
	v_exp_f32_e32 v222, v222
	v_exp_f32_e32 v223, v223
	v_pk_add_f32 v[216:217], v[216:217], 1.0 op_sel_hi:[1,0]
	v_pk_add_f32 v[218:219], v[218:219], 1.0 op_sel_hi:[1,0]
	v_pk_add_f32 v[220:221], v[220:221], 1.0 op_sel_hi:[1,0]
	v_pk_add_f32 v[222:223], v[222:223], 1.0 op_sel_hi:[1,0]
	v_rcp_f32_e32 v216, v216
	v_rcp_f32_e32 v217, v217
	v_rcp_f32_e32 v218, v218
	v_rcp_f32_e32 v219, v219
	v_rcp_f32_e32 v220, v220
	v_rcp_f32_e32 v221, v221
	v_rcp_f32_e32 v222, v222
	v_rcp_f32_e32 v223, v223
	v_lshlrev_b32_e32 v242, 16, v182
	v_and_b32_e32 v243, 0xffff0000, v182
	v_lshlrev_b32_e32 v244, 16, v183
	v_and_b32_e32 v245, 0xffff0000, v183
	v_lshlrev_b32_e32 v246, 16, v184
	v_and_b32_e32 v247, 0xffff0000, v184
	v_lshlrev_b32_e32 v248, 16, v185
	v_and_b32_e32 v249, 0xffff0000, v185
	v_pk_mul_f32 v[242:243], v[242:243], s[86:87] op_sel_hi:[1,0]
	v_pk_mul_f32 v[244:245], v[244:245], s[86:87] op_sel_hi:[1,0]
	v_pk_mul_f32 v[246:247], v[246:247], s[86:87] op_sel_hi:[1,0]
	v_pk_mul_f32 v[248:249], v[248:249], s[86:87] op_sel_hi:[1,0]
	v_exp_f32_e32 v242, v242
	v_exp_f32_e32 v243, v243
	v_exp_f32_e32 v244, v244
	v_exp_f32_e32 v245, v245
	v_exp_f32_e32 v246, v246
	v_exp_f32_e32 v247, v247
	v_exp_f32_e32 v248, v248
	v_exp_f32_e32 v249, v249
	v_pk_add_f32 v[242:243], v[242:243], 1.0 op_sel_hi:[1,0]
	v_pk_add_f32 v[244:245], v[244:245], 1.0 op_sel_hi:[1,0]
	v_pk_add_f32 v[246:247], v[246:247], 1.0 op_sel_hi:[1,0]
	v_pk_add_f32 v[248:249], v[248:249], 1.0 op_sel_hi:[1,0]
	v_pk_mul_f32 v[216:217], v[216:217], v[242:243]
	v_pk_mul_f32 v[218:219], v[218:219], v[244:245]
	v_pk_mul_f32 v[220:221], v[220:221], v[246:247]
	v_pk_mul_f32 v[222:223], v[222:223], v[248:249]
	v_pk_mul_f32 v[38:39], v[38:39], v[216:217]
	v_pk_mul_f32 v[40:41], v[40:41], v[218:219]
	v_pk_mul_f32 v[34:35], v[34:35], v[220:221]
	v_pk_mul_f32 v[36:37], v[36:37], v[222:223]
	v_lshlrev_b32_e32 v216, 16, v186
	v_and_b32_e32 v217, 0xffff0000, v186
	v_lshlrev_b32_e32 v218, 16, v187
	v_and_b32_e32 v219, 0xffff0000, v187
	v_lshlrev_b32_e32 v220, 16, v188
	v_and_b32_e32 v221, 0xffff0000, v188
	v_lshlrev_b32_e32 v222, 16, v189
	v_and_b32_e32 v223, 0xffff0000, v189
	v_pk_mul_f32 v[216:217], v[216:217], s[86:87] op_sel_hi:[1,0]
	v_pk_mul_f32 v[218:219], v[218:219], s[86:87] op_sel_hi:[1,0]
	v_pk_mul_f32 v[220:221], v[220:221], s[86:87] op_sel_hi:[1,0]
	v_pk_mul_f32 v[222:223], v[222:223], s[86:87] op_sel_hi:[1,0]
	v_exp_f32_e32 v216, v216
	v_exp_f32_e32 v217, v217
	v_exp_f32_e32 v218, v218
	v_exp_f32_e32 v219, v219
	v_exp_f32_e32 v220, v220
	v_exp_f32_e32 v221, v221
	v_exp_f32_e32 v222, v222
	v_exp_f32_e32 v223, v223
	v_pk_add_f32 v[216:217], v[216:217], 1.0 op_sel_hi:[1,0]
	v_pk_add_f32 v[218:219], v[218:219], 1.0 op_sel_hi:[1,0]
	v_pk_add_f32 v[220:221], v[220:221], 1.0 op_sel_hi:[1,0]
	v_pk_add_f32 v[222:223], v[222:223], 1.0 op_sel_hi:[1,0]
	v_rcp_f32_e32 v216, v216
	v_rcp_f32_e32 v217, v217
	v_rcp_f32_e32 v218, v218
	v_rcp_f32_e32 v219, v219
	v_rcp_f32_e32 v220, v220
	v_rcp_f32_e32 v221, v221
	v_rcp_f32_e32 v222, v222
	v_rcp_f32_e32 v223, v223
	v_lshlrev_b32_e32 v242, 16, v190
	v_and_b32_e32 v243, 0xffff0000, v190
	v_lshlrev_b32_e32 v244, 16, v191
	v_and_b32_e32 v245, 0xffff0000, v191
	v_lshlrev_b32_e32 v246, 16, v192
	v_and_b32_e32 v247, 0xffff0000, v192
	v_lshlrev_b32_e32 v248, 16, v193
	v_and_b32_e32 v249, 0xffff0000, v193
	v_pk_mul_f32 v[242:243], v[242:243], s[86:87] op_sel_hi:[1,0]
	v_pk_mul_f32 v[244:245], v[244:245], s[86:87] op_sel_hi:[1,0]
	v_pk_mul_f32 v[246:247], v[246:247], s[86:87] op_sel_hi:[1,0]
	v_pk_mul_f32 v[248:249], v[248:249], s[86:87] op_sel_hi:[1,0]
	v_exp_f32_e32 v242, v242
	v_exp_f32_e32 v243, v243
	v_exp_f32_e32 v244, v244
	v_exp_f32_e32 v245, v245
	v_exp_f32_e32 v246, v246
	v_exp_f32_e32 v247, v247
	v_exp_f32_e32 v248, v248
	v_exp_f32_e32 v249, v249
	v_pk_add_f32 v[242:243], v[242:243], 1.0 op_sel_hi:[1,0]
	v_pk_add_f32 v[244:245], v[244:245], 1.0 op_sel_hi:[1,0]
	v_pk_add_f32 v[246:247], v[246:247], 1.0 op_sel_hi:[1,0]
	v_pk_add_f32 v[248:249], v[248:249], 1.0 op_sel_hi:[1,0]
	v_pk_mul_f32 v[216:217], v[216:217], v[242:243]
	v_pk_mul_f32 v[218:219], v[218:219], v[244:245]
	v_pk_mul_f32 v[220:221], v[220:221], v[246:247]
	v_pk_mul_f32 v[222:223], v[222:223], v[248:249]
	v_pk_mul_f32 v[6:7], v[6:7], v[216:217]
	v_pk_mul_f32 v[8:9], v[8:9], v[218:219]
	v_pk_mul_f32 v[2:3], v[2:3], v[220:221]
	v_pk_mul_f32 v[4:5], v[4:5], v[222:223]
	s_branch .Lem_done

.LBB0_504:
	v_add_u32_e32 v253, 0x10000, v163
	ds_read_b128 v[130:133], v253
	ds_read_b128 v[134:137], v253 offset:1024
	ds_read_b128 v[150:153], v253 offset:2048
	ds_read_b128 v[154:157], v253 offset:3072
	s_add_u32 s10, s52, 0xfff80080
	s_addc_u32 s11, s53, -1
	s_cmp_eq_u32 s29, 28
	s_cselect_b32 s11, s9, s11
	s_cselect_b32 s10, s8, s10
	s_cselect_b32 s55, s35, s7
	s_cselect_b32 s54, s34, s5
	s_add_i32 m0, s42, 0xc000
	ds_read_b128 v[158:161], v162
	ds_read_b128 v[166:169], v162 offset:1024
	ds_read_b128 v[170:173], v162 offset:2048
	ds_read_b128 v[174:177], v162 offset:3072
	ds_read_b128 v[178:181], v162 offset:4096
	ds_read_b128 v[182:185], v162 offset:5120
	ds_read_b128 v[186:189], v162 offset:6144
	ds_read_b128 v[190:193], v162 offset:7168
	global_load_lds_dwordx4 v146, s[52:53]
	s_add_i32 m0, s42, 0xe000
	s_nop 0
	global_load_lds_dwordx4 v148, s[52:53]
	s_waitcnt lgkmcnt(8)
	s_barrier
	s_waitcnt lgkmcnt(0)
	v_mfma_f32_16x16x32_bf16 v[126:129], v[130:133], v[158:161], v[126:129]
	v_mfma_f32_16x16x32_bf16 v[122:125], v[150:153], v[158:161], v[122:125]
	v_mfma_f32_16x16x32_bf16 v[118:121], v[130:133], v[170:173], v[118:121]
	v_mfma_f32_16x16x32_bf16 v[114:117], v[150:153], v[170:173], v[114:117]
	v_mfma_f32_16x16x32_bf16 v[110:113], v[130:133], v[178:181], v[110:113]
	v_mfma_f32_16x16x32_bf16 v[106:109], v[150:153], v[178:181], v[106:109]
	v_mfma_f32_16x16x32_bf16 v[102:105], v[130:133], v[186:189], v[102:105]
	v_mfma_f32_16x16x32_bf16 v[98:101], v[150:153], v[186:189], v[98:101]
	v_mfma_f32_16x16x32_bf16 v[126:129], v[134:137], v[166:169], v[126:129]
	v_mfma_f32_16x16x32_bf16 v[122:125], v[154:157], v[166:169], v[122:125]
	v_mfma_f32_16x16x32_bf16 v[118:121], v[134:137], v[174:177], v[118:121]
	v_mfma_f32_16x16x32_bf16 v[114:117], v[154:157], v[174:177], v[114:117]
	v_mfma_f32_16x16x32_bf16 v[110:113], v[134:137], v[182:185], v[110:113]
	v_mfma_f32_16x16x32_bf16 v[106:109], v[154:157], v[182:185], v[106:109]
	v_mfma_f32_16x16x32_bf16 v[102:105], v[134:137], v[190:193], v[102:105]
	v_mfma_f32_16x16x32_bf16 v[98:101], v[154:157], v[190:193], v[98:101]
	s_barrier
	s_mov_b32 m0, s41
	ds_read_b128 v[206:209], v253 offset:16384
	ds_read_b128 v[210:213], v253 offset:17408
	ds_read_b128 v[214:217], v253 offset:18432
	ds_read_b128 v[218:221], v253 offset:19456
	global_load_lds_dwordx4 v194, s[54:55]
	s_mov_b32 m0, s57
	s_nop 0
	global_load_lds_dwordx4 v138, s[54:55]
	s_barrier
	s_waitcnt lgkmcnt(0)
	v_mfma_f32_16x16x32_bf16 v[62:65], v[206:209], v[158:161], v[62:65]
	v_mfma_f32_16x16x32_bf16 v[58:61], v[214:217], v[158:161], v[58:61]
	v_mfma_f32_16x16x32_bf16 v[54:57], v[206:209], v[170:173], v[54:57]
	v_mfma_f32_16x16x32_bf16 v[46:49], v[214:217], v[170:173], v[46:49]
	v_mfma_f32_16x16x32_bf16 v[50:53], v[206:209], v[178:181], v[50:53]
	v_mfma_f32_16x16x32_bf16 v[42:45], v[214:217], v[178:181], v[42:45]
	v_mfma_f32_16x16x32_bf16 v[38:41], v[206:209], v[186:189], v[38:41]
	v_mfma_f32_16x16x32_bf16 v[34:37], v[214:217], v[186:189], v[34:37]
	v_mfma_f32_16x16x32_bf16 v[62:65], v[210:213], v[166:169], v[62:65]
	v_mfma_f32_16x16x32_bf16 v[58:61], v[218:221], v[166:169], v[58:61]
	v_mfma_f32_16x16x32_bf16 v[54:57], v[210:213], v[174:177], v[54:57]
	v_mfma_f32_16x16x32_bf16 v[46:49], v[218:221], v[174:177], v[46:49]
	v_mfma_f32_16x16x32_bf16 v[50:53], v[210:213], v[182:185], v[50:53]
	v_mfma_f32_16x16x32_bf16 v[42:45], v[218:221], v[182:185], v[42:45]
	v_mfma_f32_16x16x32_bf16 v[38:41], v[210:213], v[190:193], v[38:41]
	s_mov_b32 m0, s42
	v_mfma_f32_16x16x32_bf16 v[34:37], v[218:221], v[190:193], v[34:37]
	s_barrier
	ds_read_b128 v[158:161], v162 offset:16384
	ds_read_b128 v[166:169], v162 offset:17408
	ds_read_b128 v[170:173], v162 offset:18432
	ds_read_b128 v[174:177], v162 offset:19456
	ds_read_b128 v[178:181], v162 offset:20480
	ds_read_b128 v[182:185], v162 offset:21504
	ds_read_b128 v[186:189], v162 offset:22528
	ds_read_b128 v[190:193], v162 offset:23552
	global_load_lds_dwordx4 v142, s[10:11]
	s_mov_b32 m0, s58
	s_nop 0
	global_load_lds_dwordx4 v140, s[10:11]
	s_barrier
	s_waitcnt lgkmcnt(0)
	v_mfma_f32_16x16x32_bf16 v[94:97], v[130:133], v[158:161], v[94:97]
	v_mfma_f32_16x16x32_bf16 v[90:93], v[150:153], v[158:161], v[90:93]
	v_mfma_f32_16x16x32_bf16 v[86:89], v[130:133], v[170:173], v[86:89]
	v_mfma_f32_16x16x32_bf16 v[82:85], v[150:153], v[170:173], v[82:85]
	v_mfma_f32_16x16x32_bf16 v[78:81], v[130:133], v[178:181], v[78:81]
	v_mfma_f32_16x16x32_bf16 v[74:77], v[150:153], v[178:181], v[74:77]
	v_mfma_f32_16x16x32_bf16 v[70:73], v[130:133], v[186:189], v[70:73]
	v_mfma_f32_16x16x32_bf16 v[66:69], v[150:153], v[186:189], v[66:69]
	v_mfma_f32_16x16x32_bf16 v[94:97], v[134:137], v[166:169], v[94:97]
	v_mfma_f32_16x16x32_bf16 v[90:93], v[154:157], v[166:169], v[90:93]
	v_mfma_f32_16x16x32_bf16 v[86:89], v[134:137], v[174:177], v[86:89]
	v_mfma_f32_16x16x32_bf16 v[82:85], v[154:157], v[174:177], v[82:85]
	v_mfma_f32_16x16x32_bf16 v[78:81], v[134:137], v[182:185], v[78:81]
	v_mfma_f32_16x16x32_bf16 v[74:77], v[154:157], v[182:185], v[74:77]
	v_mfma_f32_16x16x32_bf16 v[70:73], v[134:137], v[190:193], v[70:73]
	v_mfma_f32_16x16x32_bf16 v[66:69], v[154:157], v[190:193], v[66:69]
	s_barrier
	s_add_u32 s86, s54, 0x80000
	s_addc_u32 s87, s55, 0
	s_mov_b32 m0, s59
	s_nop 0
	global_load_lds_dwordx4 v194, s[86:87]
	s_mov_b32 m0, s60
	s_nop 0
	global_load_lds_dwordx4 v138, s[86:87]
	s_waitcnt vmcnt(6)
	s_barrier
	v_mfma_f32_16x16x32_bf16 v[30:33], v[206:209], v[158:161], v[30:33]
	v_mfma_f32_16x16x32_bf16 v[18:21], v[214:217], v[158:161], v[18:21]
	v_mfma_f32_16x16x32_bf16 v[26:29], v[206:209], v[170:173], v[26:29]
	v_mfma_f32_16x16x32_bf16 v[14:17], v[214:217], v[170:173], v[14:17]
	v_mfma_f32_16x16x32_bf16 v[22:25], v[206:209], v[178:181], v[22:25]
	v_mfma_f32_16x16x32_bf16 v[6:9], v[214:217], v[178:181], v[6:9]
	v_mfma_f32_16x16x32_bf16 v[10:13], v[206:209], v[186:189], v[10:13]
	v_mfma_f32_16x16x32_bf16 v[2:5], v[214:217], v[186:189], v[2:5]
	v_mfma_f32_16x16x32_bf16 v[30:33], v[210:213], v[166:169], v[30:33]
	v_mfma_f32_16x16x32_bf16 v[18:21], v[218:221], v[166:169], v[18:21]
	v_mfma_f32_16x16x32_bf16 v[26:29], v[210:213], v[174:177], v[26:29]
	v_mfma_f32_16x16x32_bf16 v[14:17], v[218:221], v[174:177], v[14:17]
	v_mfma_f32_16x16x32_bf16 v[22:25], v[210:213], v[182:185], v[22:25]
	v_mfma_f32_16x16x32_bf16 v[6:9], v[218:221], v[182:185], v[6:9]
	v_mfma_f32_16x16x32_bf16 v[10:13], v[210:213], v[190:193], v[10:13]
	v_mfma_f32_16x16x32_bf16 v[2:5], v[218:221], v[190:193], v[2:5]
	s_barrier
	ds_read_b128 v[130:133], v253 offset:32768
	ds_read_b128 v[134:137], v253 offset:33792
	ds_read_b128 v[150:153], v253 offset:34816
	ds_read_b128 v[154:157], v253 offset:35840
	s_add_u32 s10, s10, 0x80000
	s_addc_u32 s11, s11, 0
	s_mov_b32 m0, s61
	ds_read_b128 v[158:161], v162 offset:32768
	ds_read_b128 v[166:169], v162 offset:33792
	ds_read_b128 v[170:173], v162 offset:34816
	ds_read_b128 v[174:177], v162 offset:35840
	ds_read_b128 v[178:181], v162 offset:36864
	ds_read_b128 v[182:185], v162 offset:37888
	ds_read_b128 v[186:189], v162 offset:38912
	ds_read_b128 v[190:193], v162 offset:39936
	global_load_lds_dwordx4 v142, s[10:11]
	s_mov_b32 m0, s62
	s_nop 0
	global_load_lds_dwordx4 v140, s[10:11]
	s_waitcnt lgkmcnt(8)
	s_barrier
	s_waitcnt lgkmcnt(0)
	v_mfma_f32_16x16x32_bf16 v[126:129], v[130:133], v[158:161], v[126:129]
	v_mfma_f32_16x16x32_bf16 v[122:125], v[150:153], v[158:161], v[122:125]
	v_mfma_f32_16x16x32_bf16 v[118:121], v[130:133], v[170:173], v[118:121]
	v_mfma_f32_16x16x32_bf16 v[114:117], v[150:153], v[170:173], v[114:117]
	v_mfma_f32_16x16x32_bf16 v[110:113], v[130:133], v[178:181], v[110:113]
	v_mfma_f32_16x16x32_bf16 v[106:109], v[150:153], v[178:181], v[106:109]
	v_mfma_f32_16x16x32_bf16 v[102:105], v[130:133], v[186:189], v[102:105]
	v_mfma_f32_16x16x32_bf16 v[98:101], v[150:153], v[186:189], v[98:101]
	v_mfma_f32_16x16x32_bf16 v[126:129], v[134:137], v[166:169], v[126:129]
	v_mfma_f32_16x16x32_bf16 v[122:125], v[154:157], v[166:169], v[122:125]
	v_mfma_f32_16x16x32_bf16 v[118:121], v[134:137], v[174:177], v[118:121]
	v_mfma_f32_16x16x32_bf16 v[114:117], v[154:157], v[174:177], v[114:117]
	v_mfma_f32_16x16x32_bf16 v[110:113], v[134:137], v[182:185], v[110:113]
	v_mfma_f32_16x16x32_bf16 v[106:109], v[154:157], v[182:185], v[106:109]
	v_mfma_f32_16x16x32_bf16 v[102:105], v[134:137], v[190:193], v[102:105]
	v_mfma_f32_16x16x32_bf16 v[98:101], v[154:157], v[190:193], v[98:101]
	s_barrier
	s_mov_b32 m0, s70
	ds_read_b128 v[206:209], v253 offset:49152
	ds_read_b128 v[210:213], v253 offset:50176
	ds_read_b128 v[214:217], v253 offset:51200
	ds_read_b128 v[218:221], v253 offset:52224
	s_add_u32 s98, s54, 0x80
	s_addc_u32 s99, s55, 0
	global_load_lds_dwordx4 v194, s[98:99]
	s_mov_b32 m0, s71
	s_nop 0
	global_load_lds_dwordx4 v138, s[98:99]
	s_barrier
	s_waitcnt lgkmcnt(0)
	v_mfma_f32_16x16x32_bf16 v[62:65], v[206:209], v[158:161], v[62:65]
	v_mfma_f32_16x16x32_bf16 v[58:61], v[214:217], v[158:161], v[58:61]
	v_mfma_f32_16x16x32_bf16 v[54:57], v[206:209], v[170:173], v[54:57]
	v_mfma_f32_16x16x32_bf16 v[46:49], v[214:217], v[170:173], v[46:49]
	v_mfma_f32_16x16x32_bf16 v[50:53], v[206:209], v[178:181], v[50:53]
	v_mfma_f32_16x16x32_bf16 v[42:45], v[214:217], v[178:181], v[42:45]
	v_mfma_f32_16x16x32_bf16 v[38:41], v[206:209], v[186:189], v[38:41]
	v_mfma_f32_16x16x32_bf16 v[34:37], v[214:217], v[186:189], v[34:37]
	v_mfma_f32_16x16x32_bf16 v[62:65], v[210:213], v[166:169], v[62:65]
	v_mfma_f32_16x16x32_bf16 v[58:61], v[218:221], v[166:169], v[58:61]
	v_mfma_f32_16x16x32_bf16 v[54:57], v[210:213], v[174:177], v[54:57]
	v_mfma_f32_16x16x32_bf16 v[46:49], v[218:221], v[174:177], v[46:49]
	v_mfma_f32_16x16x32_bf16 v[50:53], v[210:213], v[182:185], v[50:53]
	v_mfma_f32_16x16x32_bf16 v[42:45], v[218:221], v[182:185], v[42:45]
	v_mfma_f32_16x16x32_bf16 v[38:41], v[210:213], v[190:193], v[38:41]
	s_mov_b32 m0, s78
	v_mfma_f32_16x16x32_bf16 v[34:37], v[218:221], v[190:193], v[34:37]
	s_barrier
	ds_read_b128 v[158:161], v162 offset:49152
	ds_read_b128 v[166:169], v162 offset:50176
	ds_read_b128 v[170:173], v162 offset:51200
	ds_read_b128 v[174:177], v162 offset:52224
	ds_read_b128 v[178:181], v162 offset:53248
	ds_read_b128 v[182:185], v162 offset:54272
	ds_read_b128 v[186:189], v162 offset:55296
	ds_read_b128 v[190:193], v162 offset:56320
	s_add_u32 s100, s10, 0xfff80080
	s_addc_u32 s101, s11, -1
	global_load_lds_dwordx4 v142, s[100:101]
	s_mov_b32 m0, s79
	s_nop 0
	global_load_lds_dwordx4 v140, s[100:101]
	s_barrier
	s_waitcnt lgkmcnt(0)
	v_mfma_f32_16x16x32_bf16 v[94:97], v[130:133], v[158:161], v[94:97]
	v_mfma_f32_16x16x32_bf16 v[90:93], v[150:153], v[158:161], v[90:93]
	v_mfma_f32_16x16x32_bf16 v[86:89], v[130:133], v[170:173], v[86:89]
	v_mfma_f32_16x16x32_bf16 v[82:85], v[150:153], v[170:173], v[82:85]
	v_mfma_f32_16x16x32_bf16 v[78:81], v[130:133], v[178:181], v[78:81]
	v_mfma_f32_16x16x32_bf16 v[74:77], v[150:153], v[178:181], v[74:77]
	v_mfma_f32_16x16x32_bf16 v[70:73], v[130:133], v[186:189], v[70:73]
	v_mfma_f32_16x16x32_bf16 v[66:69], v[150:153], v[186:189], v[66:69]
	v_mfma_f32_16x16x32_bf16 v[94:97], v[134:137], v[166:169], v[94:97]
	v_mfma_f32_16x16x32_bf16 v[90:93], v[154:157], v[166:169], v[90:93]
	v_mfma_f32_16x16x32_bf16 v[86:89], v[134:137], v[174:177], v[86:89]
	v_mfma_f32_16x16x32_bf16 v[82:85], v[154:157], v[174:177], v[82:85]
	v_mfma_f32_16x16x32_bf16 v[78:81], v[134:137], v[182:185], v[78:81]
	v_mfma_f32_16x16x32_bf16 v[74:77], v[154:157], v[182:185], v[74:77]
	v_mfma_f32_16x16x32_bf16 v[70:73], v[134:137], v[190:193], v[70:73]
	v_mfma_f32_16x16x32_bf16 v[66:69], v[154:157], v[190:193], v[66:69]
	s_barrier
	s_add_u32 s10, s54, 0x80080
	s_addc_u32 s11, s55, 0
	s_mov_b32 m0, s80
	s_nop 0
	global_load_lds_dwordx4 v194, s[10:11]
	s_mov_b32 m0, s81
	s_nop 0
	global_load_lds_dwordx4 v138, s[10:11]
	s_waitcnt vmcnt(6)
	s_barrier
	v_mfma_f32_16x16x32_bf16 v[30:33], v[206:209], v[158:161], v[30:33]
	v_mfma_f32_16x16x32_bf16 v[18:21], v[214:217], v[158:161], v[18:21]
	v_mfma_f32_16x16x32_bf16 v[26:29], v[206:209], v[170:173], v[26:29]
	v_mfma_f32_16x16x32_bf16 v[14:17], v[214:217], v[170:173], v[14:17]
	v_mfma_f32_16x16x32_bf16 v[22:25], v[206:209], v[178:181], v[22:25]
	v_mfma_f32_16x16x32_bf16 v[6:9], v[214:217], v[178:181], v[6:9]
	v_mfma_f32_16x16x32_bf16 v[10:13], v[206:209], v[186:189], v[10:13]
	v_mfma_f32_16x16x32_bf16 v[2:5], v[214:217], v[186:189], v[2:5]
	v_mfma_f32_16x16x32_bf16 v[30:33], v[210:213], v[166:169], v[30:33]
	v_mfma_f32_16x16x32_bf16 v[18:21], v[218:221], v[166:169], v[18:21]
	v_mfma_f32_16x16x32_bf16 v[26:29], v[210:213], v[174:177], v[26:29]
	v_mfma_f32_16x16x32_bf16 v[14:17], v[218:221], v[174:177], v[14:17]
	v_mfma_f32_16x16x32_bf16 v[22:25], v[210:213], v[182:185], v[22:25]
	v_mfma_f32_16x16x32_bf16 v[6:9], v[218:221], v[182:185], v[6:9]
	v_mfma_f32_16x16x32_bf16 v[10:13], v[210:213], v[190:193], v[10:13]
	v_mfma_f32_16x16x32_bf16 v[2:5], v[218:221], v[190:193], v[2:5]
	s_add_i32 s29, s29, 2
	s_add_u32 s52, s52, 0x100
	s_addc_u32 s53, s53, 0
	s_add_u32 s5, s5, 0x100
	s_addc_u32 s7, s7, 0
	s_cmp_gt_u32 s29, 29
	s_barrier
	s_cbranch_scc0 .LBB0_504
	v_readlane_b32 s10, v250, 21
	s_cmp_gt_i32 s40, 63
	v_readlane_b32 s11, v250, 22
	s_mov_b64 s[20:21], s[48:49]
	s_cselect_b32 s11, s21, s11
	s_cselect_b32 s10, s20, s10
	v_readlane_b32 s20, v252, 0
	v_readlane_b32 s26, v252, 6
	v_readlane_b32 s27, v252, 7
	s_cselect_b32 s53, s3, s27
	s_cselect_b32 s52, s2, s26
	s_sub_i32 s5, s40, 64
	s_cmp_gt_i32 s40, 63
	s_cselect_b32 s54, s5, s40
	s_lshr_b32 s5, s40, 3
	s_cmp_gt_i32 s40, 63
	s_mulk_i32 s5, 0x1800
	v_lshl_or_b32 v130, s28, 8, v164
	s_cselect_b32 s28, 0xc000, s5
	s_ashr_i32 s29, s28, 31
	s_lshl_b64 s[28:29], s[28:29], 2
	s_add_u32 s28, s63, s28
	v_ashrrev_i32_e32 v131, 31, v130
	s_addc_u32 s29, s67, s29
	v_lshlrev_b64 v[130:131], 2, v[130:131]
	v_lshl_add_u64 v[132:133], s[28:29], 0, v[130:131]
	s_mov_b64 s[28:29], 0x6484000
	s_ashr_i32 s55, s54, 31
	v_lshl_add_u64 v[154:155], v[132:133], 0, s[28:29]
	s_lshl_b64 s[28:29], s[54:55], 19
	v_lshl_add_u64 v[134:135], s[28:29], 0, v[144:145]
	v_lshlrev_b64 v[134:135], 2, v[134:135]
	v_lshl_add_u64 v[136:137], s[10:11], 0, v[134:135]
	v_lshl_add_u64 v[134:135], s[52:53], 0, v[134:135]
	s_mov_b32 s5, 0x6484000
	v_lshl_add_u64 v[150:151], v[136:137], 0, v[130:131]
	v_lshl_add_u64 v[152:153], v[134:135], 0, v[130:131]
	v_add_co_u32_e32 v130, vcc, s5, v132
	s_mov_b64 s[10:11], 0x20000
	s_nop 0
	v_addc_co_u32_e32 v131, vcc, 0, v133, vcc
	v_add_co_u32_e32 v156, vcc, s13, v150
	global_load_dwordx4 v[134:137], v[130:131], off
	s_nop 0
	global_load_dwordx4 v[130:133], v[154:155], off offset:16
	global_load_dwordx4 v[166:169], v[150:151], off offset:16
	global_load_dwordx4 v[170:173], v[150:151], off
	v_lshl_add_u64 v[158:159], v[150:151], 0, s[10:11]
	v_addc_co_u32_e32 v157, vcc, 0, v151, vcc
	s_mov_b32 s5, 0x40000
	global_load_dwordx4 v[174:177], v[156:157], off
	global_load_dwordx4 v[178:181], v[158:159], off offset:16
	s_mov_b64 s[10:11], 0x40000
	v_add_co_u32_e32 v158, vcc, s5, v150
	v_lshl_add_u64 v[160:161], v[150:151], 0, s[10:11]
	s_nop 0
	v_addc_co_u32_e32 v159, vcc, 0, v151, vcc
	s_mov_b32 s7, 0x60000
	global_load_dwordx4 v[182:185], v[158:159], off
	global_load_dwordx4 v[186:189], v[160:161], off offset:16
	s_mov_b64 s[10:11], 0x60000
	v_add_co_u32_e32 v160, vcc, s7, v150
	v_lshl_add_u64 v[206:207], v[150:151], 0, s[10:11]
	s_nop 0
	v_addc_co_u32_e32 v161, vcc, 0, v151, vcc
	global_load_dwordx4 v[190:193], v[160:161], off
	s_nop 0
	global_load_dwordx4 v[206:209], v[206:207], off offset:16
	v_readlane_b32 s21, v252, 1
	v_readlane_b32 s22, v252, 2
	v_readlane_b32 s23, v252, 3
	v_readlane_b32 s24, v252, 4
	v_readlane_b32 s25, v252, 5
	s_waitcnt vmcnt(0)
	v_pk_fma_f32 v[124:125], v[124:125], v[132:133], v[168:169]
	v_pk_fma_f32 v[122:123], v[122:123], v[130:131], v[166:167]
	global_store_dwordx4 v[152:153], v[122:125], off offset:16
	v_pk_fma_f32 v[128:129], v[128:129], v[136:137], v[172:173]
	v_pk_fma_f32 v[126:127], v[126:127], v[134:135], v[170:171]
	v_pk_fma_f32 v[122:123], v[120:121], v[136:137], v[176:177]
	v_pk_fma_f32 v[120:121], v[118:119], v[134:135], v[174:175]
	v_add_co_u32_e32 v118, vcc, s13, v152
	v_pk_fma_f32 v[116:117], v[116:117], v[132:133], v[180:181]
	s_nop 0
	v_addc_co_u32_e32 v119, vcc, 0, v153, vcc
	v_pk_fma_f32 v[114:115], v[114:115], v[130:131], v[178:179]
	global_store_dwordx4 v[118:119], v[114:117], off offset:16
	v_pk_fma_f32 v[108:109], v[108:109], v[132:133], v[188:189]
	v_pk_fma_f32 v[106:107], v[106:107], v[130:131], v[186:187]
	v_pk_fma_f32 v[114:115], v[112:113], v[136:137], v[184:185]
	v_pk_fma_f32 v[112:113], v[110:111], v[134:135], v[182:183]
	v_add_co_u32_e32 v110, vcc, s5, v152
	global_store_dwordx4 v[152:153], v[126:129], off
	s_nop 0
	v_addc_co_u32_e32 v111, vcc, 0, v153, vcc
	global_store_dwordx4 v[110:111], v[106:109], off offset:16
	v_pk_fma_f32 v[100:101], v[100:101], v[132:133], v[208:209]
	v_pk_fma_f32 v[98:99], v[98:99], v[130:131], v[206:207]
	v_pk_fma_f32 v[106:107], v[104:105], v[136:137], v[192:193]
	v_pk_fma_f32 v[104:105], v[102:103], v[134:135], v[190:191]
	v_add_co_u32_e32 v102, vcc, s7, v152
	global_store_dwordx4 v[118:119], v[120:123], off
	s_nop 0
	v_addc_co_u32_e32 v103, vcc, 0, v153, vcc
	global_store_dwordx4 v[110:111], v[112:115], off
	global_store_dwordx4 v[102:103], v[104:107], off
	global_store_dwordx4 v[102:103], v[98:101], off offset:16
	s_mov_b32 s5, 0x100000
	s_mov_b64 s[10:11], 0x100000
	v_add_co_u32_e32 v98, vcc, s5, v150
	v_lshl_add_u64 v[100:101], v[150:151], 0, s[10:11]
	s_nop 0
	v_addc_co_u32_e32 v99, vcc, 0, v151, vcc
	global_load_dwordx4 v[112:115], v[98:99], off
	global_load_dwordx4 v[120:123], v[100:101], off offset:16
	s_mov_b64 s[10:11], 0x120000
	v_add_co_u32_e32 v100, vcc, s45, v150
	v_lshl_add_u64 v[104:105], v[150:151], 0, s[10:11]
	s_nop 0
	v_addc_co_u32_e32 v101, vcc, 0, v151, vcc
	s_mov_b64 s[10:11], 0x140000
	s_mov_b32 s7, 0x140000
	global_load_dwordx4 v[124:127], v[100:101], off
	global_load_dwordx4 v[166:169], v[104:105], off offset:16
	v_lshl_add_u64 v[106:107], v[150:151], 0, s[10:11]
	v_add_co_u32_e32 v104, vcc, s7, v150
	s_mov_b64 s[10:11], 0x160000
	s_nop 0
	v_addc_co_u32_e32 v105, vcc, 0, v151, vcc
	v_lshl_add_u64 v[108:109], v[150:151], 0, s[10:11]
	s_mov_b32 s10, 0x160000
	global_load_dwordx4 v[170:173], v[104:105], off
	global_load_dwordx4 v[174:177], v[106:107], off offset:16
	v_add_co_u32_e32 v106, vcc, s10, v150
	s_waitcnt vmcnt(0)
	v_pk_fma_f32 v[112:113], v[94:95], v[134:135], v[112:113]
	v_addc_co_u32_e32 v107, vcc, 0, v151, vcc
	global_load_dwordx4 v[178:181], v[106:107], off
	global_load_dwordx4 v[182:185], v[108:109], off offset:16
	v_add_co_u32_e32 v94, vcc, s5, v152
	v_pk_fma_f32 v[92:93], v[92:93], v[132:133], v[122:123]
	s_nop 0
	v_addc_co_u32_e32 v95, vcc, 0, v153, vcc
	v_pk_fma_f32 v[90:91], v[90:91], v[130:131], v[120:121]
	global_store_dwordx4 v[94:95], v[90:93], off offset:16
	v_pk_fma_f32 v[84:85], v[84:85], v[132:133], v[168:169]
	v_pk_fma_f32 v[82:83], v[82:83], v[130:131], v[166:167]
	v_pk_fma_f32 v[90:91], v[88:89], v[136:137], v[126:127]
	v_pk_fma_f32 v[88:89], v[86:87], v[134:135], v[124:125]
	v_add_co_u32_e32 v86, vcc, s45, v152
	v_pk_fma_f32 v[114:115], v[96:97], v[136:137], v[114:115]
	s_nop 0
	v_addc_co_u32_e32 v87, vcc, 0, v153, vcc
	global_store_dwordx4 v[86:87], v[82:85], off offset:16
	v_pk_fma_f32 v[76:77], v[76:77], v[132:133], v[176:177]
	v_pk_fma_f32 v[74:75], v[74:75], v[130:131], v[174:175]
	v_pk_fma_f32 v[82:83], v[80:81], v[136:137], v[172:173]
	v_pk_fma_f32 v[80:81], v[78:79], v[134:135], v[170:171]
	v_add_co_u32_e32 v78, vcc, s7, v152
	global_store_dwordx4 v[94:95], v[112:115], off
	s_nop 0
	v_addc_co_u32_e32 v79, vcc, 0, v153, vcc
	global_store_dwordx4 v[78:79], v[74:77], off offset:16
	global_store_dwordx4 v[86:87], v[88:91], off
	global_store_dwordx4 v[78:79], v[80:83], off
	v_add_co_u32_e32 v74, vcc, s10, v152
	s_waitcnt vmcnt(0)
	v_pk_fma_f32 v[72:73], v[72:73], v[136:137], v[180:181]
	v_pk_fma_f32 v[70:71], v[70:71], v[134:135], v[178:179]
	v_addc_co_u32_e32 v75, vcc, 0, v153, vcc
	v_pk_fma_f32 v[68:69], v[68:69], v[132:133], v[184:185]
	v_pk_fma_f32 v[66:67], v[66:67], v[130:131], v[182:183]
	global_store_dwordx4 v[74:75], v[70:73], off
	global_store_dwordx4 v[74:75], v[66:69], off offset:16
	s_mov_b64 s[10:11], 0x20200
	v_lshl_add_u64 v[76:77], v[150:151], 0, s[10:11]
	s_mov_b64 s[10:11], 0x40200
	global_load_dwordx4 v[80:83], v[150:151], off offset:512
	global_load_dwordx4 v[70:73], v[154:155], off offset:512
	global_load_dwordx4 v[66:69], v[154:155], off offset:528
	global_load_dwordx4 v[88:91], v[150:151], off offset:528
	global_load_dwordx4 v[112:115], v[156:157], off offset:512
	global_load_dwordx4 v[120:123], v[158:159], off offset:512
	global_load_dwordx4 v[124:127], v[76:77], off offset:16
	v_lshl_add_u64 v[76:77], v[150:151], 0, s[10:11]
	s_mov_b64 s[10:11], 0x60200
	global_load_dwordx4 v[128:131], v[76:77], off offset:16
	global_load_dwordx4 v[132:135], v[160:161], off offset:512
	v_lshl_add_u64 v[76:77], v[150:151], 0, s[10:11]
	global_load_dwordx4 v[154:157], v[76:77], off offset:16
	s_waitcnt vmcnt(0)
	v_pk_fma_f32 v[64:65], v[64:65], v[72:73], v[82:83]
	v_pk_fma_f32 v[62:63], v[62:63], v[70:71], v[80:81]
	v_pk_fma_f32 v[60:61], v[60:61], v[68:69], v[90:91]
	v_pk_fma_f32 v[58:59], v[58:59], v[66:67], v[88:89]
	v_pk_fma_f32 v[52:53], v[52:53], v[72:73], v[122:123]
	v_pk_fma_f32 v[50:51], v[50:51], v[70:71], v[120:121]
	v_pk_fma_f32 v[48:49], v[48:49], v[68:69], v[126:127]
	v_pk_fma_f32 v[46:47], v[46:47], v[66:67], v[124:125]
	v_pk_fma_f32 v[56:57], v[56:57], v[72:73], v[114:115]
	v_pk_fma_f32 v[54:55], v[54:55], v[70:71], v[112:113]
	global_store_dwordx4 v[152:153], v[62:65], off offset:512
	global_store_dwordx4 v[152:153], v[58:61], off offset:528
	global_store_dwordx4 v[118:119], v[54:57], off offset:512
	global_store_dwordx4 v[110:111], v[50:53], off offset:512
	v_pk_fma_f32 v[44:45], v[44:45], v[68:69], v[130:131]
	v_pk_fma_f32 v[42:43], v[42:43], v[66:67], v[128:129]
	v_pk_fma_f32 v[40:41], v[40:41], v[72:73], v[134:135]
	v_pk_fma_f32 v[38:39], v[38:39], v[70:71], v[132:133]
	v_pk_fma_f32 v[36:37], v[36:37], v[68:69], v[156:157]
	v_pk_fma_f32 v[34:35], v[34:35], v[66:67], v[154:155]
	global_store_dwordx4 v[118:119], v[46:49], off offset:528
	global_store_dwordx4 v[110:111], v[42:45], off offset:528
	global_store_dwordx4 v[102:103], v[38:41], off offset:512
	global_store_dwordx4 v[102:103], v[34:37], off offset:528
	s_mov_b64 s[10:11], 0x100200
	v_lshl_add_u64 v[50:51], v[150:151], 0, s[10:11]
	s_mov_b64 s[10:11], 0x120200
	v_lshl_add_u64 v[54:55], v[150:151], 0, s[10:11]
	s_mov_b64 s[10:11], 0x140200
	v_lshl_add_u64 v[58:59], v[150:151], 0, s[10:11]
	s_mov_b64 s[10:11], 0x160200
	global_load_dwordx4 v[34:37], v[98:99], off offset:512
	global_load_dwordx4 v[38:41], v[100:101], off offset:512
	global_load_dwordx4 v[42:45], v[104:105], off offset:512
	global_load_dwordx4 v[46:49], v[106:107], off offset:512
	v_lshl_add_u64 v[62:63], v[150:151], 0, s[10:11]
	global_load_dwordx4 v[50:53], v[50:51], off offset:16
	s_waitcnt vmcnt(0)
	v_pk_fma_f32 v[32:33], v[32:33], v[72:73], v[36:37]
	global_load_dwordx4 v[54:57], v[54:55], off offset:16
	v_pk_fma_f32 v[30:31], v[30:31], v[70:71], v[34:35]
	global_load_dwordx4 v[58:61], v[58:59], off offset:16
	v_pk_fma_f32 v[28:29], v[28:29], v[72:73], v[40:41]
	global_load_dwordx4 v[62:65], v[62:63], off offset:16
	v_pk_fma_f32 v[26:27], v[26:27], v[70:71], v[38:39]
	v_pk_fma_f32 v[24:25], v[24:25], v[72:73], v[44:45]
	v_pk_fma_f32 v[22:23], v[22:23], v[70:71], v[42:43]
	v_pk_fma_f32 v[12:13], v[12:13], v[72:73], v[48:49]
	v_pk_fma_f32 v[10:11], v[10:11], v[70:71], v[46:47]
	v_pk_fma_f32 v[20:21], v[20:21], v[68:69], v[52:53]
	v_pk_fma_f32 v[18:19], v[18:19], v[66:67], v[50:51]
	global_store_dwordx4 v[94:95], v[30:33], off offset:512
	global_store_dwordx4 v[86:87], v[26:29], off offset:512
	global_store_dwordx4 v[78:79], v[22:25], off offset:512
	global_store_dwordx4 v[74:75], v[10:13], off offset:512
	s_waitcnt vmcnt(0)
	v_pk_fma_f32 v[16:17], v[16:17], v[68:69], v[56:57]
	v_pk_fma_f32 v[14:15], v[14:15], v[66:67], v[54:55]
	v_pk_fma_f32 v[8:9], v[8:9], v[68:69], v[60:61]
	v_pk_fma_f32 v[6:7], v[6:7], v[66:67], v[58:59]
	v_pk_fma_f32 v[4:5], v[4:5], v[68:69], v[64:65]
	v_pk_fma_f32 v[2:3], v[2:3], v[66:67], v[62:63]
	global_store_dwordx4 v[94:95], v[18:21], off offset:528
	global_store_dwordx4 v[86:87], v[14:17], off offset:528
	global_store_dwordx4 v[78:79], v[6:9], off offset:528
	global_store_dwordx4 v[74:75], v[2:5], off offset:528
	s_and_b64 vcc, exec, s[0:1]
	s_mov_b32 s40, s6
	s_mov_b32 s28, s4
	s_mov_b64 s[54:55], s[34:35]
	s_mov_b64 s[52:53], s[8:9]
	s_cbranch_vccz .LBB0_501
	s_waitcnt vmcnt(0)
	v_readlane_b32 s28, v250, 12
	v_readlane_b32 s26, v250, 15
	s_cmpk_gt_u32 s12, 0xff
	v_readlane_b32 s29, v250, 13
	v_readlane_b32 s27, v250, 16
	s_mov_b32 s70, 0x800000
	v_readlane_b32 s79, v250, 18
	s_cbranch_scc1 .LBB0_508
	s_barrier
